# E2: GEMM-epilogue bf16 tile stores write-through (sc1) so seam wbl2 is cheap; on top of E1
# speedup vs baseline: 1.0110x; 1.0110x over previous
.LBB0_220:
	v_lshl_add_u32 v148, s4, 8, v154
	s_lshl_b32 s4, s48, 8
	s_and_b32 s4, s4, 0x100
	s_cmp_eq_u32 s5, 1
	s_cselect_b64 vcc, -1, 0
	v_ashrrev_i32_e32 v149, 31, v148
	v_or_b32_e32 v161, s4, v156
	v_cndmask_b32_e32 v146, 1.0, v160, vcc
	v_lshlrev_b64 v[150:151], 9, v[148:149]
	v_cndmask_b32_e64 v146, v146, 1.0, s[84:85]
	s_cmp_lg_u64 s[78:79], 0
	v_or_b32_e32 v150, v150, v161
	s_cselect_b64 s[48:49], -1, 0
	s_cmp_eq_u64 s[78:79], 0
	v_lshl_add_u64 v[152:153], v[150:151], 1, s[76:77]
	v_lshl_add_u64 v[150:151], v[150:151], 2, s[78:79]
	v_pk_mul_f32 v[128:129], v[146:147], v[128:129] op_sel_hi:[0,1]
	v_pk_mul_f32 v[126:127], v[146:147], v[126:127] op_sel_hi:[0,1]
	v_pk_mul_f32 v[124:125], v[146:147], v[124:125] op_sel_hi:[0,1]
	v_pk_mul_f32 v[122:123], v[146:147], v[122:123] op_sel_hi:[0,1]
	v_cvt_pk_bf16_f32 v164, v126, v127
	v_cvt_pk_bf16_f32 v165, v128, v129
	v_cvt_pk_bf16_f32 v166, v122, v123
	v_cvt_pk_bf16_f32 v167, v124, v125
	global_store_dwordx4 v[152:153], v[164:167], off sc1
	s_cbranch_scc1 .LBB0_222
	global_store_dwordx4 v[150:151], v[126:129], off nt
	global_store_dwordx4 v[150:151], v[122:125], off offset:16 nt
.LBB0_222:
	v_mov_b32_e32 v147, v146
	s_nop 0
	v_mov_b32_e32 v122, v146
	v_mov_b32_e32 v123, v146
	v_pk_mul_f32 v[118:119], v[146:147], v[118:119]
	v_pk_mul_f32 v[120:121], v[122:123], v[120:121]
	v_cvt_pk_bf16_f32 v124, v118, v119
	v_pk_mul_f32 v[116:117], v[122:123], v[116:117]
	v_pk_mul_f32 v[114:115], v[146:147], v[114:115]
	v_cvt_pk_bf16_f32 v125, v120, v121
	s_andn2_b64 vcc, exec, s[48:49]
	v_cvt_pk_bf16_f32 v126, v114, v115
	v_cvt_pk_bf16_f32 v127, v116, v117
	global_store_dwordx4 v[152:153], v[124:127], off offset:256 sc1
	s_nop 1
	v_cndmask_b32_e64 v124, 0, 1, s[48:49]
	v_cmp_ne_u32_e64 s[4:5], 1, v124
	s_cbranch_vccnz .LBB0_224
	global_store_dwordx4 v[150:151], v[118:121], off offset:512 nt
	global_store_dwordx4 v[150:151], v[114:117], off offset:528 nt
.LBB0_224:
	s_nop 1
	v_or_b32_e32 v114, 16, v148
	v_ashrrev_i32_e32 v115, 31, v114
	v_lshlrev_b64 v[114:115], 9, v[114:115]
	v_or_b32_e32 v114, v114, v161
	v_lshl_add_u64 v[116:117], v[114:115], 1, s[76:77]
	v_lshl_add_u64 v[114:115], v[114:115], 2, s[78:79]
	v_pk_mul_f32 v[112:113], v[122:123], v[112:113]
	v_pk_mul_f32 v[110:111], v[146:147], v[110:111]
	v_pk_mul_f32 v[108:109], v[122:123], v[108:109]
	v_pk_mul_f32 v[106:107], v[146:147], v[106:107]
	s_and_b64 vcc, exec, s[4:5]
	v_cvt_pk_bf16_f32 v118, v110, v111
	v_cvt_pk_bf16_f32 v119, v112, v113
	v_cvt_pk_bf16_f32 v120, v106, v107
	v_cvt_pk_bf16_f32 v121, v108, v109
	global_store_dwordx4 v[116:117], v[118:121], off sc1
	s_cbranch_vccnz .LBB0_226
	global_store_dwordx4 v[114:115], v[110:113], off nt
	global_store_dwordx4 v[114:115], v[106:109], off offset:16 nt
.LBB0_226:
	s_nop 1
	v_mov_b32_e32 v106, v146
	v_mov_b32_e32 v107, v146
	v_pk_mul_f32 v[104:105], v[106:107], v[104:105]
	v_pk_mul_f32 v[102:103], v[146:147], v[102:103]
	v_pk_mul_f32 v[100:101], v[106:107], v[100:101]
	v_pk_mul_f32 v[98:99], v[146:147], v[98:99]
	s_and_b64 vcc, exec, s[4:5]
	v_cvt_pk_bf16_f32 v108, v102, v103
	v_cvt_pk_bf16_f32 v109, v104, v105
	v_cvt_pk_bf16_f32 v110, v98, v99
	v_cvt_pk_bf16_f32 v111, v100, v101
	global_store_dwordx4 v[116:117], v[108:111], off offset:256 sc1
	s_cbranch_vccnz .LBB0_228
	global_store_dwordx4 v[114:115], v[102:105], off offset:512 nt
	global_store_dwordx4 v[114:115], v[98:101], off offset:528 nt
.LBB0_228:
	s_nop 1
	v_or_b32_e32 v98, 32, v148
	v_ashrrev_i32_e32 v99, 31, v98
	v_lshlrev_b64 v[98:99], 9, v[98:99]
	v_or_b32_e32 v98, v98, v161
	v_lshl_add_u64 v[100:101], v[98:99], 1, s[76:77]
	v_lshl_add_u64 v[98:99], v[98:99], 2, s[78:79]
	v_pk_mul_f32 v[96:97], v[106:107], v[96:97]
	v_pk_mul_f32 v[94:95], v[146:147], v[94:95]
	v_pk_mul_f32 v[92:93], v[106:107], v[92:93]
	v_pk_mul_f32 v[90:91], v[146:147], v[90:91]
	s_and_b64 vcc, exec, s[4:5]
	v_cvt_pk_bf16_f32 v102, v94, v95
	v_cvt_pk_bf16_f32 v103, v96, v97
	v_cvt_pk_bf16_f32 v104, v90, v91
	v_cvt_pk_bf16_f32 v105, v92, v93
	global_store_dwordx4 v[100:101], v[102:105], off sc1
	s_cbranch_vccnz .LBB0_230
	global_store_dwordx4 v[98:99], v[94:97], off nt
	global_store_dwordx4 v[98:99], v[90:93], off offset:16 nt
.LBB0_230:
	s_nop 1
	v_mov_b32_e32 v90, v146
	v_mov_b32_e32 v91, v146
	v_pk_mul_f32 v[88:89], v[90:91], v[88:89]
	v_pk_mul_f32 v[86:87], v[146:147], v[86:87]
	v_pk_mul_f32 v[84:85], v[90:91], v[84:85]
	v_pk_mul_f32 v[82:83], v[146:147], v[82:83]
	s_and_b64 vcc, exec, s[4:5]
	v_cvt_pk_bf16_f32 v92, v86, v87
	v_cvt_pk_bf16_f32 v93, v88, v89
	v_cvt_pk_bf16_f32 v94, v82, v83
	v_cvt_pk_bf16_f32 v95, v84, v85
	global_store_dwordx4 v[100:101], v[92:95], off offset:256 sc1
	s_cbranch_vccnz .LBB0_232
	global_store_dwordx4 v[98:99], v[86:89], off offset:512 nt
	global_store_dwordx4 v[98:99], v[82:85], off offset:528 nt
.LBB0_232:
	s_nop 1
	v_or_b32_e32 v82, 48, v148
	v_ashrrev_i32_e32 v83, 31, v82
	v_lshlrev_b64 v[82:83], 9, v[82:83]
	v_or_b32_e32 v82, v82, v161
	v_lshl_add_u64 v[84:85], v[82:83], 1, s[76:77]
	v_lshl_add_u64 v[82:83], v[82:83], 2, s[78:79]
	v_pk_mul_f32 v[80:81], v[90:91], v[80:81]
	v_pk_mul_f32 v[78:79], v[146:147], v[78:79]
	v_pk_mul_f32 v[76:77], v[90:91], v[76:77]
	v_pk_mul_f32 v[74:75], v[146:147], v[74:75]
	s_and_b64 vcc, exec, s[4:5]
	v_cvt_pk_bf16_f32 v86, v78, v79
	v_cvt_pk_bf16_f32 v87, v80, v81
	v_cvt_pk_bf16_f32 v88, v74, v75
	v_cvt_pk_bf16_f32 v89, v76, v77
	global_store_dwordx4 v[84:85], v[86:89], off sc1
	s_cbranch_vccnz .LBB0_234
	global_store_dwordx4 v[82:83], v[78:81], off nt
	global_store_dwordx4 v[82:83], v[74:77], off offset:16 nt
.LBB0_234:
	s_nop 1
	v_mov_b32_e32 v74, v146
	v_mov_b32_e32 v75, v146
	v_pk_mul_f32 v[72:73], v[74:75], v[72:73]
	v_pk_mul_f32 v[70:71], v[146:147], v[70:71]
	v_pk_mul_f32 v[68:69], v[74:75], v[68:69]
	v_pk_mul_f32 v[66:67], v[146:147], v[66:67]
	s_and_b64 vcc, exec, s[4:5]
	v_cvt_pk_bf16_f32 v76, v70, v71
	v_cvt_pk_bf16_f32 v77, v72, v73
	v_cvt_pk_bf16_f32 v78, v66, v67
	v_cvt_pk_bf16_f32 v79, v68, v69
	global_store_dwordx4 v[84:85], v[76:79], off offset:256 sc1
	s_cbranch_vccnz .LBB0_236
	global_store_dwordx4 v[82:83], v[70:73], off offset:512 nt
	global_store_dwordx4 v[82:83], v[66:69], off offset:528 nt
.LBB0_236:
	s_nop 1
	v_lshlrev_b64 v[66:67], 9, v[148:149]
	v_or_b32_e32 v66, v66, v161
	s_mov_b64 s[48:49], 0x10000
	v_lshl_add_u64 v[66:67], v[66:67], 0, s[48:49]
	v_lshl_add_u64 v[68:69], v[66:67], 1, s[76:77]
	v_lshl_add_u64 v[66:67], v[66:67], 2, s[78:79]
	v_pk_mul_f32 v[64:65], v[74:75], v[64:65]
	v_pk_mul_f32 v[62:63], v[146:147], v[62:63]
	v_pk_mul_f32 v[60:61], v[74:75], v[60:61]
	v_pk_mul_f32 v[58:59], v[146:147], v[58:59]
	s_and_b64 vcc, exec, s[4:5]
	v_cvt_pk_bf16_f32 v70, v62, v63
	v_cvt_pk_bf16_f32 v71, v64, v65
	v_cvt_pk_bf16_f32 v72, v58, v59
	v_cvt_pk_bf16_f32 v73, v60, v61
	global_store_dwordx4 v[68:69], v[70:73], off sc1
	s_cbranch_vccnz .LBB0_238
	global_store_dwordx4 v[66:67], v[62:65], off nt
	global_store_dwordx4 v[66:67], v[58:61], off offset:16 nt
.LBB0_238:
	s_nop 1
	v_mov_b32_e32 v58, v146
	v_mov_b32_e32 v59, v146
	v_pk_mul_f32 v[56:57], v[58:59], v[56:57]
	v_pk_mul_f32 v[54:55], v[146:147], v[54:55]
	v_pk_mul_f32 v[52:53], v[58:59], v[52:53]
	v_pk_mul_f32 v[50:51], v[146:147], v[50:51]
	s_and_b64 vcc, exec, s[4:5]
	v_cvt_pk_bf16_f32 v60, v54, v55
	v_cvt_pk_bf16_f32 v61, v56, v57
	v_cvt_pk_bf16_f32 v62, v50, v51
	v_cvt_pk_bf16_f32 v63, v52, v53
	global_store_dwordx4 v[68:69], v[60:63], off offset:256 sc1
	s_cbranch_vccnz .LBB0_240
	global_store_dwordx4 v[66:67], v[54:57], off offset:512 nt
	global_store_dwordx4 v[66:67], v[50:53], off offset:528 nt
.LBB0_240:
	s_nop 1
	v_lshlrev_b64 v[50:51], 9, v[148:149]
	v_or_b32_e32 v50, v50, v161
	s_mov_b64 s[48:49], 0x12000
	v_lshl_add_u64 v[50:51], v[50:51], 0, s[48:49]
	v_lshl_add_u64 v[52:53], v[50:51], 1, s[76:77]
	v_lshl_add_u64 v[50:51], v[50:51], 2, s[78:79]
	v_pk_mul_f32 v[48:49], v[58:59], v[48:49]
	v_pk_mul_f32 v[46:47], v[146:147], v[46:47]
	v_pk_mul_f32 v[44:45], v[58:59], v[44:45]
	v_pk_mul_f32 v[42:43], v[146:147], v[42:43]
	s_and_b64 vcc, exec, s[4:5]
	v_cvt_pk_bf16_f32 v54, v46, v47
	v_cvt_pk_bf16_f32 v55, v48, v49
	v_cvt_pk_bf16_f32 v56, v42, v43
	v_cvt_pk_bf16_f32 v57, v44, v45
	global_store_dwordx4 v[52:53], v[54:57], off sc1
	s_cbranch_vccnz .LBB0_242
	global_store_dwordx4 v[50:51], v[46:49], off nt
	global_store_dwordx4 v[50:51], v[42:45], off offset:16 nt
.LBB0_242:
	s_nop 1
	v_mov_b32_e32 v42, v146
	v_mov_b32_e32 v43, v146
	v_pk_mul_f32 v[40:41], v[42:43], v[40:41]
	v_pk_mul_f32 v[38:39], v[146:147], v[38:39]
	v_pk_mul_f32 v[36:37], v[42:43], v[36:37]
	v_pk_mul_f32 v[34:35], v[146:147], v[34:35]
	s_and_b64 vcc, exec, s[4:5]
	v_cvt_pk_bf16_f32 v44, v38, v39
	v_cvt_pk_bf16_f32 v45, v40, v41
	v_cvt_pk_bf16_f32 v46, v34, v35
	v_cvt_pk_bf16_f32 v47, v36, v37
	global_store_dwordx4 v[52:53], v[44:47], off offset:256 sc1
	s_cbranch_vccnz .LBB0_244
	global_store_dwordx4 v[50:51], v[38:41], off offset:512 nt
	global_store_dwordx4 v[50:51], v[34:37], off offset:528 nt
.LBB0_244:
	s_nop 1
	v_lshlrev_b64 v[34:35], 9, v[148:149]
	v_or_b32_e32 v34, v34, v161
	s_mov_b64 s[48:49], 0x14000
	v_lshl_add_u64 v[34:35], v[34:35], 0, s[48:49]
	v_lshl_add_u64 v[36:37], v[34:35], 1, s[76:77]
	v_lshl_add_u64 v[34:35], v[34:35], 2, s[78:79]
	v_pk_mul_f32 v[32:33], v[42:43], v[32:33]
	v_pk_mul_f32 v[30:31], v[146:147], v[30:31]
	v_pk_mul_f32 v[28:29], v[42:43], v[28:29]
	v_pk_mul_f32 v[26:27], v[146:147], v[26:27]
	s_and_b64 vcc, exec, s[4:5]
	v_cvt_pk_bf16_f32 v38, v30, v31
	v_cvt_pk_bf16_f32 v39, v32, v33
	v_cvt_pk_bf16_f32 v40, v26, v27
	v_cvt_pk_bf16_f32 v41, v28, v29
	global_store_dwordx4 v[36:37], v[38:41], off sc1
	s_cbranch_vccnz .LBB0_246
	global_store_dwordx4 v[34:35], v[30:33], off nt
	global_store_dwordx4 v[34:35], v[26:29], off offset:16 nt
.LBB0_246:
	s_nop 1
	v_mov_b32_e32 v26, v146
	v_mov_b32_e32 v27, v146
	v_pk_mul_f32 v[24:25], v[26:27], v[24:25]
	v_pk_mul_f32 v[22:23], v[146:147], v[22:23]
	v_pk_mul_f32 v[20:21], v[26:27], v[20:21]
	v_pk_mul_f32 v[18:19], v[146:147], v[18:19]
	s_and_b64 vcc, exec, s[4:5]
	v_cvt_pk_bf16_f32 v28, v22, v23
	v_cvt_pk_bf16_f32 v29, v24, v25
	v_cvt_pk_bf16_f32 v30, v18, v19
	v_cvt_pk_bf16_f32 v31, v20, v21
	global_store_dwordx4 v[36:37], v[28:31], off offset:256 sc1
	s_cbranch_vccnz .LBB0_248
	global_store_dwordx4 v[34:35], v[22:25], off offset:512 nt
	global_store_dwordx4 v[34:35], v[18:21], off offset:528 nt
.LBB0_248:
	s_nop 1
	v_lshlrev_b64 v[18:19], 9, v[148:149]
	v_or_b32_e32 v18, v18, v161
	s_mov_b64 s[48:49], 0x16000
	v_lshl_add_u64 v[18:19], v[18:19], 0, s[48:49]
	v_lshl_add_u64 v[20:21], v[18:19], 1, s[76:77]
	v_lshl_add_u64 v[18:19], v[18:19], 2, s[78:79]
	v_pk_mul_f32 v[16:17], v[26:27], v[16:17]
	v_pk_mul_f32 v[14:15], v[146:147], v[14:15]
	v_pk_mul_f32 v[12:13], v[26:27], v[12:13]
	v_pk_mul_f32 v[10:11], v[146:147], v[10:11]
	s_and_b64 vcc, exec, s[4:5]
	v_cvt_pk_bf16_f32 v22, v14, v15
	v_cvt_pk_bf16_f32 v23, v16, v17
	v_cvt_pk_bf16_f32 v24, v10, v11
	v_cvt_pk_bf16_f32 v25, v12, v13
	global_store_dwordx4 v[20:21], v[22:25], off sc1
	s_cbranch_vccnz .LBB0_250
	global_store_dwordx4 v[18:19], v[14:17], off nt
	global_store_dwordx4 v[18:19], v[10:13], off offset:16 nt
.LBB0_250:
	s_nop 1
	v_mov_b32_e32 v10, v146
	v_mov_b32_e32 v11, v146
	v_pk_mul_f32 v[8:9], v[10:11], v[8:9]
	v_pk_mul_f32 v[6:7], v[146:147], v[6:7]
	v_pk_mul_f32 v[4:5], v[10:11], v[4:5]
	v_pk_mul_f32 v[2:3], v[146:147], v[2:3]
	s_and_b64 vcc, exec, s[4:5]
	v_cvt_pk_bf16_f32 v10, v6, v7
	v_cvt_pk_bf16_f32 v11, v8, v9
	v_cvt_pk_bf16_f32 v12, v2, v3
	v_cvt_pk_bf16_f32 v13, v4, v5
	global_store_dwordx4 v[20:21], v[10:13], off offset:256 sc1
	s_cbranch_vccnz .LBB0_252
	global_store_dwordx4 v[18:19], v[6:9], off offset:512 nt
	global_store_dwordx4 v[18:19], v[2:5], off offset:528 nt

.LBB0_713:
	s_or_b64 exec, exec, s[12:13]
	s_lshl_b32 s4, s33, 5
	s_lshl_b32 s5, s6, 8
	s_or_b32 s4, s5, s4
	v_add_u32_e32 v150, s3, v152
	v_and_or_b32 v148, v3, 24, s4
	v_ashrrev_i32_e32 v151, 31, v150
	v_ashrrev_i32_e32 v149, 31, v148
	s_waitcnt lgkmcnt(0)
	v_lshlrev_b64 v[132:133], 10, v[150:151]
	v_readlane_b32 s16, v244, 7
	s_waitcnt vmcnt(0) lgkmcnt(0)
	s_barrier
	v_lshl_add_u64 v[136:137], v[148:149], 2, s[52:53]
	v_lshl_add_u64 v[164:165], v[132:133], 0, v[148:149]
	v_readlane_b32 s17, v244, 8
	global_load_dwordx4 v[140:143], v[136:137], off offset:16
	global_load_dwordx4 v[144:147], v[136:137], off
	v_lshl_add_u64 v[166:167], v[164:165], 2, s[16:17]
	global_load_dwordx4 v[156:159], v[166:167], off nt
	global_load_dwordx4 v[160:163], v[166:167], off offset:16 nt
	v_lshl_add_u32 v3, v152, 2, 0
	ds_read_b32 v168, v3 offset:4096
	v_lshl_add_u64 v[164:165], v[164:165], 1, s[62:63]
	global_load_dwordx4 v[132:135], v[136:137], off offset:528
	s_nop 0
	global_load_dwordx4 v[136:139], v[136:137], off offset:512
	s_lshl_b32 s4, s6, 2
	s_ashr_i32 s5, s4, 31
	s_mov_b32 s11, 0
	v_readlane_b32 s18, v244, 9
	v_readlane_b32 s19, v244, 10
	v_readlane_b32 s20, v244, 11
	v_readlane_b32 s21, v244, 12
	v_readlane_b32 s22, v244, 13
	v_readlane_b32 s23, v244, 14
	v_readlane_b32 s24, v244, 15
	v_readlane_b32 s25, v244, 16
	v_readlane_b32 s26, v244, 17
	v_readlane_b32 s27, v244, 18
	v_readlane_b32 s28, v244, 19
	v_readlane_b32 s29, v244, 20
	v_readlane_b32 s30, v244, 21
	v_readlane_b32 s31, v244, 22
	s_waitcnt vmcnt(0)
	v_pk_mul_f32 v[126:127], v[126:127], v[142:143]
	v_pk_mul_f32 v[130:131], v[130:131], v[146:147]
	v_pk_mul_f32 v[128:129], v[128:129], v[144:145]
	v_pk_mul_f32 v[124:125], v[124:125], v[140:141]
	s_waitcnt lgkmcnt(0)
	v_pk_fma_f32 v[158:159], v[130:131], v[168:169], v[158:159] op_sel_hi:[1,0,1]
	v_pk_fma_f32 v[156:157], v[128:129], v[168:169], v[156:157] op_sel_hi:[1,0,1]
	v_pk_fma_f32 v[162:163], v[126:127], v[168:169], v[162:163] op_sel_hi:[1,0,1]
	v_pk_fma_f32 v[160:161], v[124:125], v[168:169], v[160:161] op_sel_hi:[1,0,1]
	v_cvt_pk_bf16_f32 v124, v156, v157
	v_cvt_pk_bf16_f32 v125, v158, v159
	v_pk_mul_f32 v[122:123], v[122:123], v[138:139]
	v_cvt_pk_bf16_f32 v126, v160, v161
	v_cvt_pk_bf16_f32 v127, v162, v163
	global_store_dwordx4 v[164:165], v[124:127], off sc1
	global_load_dwordx4 v[124:127], v[166:167], off offset:512 nt
	s_nop 0
	global_load_dwordx4 v[128:131], v[166:167], off offset:528 nt
	v_pk_mul_f32 v[120:121], v[120:121], v[136:137]
	v_pk_mul_f32 v[118:119], v[118:119], v[134:135]
	v_pk_mul_f32 v[116:117], v[116:117], v[132:133]
	v_mul_f32_e32 v155, v157, v157
	v_mul_f32_e32 v157, v159, v159
	v_mul_f32_e32 v159, v161, v161
	v_mul_f32_e32 v161, v163, v163
	v_fmac_f32_e32 v155, v156, v156
	v_fmac_f32_e32 v157, v158, v158
	v_fmac_f32_e32 v159, v160, v160
	v_fmac_f32_e32 v161, v162, v162
	v_add_f32_e32 v155, v155, v157
	v_add_f32_e32 v156, v159, v161
	v_add_f32_e32 v155, v155, v156
	s_waitcnt vmcnt(1)
	v_pk_fma_f32 v[122:123], v[122:123], v[168:169], v[126:127] op_sel_hi:[1,0,1]
	v_pk_fma_f32 v[120:121], v[120:121], v[168:169], v[124:125] op_sel_hi:[1,0,1]
	s_waitcnt vmcnt(0)
	v_pk_fma_f32 v[124:125], v[118:119], v[168:169], v[130:131] op_sel_hi:[1,0,1]
	v_pk_fma_f32 v[126:127], v[116:117], v[168:169], v[128:129] op_sel_hi:[1,0,1]
	v_mul_f32_e32 v116, v121, v121
	v_mul_f32_e32 v117, v123, v123
	v_mul_f32_e32 v118, v127, v127
	v_mul_f32_e32 v119, v125, v125
	v_fmac_f32_e32 v116, v120, v120
	v_fmac_f32_e32 v117, v122, v122
	v_fmac_f32_e32 v118, v126, v126
	v_fmac_f32_e32 v119, v124, v124
	v_add_f32_e32 v116, v116, v117
	v_add_f32_e32 v117, v118, v119
	v_add_f32_e32 v116, v116, v117
	v_add_f32_e32 v116, v155, v116
	ds_bpermute_b32 v117, v153, v116
	v_cvt_pk_bf16_f32 v118, v120, v121
	v_cvt_pk_bf16_f32 v119, v122, v123
	v_cvt_pk_bf16_f32 v120, v126, v127
	v_cvt_pk_bf16_f32 v121, v124, v125
	s_waitcnt lgkmcnt(0)
	v_add_f32_e32 v116, v116, v117
	ds_bpermute_b32 v117, v154, v116
	global_store_dwordx4 v[164:165], v[118:121], off offset:256 sc1
	s_and_saveexec_b64 s[6:7], s[0:1]
	s_cbranch_execz .LBB0_715
	s_waitcnt lgkmcnt(0)
	v_add_f32_e32 v118, v116, v117
	v_lshlrev_b64 v[116:117], 6, v[150:151]
	v_lshl_add_u64 v[116:117], s[86:87], 0, v[116:117]
	v_lshl_add_u64 v[116:117], s[4:5], 2, v[116:117]
	v_lshl_add_u64 v[116:117], v[116:117], 0, s[10:11]
	global_store_dword v[116:117], v118, off
.LBB0_715:
	s_or_b64 exec, exec, s[6:7]
	v_add3_u32 v116, s3, v152, 16
	s_waitcnt lgkmcnt(0)
	v_ashrrev_i32_e32 v117, 31, v116
	v_lshlrev_b64 v[118:119], 10, v[116:117]
	v_readlane_b32 s16, v244, 7
	v_lshl_add_u64 v[126:127], v[118:119], 0, v[148:149]
	v_readlane_b32 s17, v244, 8
	v_pk_mul_f32 v[114:115], v[114:115], v[146:147]
	v_pk_mul_f32 v[112:113], v[112:113], v[144:145]
	v_lshl_add_u64 v[128:129], v[126:127], 2, s[16:17]
	global_load_dwordx4 v[118:121], v[128:129], off nt
	global_load_dwordx4 v[122:125], v[128:129], off offset:16 nt
	ds_read_b32 v130, v3 offset:4160
	v_pk_mul_f32 v[110:111], v[110:111], v[142:143]
	v_pk_mul_f32 v[108:109], v[108:109], v[140:141]
	v_lshl_add_u64 v[126:127], v[126:127], 1, s[62:63]
	v_pk_mul_f32 v[106:107], v[106:107], v[138:139]
	v_pk_mul_f32 v[104:105], v[104:105], v[136:137]
	v_pk_mul_f32 v[102:103], v[102:103], v[134:135]
	v_pk_mul_f32 v[100:101], v[100:101], v[132:133]
	v_readlane_b32 s18, v244, 9
	v_readlane_b32 s19, v244, 10
	v_readlane_b32 s20, v244, 11
	v_readlane_b32 s21, v244, 12
	v_readlane_b32 s22, v244, 13
	v_readlane_b32 s23, v244, 14
	v_readlane_b32 s24, v244, 15
	v_readlane_b32 s25, v244, 16
	v_readlane_b32 s26, v244, 17
	v_readlane_b32 s27, v244, 18
	v_readlane_b32 s28, v244, 19
	v_readlane_b32 s29, v244, 20
	v_readlane_b32 s30, v244, 21
	v_readlane_b32 s31, v244, 22
	s_waitcnt vmcnt(1) lgkmcnt(0)
	v_pk_fma_f32 v[120:121], v[114:115], v[130:131], v[120:121] op_sel_hi:[1,0,1]
	v_pk_fma_f32 v[118:119], v[112:113], v[130:131], v[118:119] op_sel_hi:[1,0,1]
	s_waitcnt vmcnt(0)
	v_pk_fma_f32 v[124:125], v[110:111], v[130:131], v[124:125] op_sel_hi:[1,0,1]
	v_pk_fma_f32 v[122:123], v[108:109], v[130:131], v[122:123] op_sel_hi:[1,0,1]
	v_cvt_pk_bf16_f32 v108, v118, v119
	v_cvt_pk_bf16_f32 v109, v120, v121
	v_mul_f32_e32 v119, v119, v119
	v_cvt_pk_bf16_f32 v110, v122, v123
	v_cvt_pk_bf16_f32 v111, v124, v125
	global_store_dwordx4 v[126:127], v[108:111], off sc1
	global_load_dwordx4 v[108:111], v[128:129], off offset:512 nt
	s_nop 0
	global_load_dwordx4 v[112:115], v[128:129], off offset:528 nt
	v_mul_f32_e32 v121, v121, v121
	v_mul_f32_e32 v123, v123, v123
	v_mul_f32_e32 v125, v125, v125
	v_fmac_f32_e32 v119, v118, v118
	v_fmac_f32_e32 v121, v120, v120
	v_fmac_f32_e32 v123, v122, v122
	v_fmac_f32_e32 v125, v124, v124
	v_add_f32_e32 v118, v119, v121
	v_add_f32_e32 v119, v123, v125
	v_add_f32_e32 v118, v118, v119
	s_waitcnt vmcnt(1)
	v_pk_fma_f32 v[106:107], v[106:107], v[130:131], v[110:111] op_sel_hi:[1,0,1]
	v_pk_fma_f32 v[104:105], v[104:105], v[130:131], v[108:109] op_sel_hi:[1,0,1]
	s_waitcnt vmcnt(0)
	v_pk_fma_f32 v[108:109], v[102:103], v[130:131], v[114:115] op_sel_hi:[1,0,1]
	v_pk_fma_f32 v[110:111], v[100:101], v[130:131], v[112:113] op_sel_hi:[1,0,1]
	v_mul_f32_e32 v100, v105, v105
	v_mul_f32_e32 v101, v107, v107
	v_mul_f32_e32 v102, v111, v111
	v_mul_f32_e32 v103, v109, v109
	v_fmac_f32_e32 v100, v104, v104
	v_fmac_f32_e32 v101, v106, v106
	v_fmac_f32_e32 v102, v110, v110
	v_fmac_f32_e32 v103, v108, v108
	v_add_f32_e32 v100, v100, v101
	v_add_f32_e32 v101, v102, v103
	v_add_f32_e32 v100, v100, v101
	v_add_f32_e32 v100, v118, v100
	ds_bpermute_b32 v101, v153, v100
	v_cvt_pk_bf16_f32 v102, v104, v105
	v_cvt_pk_bf16_f32 v103, v106, v107
	v_cvt_pk_bf16_f32 v104, v110, v111
	v_cvt_pk_bf16_f32 v105, v108, v109
	s_waitcnt lgkmcnt(0)
	v_add_f32_e32 v100, v100, v101
	ds_bpermute_b32 v101, v154, v100
	global_store_dwordx4 v[126:127], v[102:105], off offset:256 sc1
	s_and_saveexec_b64 s[6:7], s[0:1]
	s_cbranch_execz .LBB0_717
	s_waitcnt lgkmcnt(0)
	v_add_f32_e32 v102, v100, v101
	v_lshlrev_b64 v[100:101], 6, v[116:117]
	v_lshl_add_u64 v[100:101], s[86:87], 0, v[100:101]
	v_lshl_add_u64 v[100:101], s[4:5], 2, v[100:101]
	v_lshl_add_u64 v[100:101], v[100:101], 0, s[10:11]
	global_store_dword v[100:101], v102, off
.LBB0_717:
	s_or_b64 exec, exec, s[6:7]
	v_add3_u32 v100, s3, v152, 32
	s_waitcnt lgkmcnt(0)
	v_ashrrev_i32_e32 v101, 31, v100
	v_lshlrev_b64 v[102:103], 10, v[100:101]
	v_readlane_b32 s16, v244, 7
	v_lshl_add_u64 v[110:111], v[102:103], 0, v[148:149]
	v_readlane_b32 s17, v244, 8
	v_pk_mul_f32 v[98:99], v[98:99], v[146:147]
	v_pk_mul_f32 v[96:97], v[96:97], v[144:145]
	v_lshl_add_u64 v[112:113], v[110:111], 2, s[16:17]
	global_load_dwordx4 v[102:105], v[112:113], off nt
	global_load_dwordx4 v[106:109], v[112:113], off offset:16 nt
	ds_read_b32 v114, v3 offset:4224
	v_pk_mul_f32 v[94:95], v[94:95], v[142:143]
	v_pk_mul_f32 v[92:93], v[92:93], v[140:141]
	v_lshl_add_u64 v[110:111], v[110:111], 1, s[62:63]
	v_pk_mul_f32 v[90:91], v[90:91], v[138:139]
	v_pk_mul_f32 v[88:89], v[88:89], v[136:137]
	v_pk_mul_f32 v[86:87], v[86:87], v[134:135]
	v_pk_mul_f32 v[84:85], v[84:85], v[132:133]
	v_readlane_b32 s18, v244, 9
	v_readlane_b32 s19, v244, 10
	v_readlane_b32 s20, v244, 11
	v_readlane_b32 s21, v244, 12
	v_readlane_b32 s22, v244, 13
	v_readlane_b32 s23, v244, 14
	v_readlane_b32 s24, v244, 15
	v_readlane_b32 s25, v244, 16
	v_readlane_b32 s26, v244, 17
	v_readlane_b32 s27, v244, 18
	v_readlane_b32 s28, v244, 19
	v_readlane_b32 s29, v244, 20
	v_readlane_b32 s30, v244, 21
	v_readlane_b32 s31, v244, 22
	s_waitcnt vmcnt(1) lgkmcnt(0)
	v_pk_fma_f32 v[104:105], v[98:99], v[114:115], v[104:105] op_sel_hi:[1,0,1]
	v_pk_fma_f32 v[102:103], v[96:97], v[114:115], v[102:103] op_sel_hi:[1,0,1]
	s_waitcnt vmcnt(0)
	v_pk_fma_f32 v[108:109], v[94:95], v[114:115], v[108:109] op_sel_hi:[1,0,1]
	v_pk_fma_f32 v[106:107], v[92:93], v[114:115], v[106:107] op_sel_hi:[1,0,1]
	v_cvt_pk_bf16_f32 v92, v102, v103
	v_cvt_pk_bf16_f32 v93, v104, v105
	v_mul_f32_e32 v103, v103, v103
	v_cvt_pk_bf16_f32 v94, v106, v107
	v_cvt_pk_bf16_f32 v95, v108, v109
	global_store_dwordx4 v[110:111], v[92:95], off sc1
	global_load_dwordx4 v[92:95], v[112:113], off offset:512 nt
	s_nop 0
	global_load_dwordx4 v[96:99], v[112:113], off offset:528 nt
	v_mul_f32_e32 v105, v105, v105
	v_mul_f32_e32 v107, v107, v107
	v_mul_f32_e32 v109, v109, v109
	v_fmac_f32_e32 v103, v102, v102
	v_fmac_f32_e32 v105, v104, v104
	v_fmac_f32_e32 v107, v106, v106
	v_fmac_f32_e32 v109, v108, v108
	v_add_f32_e32 v102, v103, v105
	v_add_f32_e32 v103, v107, v109
	v_add_f32_e32 v102, v102, v103
	s_waitcnt vmcnt(1)
	v_pk_fma_f32 v[90:91], v[90:91], v[114:115], v[94:95] op_sel_hi:[1,0,1]
	v_pk_fma_f32 v[88:89], v[88:89], v[114:115], v[92:93] op_sel_hi:[1,0,1]
	s_waitcnt vmcnt(0)
	v_pk_fma_f32 v[92:93], v[86:87], v[114:115], v[98:99] op_sel_hi:[1,0,1]
	v_pk_fma_f32 v[94:95], v[84:85], v[114:115], v[96:97] op_sel_hi:[1,0,1]
	v_mul_f32_e32 v84, v89, v89
	v_mul_f32_e32 v85, v91, v91
	v_mul_f32_e32 v86, v95, v95
	v_mul_f32_e32 v87, v93, v93
	v_fmac_f32_e32 v84, v88, v88
	v_fmac_f32_e32 v85, v90, v90
	v_fmac_f32_e32 v86, v94, v94
	v_fmac_f32_e32 v87, v92, v92
	v_add_f32_e32 v84, v84, v85
	v_add_f32_e32 v85, v86, v87
	v_add_f32_e32 v84, v84, v85
	v_add_f32_e32 v84, v102, v84
	ds_bpermute_b32 v85, v153, v84
	v_cvt_pk_bf16_f32 v86, v88, v89
	v_cvt_pk_bf16_f32 v87, v90, v91
	v_cvt_pk_bf16_f32 v88, v94, v95
	v_cvt_pk_bf16_f32 v89, v92, v93
	s_waitcnt lgkmcnt(0)
	v_add_f32_e32 v84, v84, v85
	ds_bpermute_b32 v85, v154, v84
	global_store_dwordx4 v[110:111], v[86:89], off offset:256 sc1
	s_and_saveexec_b64 s[6:7], s[0:1]
	s_cbranch_execz .LBB0_719
	s_waitcnt lgkmcnt(0)
	v_add_f32_e32 v86, v84, v85
	v_lshlrev_b64 v[84:85], 6, v[100:101]
	v_lshl_add_u64 v[84:85], s[86:87], 0, v[84:85]
	v_lshl_add_u64 v[84:85], s[4:5], 2, v[84:85]
	v_lshl_add_u64 v[84:85], v[84:85], 0, s[10:11]
	global_store_dword v[84:85], v86, off
.LBB0_719:
	s_or_b64 exec, exec, s[6:7]
	v_add3_u32 v84, s3, v152, 48
	s_waitcnt lgkmcnt(0)
	v_ashrrev_i32_e32 v85, 31, v84
	v_lshlrev_b64 v[86:87], 10, v[84:85]
	v_readlane_b32 s16, v244, 7
	v_lshl_add_u64 v[94:95], v[86:87], 0, v[148:149]
	v_readlane_b32 s17, v244, 8
	v_pk_mul_f32 v[82:83], v[82:83], v[146:147]
	v_pk_mul_f32 v[80:81], v[80:81], v[144:145]
	v_lshl_add_u64 v[96:97], v[94:95], 2, s[16:17]
	global_load_dwordx4 v[86:89], v[96:97], off nt
	global_load_dwordx4 v[90:93], v[96:97], off offset:16 nt
	ds_read_b32 v98, v3 offset:4288
	v_pk_mul_f32 v[78:79], v[78:79], v[142:143]
	v_pk_mul_f32 v[76:77], v[76:77], v[140:141]
	v_lshl_add_u64 v[94:95], v[94:95], 1, s[62:63]
	v_pk_mul_f32 v[74:75], v[74:75], v[138:139]
	v_pk_mul_f32 v[72:73], v[72:73], v[136:137]
	v_pk_mul_f32 v[70:71], v[70:71], v[134:135]
	v_pk_mul_f32 v[68:69], v[68:69], v[132:133]
	v_readlane_b32 s18, v244, 9
	v_readlane_b32 s19, v244, 10
	v_readlane_b32 s20, v244, 11
	v_readlane_b32 s21, v244, 12
	v_readlane_b32 s22, v244, 13
	v_readlane_b32 s23, v244, 14
	v_readlane_b32 s24, v244, 15
	v_readlane_b32 s25, v244, 16
	v_readlane_b32 s26, v244, 17
	v_readlane_b32 s27, v244, 18
	v_readlane_b32 s28, v244, 19
	v_readlane_b32 s29, v244, 20
	v_readlane_b32 s30, v244, 21
	v_readlane_b32 s31, v244, 22
	s_waitcnt vmcnt(1) lgkmcnt(0)
	v_pk_fma_f32 v[88:89], v[82:83], v[98:99], v[88:89] op_sel_hi:[1,0,1]
	v_pk_fma_f32 v[86:87], v[80:81], v[98:99], v[86:87] op_sel_hi:[1,0,1]
	s_waitcnt vmcnt(0)
	v_pk_fma_f32 v[92:93], v[78:79], v[98:99], v[92:93] op_sel_hi:[1,0,1]
	v_pk_fma_f32 v[90:91], v[76:77], v[98:99], v[90:91] op_sel_hi:[1,0,1]
	v_cvt_pk_bf16_f32 v76, v86, v87
	v_cvt_pk_bf16_f32 v77, v88, v89
	v_mul_f32_e32 v87, v87, v87
	v_cvt_pk_bf16_f32 v78, v90, v91
	v_cvt_pk_bf16_f32 v79, v92, v93
	global_store_dwordx4 v[94:95], v[76:79], off sc1
	global_load_dwordx4 v[76:79], v[96:97], off offset:512 nt
	s_nop 0
	global_load_dwordx4 v[80:83], v[96:97], off offset:528 nt
	v_mul_f32_e32 v89, v89, v89
	v_mul_f32_e32 v91, v91, v91
	v_mul_f32_e32 v93, v93, v93
	v_fmac_f32_e32 v87, v86, v86
	v_fmac_f32_e32 v89, v88, v88
	v_fmac_f32_e32 v91, v90, v90
	v_fmac_f32_e32 v93, v92, v92
	v_add_f32_e32 v86, v87, v89
	v_add_f32_e32 v87, v91, v93
	v_add_f32_e32 v86, v86, v87
	s_waitcnt vmcnt(1)
	v_pk_fma_f32 v[74:75], v[74:75], v[98:99], v[78:79] op_sel_hi:[1,0,1]
	v_pk_fma_f32 v[72:73], v[72:73], v[98:99], v[76:77] op_sel_hi:[1,0,1]
	s_waitcnt vmcnt(0)
	v_pk_fma_f32 v[76:77], v[70:71], v[98:99], v[82:83] op_sel_hi:[1,0,1]
	v_pk_fma_f32 v[78:79], v[68:69], v[98:99], v[80:81] op_sel_hi:[1,0,1]
	v_mul_f32_e32 v68, v73, v73
	v_mul_f32_e32 v69, v75, v75
	v_mul_f32_e32 v70, v79, v79
	v_mul_f32_e32 v71, v77, v77
	v_fmac_f32_e32 v68, v72, v72
	v_fmac_f32_e32 v69, v74, v74
	v_fmac_f32_e32 v70, v78, v78
	v_fmac_f32_e32 v71, v76, v76
	v_add_f32_e32 v68, v68, v69
	v_add_f32_e32 v69, v70, v71
	v_add_f32_e32 v68, v68, v69
	v_add_f32_e32 v68, v86, v68
	ds_bpermute_b32 v69, v153, v68
	v_cvt_pk_bf16_f32 v70, v72, v73
	v_cvt_pk_bf16_f32 v71, v74, v75
	v_cvt_pk_bf16_f32 v72, v78, v79
	v_cvt_pk_bf16_f32 v73, v76, v77
	s_waitcnt lgkmcnt(0)
	v_add_f32_e32 v68, v68, v69
	ds_bpermute_b32 v69, v154, v68
	global_store_dwordx4 v[94:95], v[70:73], off offset:256 sc1
	s_and_saveexec_b64 s[6:7], s[0:1]
	s_cbranch_execz .LBB0_721
	s_waitcnt lgkmcnt(0)
	v_add_f32_e32 v70, v68, v69
	v_lshlrev_b64 v[68:69], 6, v[84:85]
	v_lshl_add_u64 v[68:69], s[86:87], 0, v[68:69]
	v_lshl_add_u64 v[68:69], s[4:5], 2, v[68:69]
	v_lshl_add_u64 v[68:69], v[68:69], 0, s[10:11]
	global_store_dword v[68:69], v70, off
.LBB0_721:
	s_or_b64 exec, exec, s[6:7]
	v_add_u32_e32 v68, 0x80, v150
	s_waitcnt lgkmcnt(0)
	v_ashrrev_i32_e32 v69, 31, v68
	v_lshlrev_b64 v[70:71], 10, v[68:69]
	v_readlane_b32 s16, v244, 7
	v_lshl_add_u64 v[78:79], v[70:71], 0, v[148:149]
	v_readlane_b32 s17, v244, 8
	v_pk_mul_f32 v[66:67], v[66:67], v[146:147]
	v_pk_mul_f32 v[64:65], v[64:65], v[144:145]
	v_lshl_add_u64 v[80:81], v[78:79], 2, s[16:17]
	global_load_dwordx4 v[70:73], v[80:81], off nt
	global_load_dwordx4 v[74:77], v[80:81], off offset:16 nt
	ds_read_b32 v82, v3 offset:4608
	v_pk_mul_f32 v[62:63], v[62:63], v[142:143]
	v_pk_mul_f32 v[60:61], v[60:61], v[140:141]
	v_lshl_add_u64 v[78:79], v[78:79], 1, s[62:63]
	v_pk_mul_f32 v[58:59], v[58:59], v[138:139]
	v_pk_mul_f32 v[56:57], v[56:57], v[136:137]
	v_pk_mul_f32 v[54:55], v[54:55], v[134:135]
	v_pk_mul_f32 v[52:53], v[52:53], v[132:133]
	v_readlane_b32 s18, v244, 9
	v_readlane_b32 s19, v244, 10
	v_readlane_b32 s20, v244, 11
	v_readlane_b32 s21, v244, 12
	v_readlane_b32 s22, v244, 13
	v_readlane_b32 s23, v244, 14
	v_readlane_b32 s24, v244, 15
	v_readlane_b32 s25, v244, 16
	v_readlane_b32 s26, v244, 17
	v_readlane_b32 s27, v244, 18
	v_readlane_b32 s28, v244, 19
	v_readlane_b32 s29, v244, 20
	v_readlane_b32 s30, v244, 21
	v_readlane_b32 s31, v244, 22
	s_waitcnt vmcnt(1) lgkmcnt(0)
	v_pk_fma_f32 v[72:73], v[66:67], v[82:83], v[72:73] op_sel_hi:[1,0,1]
	v_pk_fma_f32 v[70:71], v[64:65], v[82:83], v[70:71] op_sel_hi:[1,0,1]
	s_waitcnt vmcnt(0)
	v_pk_fma_f32 v[76:77], v[62:63], v[82:83], v[76:77] op_sel_hi:[1,0,1]
	v_pk_fma_f32 v[74:75], v[60:61], v[82:83], v[74:75] op_sel_hi:[1,0,1]
	v_cvt_pk_bf16_f32 v60, v70, v71
	v_cvt_pk_bf16_f32 v61, v72, v73
	v_mul_f32_e32 v71, v71, v71
	v_cvt_pk_bf16_f32 v62, v74, v75
	v_cvt_pk_bf16_f32 v63, v76, v77
	global_store_dwordx4 v[78:79], v[60:63], off sc1
	global_load_dwordx4 v[60:63], v[80:81], off offset:512 nt
	s_nop 0
	global_load_dwordx4 v[64:67], v[80:81], off offset:528 nt
	v_mul_f32_e32 v73, v73, v73
	v_mul_f32_e32 v75, v75, v75
	v_mul_f32_e32 v77, v77, v77
	v_fmac_f32_e32 v71, v70, v70
	v_fmac_f32_e32 v73, v72, v72
	v_fmac_f32_e32 v75, v74, v74
	v_fmac_f32_e32 v77, v76, v76
	v_add_f32_e32 v70, v71, v73
	v_add_f32_e32 v71, v75, v77
	v_add_f32_e32 v70, v70, v71
	s_waitcnt vmcnt(1)
	v_pk_fma_f32 v[58:59], v[58:59], v[82:83], v[62:63] op_sel_hi:[1,0,1]
	v_pk_fma_f32 v[56:57], v[56:57], v[82:83], v[60:61] op_sel_hi:[1,0,1]
	s_waitcnt vmcnt(0)
	v_pk_fma_f32 v[60:61], v[54:55], v[82:83], v[66:67] op_sel_hi:[1,0,1]
	v_pk_fma_f32 v[62:63], v[52:53], v[82:83], v[64:65] op_sel_hi:[1,0,1]
	v_mul_f32_e32 v52, v57, v57
	v_mul_f32_e32 v53, v59, v59
	v_mul_f32_e32 v54, v63, v63
	v_mul_f32_e32 v55, v61, v61
	v_fmac_f32_e32 v52, v56, v56
	v_fmac_f32_e32 v53, v58, v58
	v_fmac_f32_e32 v54, v62, v62
	v_fmac_f32_e32 v55, v60, v60
	v_add_f32_e32 v52, v52, v53
	v_add_f32_e32 v53, v54, v55
	v_add_f32_e32 v52, v52, v53
	v_add_f32_e32 v52, v70, v52
	ds_bpermute_b32 v53, v153, v52
	v_cvt_pk_bf16_f32 v54, v56, v57
	v_cvt_pk_bf16_f32 v55, v58, v59
	v_cvt_pk_bf16_f32 v56, v62, v63
	v_cvt_pk_bf16_f32 v57, v60, v61
	s_waitcnt lgkmcnt(0)
	v_add_f32_e32 v52, v52, v53
	ds_bpermute_b32 v53, v154, v52
	global_store_dwordx4 v[78:79], v[54:57], off offset:256 sc1
	s_and_saveexec_b64 s[6:7], s[0:1]
	s_cbranch_execz .LBB0_723
	s_waitcnt lgkmcnt(0)
	v_add_f32_e32 v54, v52, v53
	v_lshlrev_b64 v[52:53], 6, v[68:69]
	v_lshl_add_u64 v[52:53], s[86:87], 0, v[52:53]
	v_lshl_add_u64 v[52:53], s[4:5], 2, v[52:53]
	v_lshl_add_u64 v[52:53], v[52:53], 0, s[10:11]
	global_store_dword v[52:53], v54, off
.LBB0_723:
	s_or_b64 exec, exec, s[6:7]
	v_add_u32_e32 v52, 0x90, v150
	s_waitcnt lgkmcnt(0)
	v_ashrrev_i32_e32 v53, 31, v52
	v_lshlrev_b64 v[54:55], 10, v[52:53]
	v_readlane_b32 s16, v244, 7
	v_lshl_add_u64 v[62:63], v[54:55], 0, v[148:149]
	v_readlane_b32 s17, v244, 8
	v_pk_mul_f32 v[50:51], v[50:51], v[146:147]
	v_pk_mul_f32 v[48:49], v[48:49], v[144:145]
	v_lshl_add_u64 v[64:65], v[62:63], 2, s[16:17]
	global_load_dwordx4 v[54:57], v[64:65], off nt
	global_load_dwordx4 v[58:61], v[64:65], off offset:16 nt
	ds_read_b32 v66, v3 offset:4672
	v_pk_mul_f32 v[46:47], v[46:47], v[142:143]
	v_pk_mul_f32 v[44:45], v[44:45], v[140:141]
	v_lshl_add_u64 v[62:63], v[62:63], 1, s[62:63]
	v_pk_mul_f32 v[42:43], v[42:43], v[138:139]
	v_pk_mul_f32 v[40:41], v[40:41], v[136:137]
	v_pk_mul_f32 v[38:39], v[38:39], v[134:135]
	v_pk_mul_f32 v[36:37], v[36:37], v[132:133]
	v_readlane_b32 s18, v244, 9
	v_readlane_b32 s19, v244, 10
	v_readlane_b32 s20, v244, 11
	v_readlane_b32 s21, v244, 12
	v_readlane_b32 s22, v244, 13
	v_readlane_b32 s23, v244, 14
	v_readlane_b32 s24, v244, 15
	v_readlane_b32 s25, v244, 16
	v_readlane_b32 s26, v244, 17
	v_readlane_b32 s27, v244, 18
	v_readlane_b32 s28, v244, 19
	v_readlane_b32 s29, v244, 20
	v_readlane_b32 s30, v244, 21
	v_readlane_b32 s31, v244, 22
	s_waitcnt vmcnt(1) lgkmcnt(0)
	v_pk_fma_f32 v[56:57], v[50:51], v[66:67], v[56:57] op_sel_hi:[1,0,1]
	v_pk_fma_f32 v[54:55], v[48:49], v[66:67], v[54:55] op_sel_hi:[1,0,1]
	s_waitcnt vmcnt(0)
	v_pk_fma_f32 v[60:61], v[46:47], v[66:67], v[60:61] op_sel_hi:[1,0,1]
	v_pk_fma_f32 v[58:59], v[44:45], v[66:67], v[58:59] op_sel_hi:[1,0,1]
	v_cvt_pk_bf16_f32 v44, v54, v55
	v_cvt_pk_bf16_f32 v45, v56, v57
	v_mul_f32_e32 v55, v55, v55
	v_cvt_pk_bf16_f32 v46, v58, v59
	v_cvt_pk_bf16_f32 v47, v60, v61
	global_store_dwordx4 v[62:63], v[44:47], off sc1
	global_load_dwordx4 v[44:47], v[64:65], off offset:512 nt
	s_nop 0
	global_load_dwordx4 v[48:51], v[64:65], off offset:528 nt
	v_mul_f32_e32 v57, v57, v57
	v_mul_f32_e32 v59, v59, v59
	v_mul_f32_e32 v61, v61, v61
	v_fmac_f32_e32 v55, v54, v54
	v_fmac_f32_e32 v57, v56, v56
	v_fmac_f32_e32 v59, v58, v58
	v_fmac_f32_e32 v61, v60, v60
	v_add_f32_e32 v54, v55, v57
	v_add_f32_e32 v55, v59, v61
	v_add_f32_e32 v54, v54, v55
	s_waitcnt vmcnt(1)
	v_pk_fma_f32 v[42:43], v[42:43], v[66:67], v[46:47] op_sel_hi:[1,0,1]
	v_pk_fma_f32 v[40:41], v[40:41], v[66:67], v[44:45] op_sel_hi:[1,0,1]
	s_waitcnt vmcnt(0)
	v_pk_fma_f32 v[44:45], v[38:39], v[66:67], v[50:51] op_sel_hi:[1,0,1]
	v_pk_fma_f32 v[46:47], v[36:37], v[66:67], v[48:49] op_sel_hi:[1,0,1]
	v_mul_f32_e32 v36, v41, v41
	v_mul_f32_e32 v37, v43, v43
	v_mul_f32_e32 v38, v47, v47
	v_mul_f32_e32 v39, v45, v45
	v_fmac_f32_e32 v36, v40, v40
	v_fmac_f32_e32 v37, v42, v42
	v_fmac_f32_e32 v38, v46, v46
	v_fmac_f32_e32 v39, v44, v44
	v_add_f32_e32 v36, v36, v37
	v_add_f32_e32 v37, v38, v39
	v_add_f32_e32 v36, v36, v37
	v_add_f32_e32 v36, v54, v36
	ds_bpermute_b32 v37, v153, v36
	v_cvt_pk_bf16_f32 v38, v40, v41
	v_cvt_pk_bf16_f32 v39, v42, v43
	v_cvt_pk_bf16_f32 v40, v46, v47
	v_cvt_pk_bf16_f32 v41, v44, v45
	s_waitcnt lgkmcnt(0)
	v_add_f32_e32 v36, v36, v37
	ds_bpermute_b32 v37, v154, v36
	global_store_dwordx4 v[62:63], v[38:41], off offset:256 sc1
	s_and_saveexec_b64 s[6:7], s[0:1]
	s_cbranch_execz .LBB0_725
	s_waitcnt lgkmcnt(0)
	v_add_f32_e32 v38, v36, v37
	v_lshlrev_b64 v[36:37], 6, v[52:53]
	v_lshl_add_u64 v[36:37], s[86:87], 0, v[36:37]
	v_lshl_add_u64 v[36:37], s[4:5], 2, v[36:37]
	v_lshl_add_u64 v[36:37], v[36:37], 0, s[10:11]
	global_store_dword v[36:37], v38, off
.LBB0_725:
	s_or_b64 exec, exec, s[6:7]
	v_add_u32_e32 v36, 0xa0, v150
	s_waitcnt lgkmcnt(0)
	v_ashrrev_i32_e32 v37, 31, v36
	v_lshlrev_b64 v[38:39], 10, v[36:37]
	v_readlane_b32 s16, v244, 7
	v_lshl_add_u64 v[46:47], v[38:39], 0, v[148:149]
	v_readlane_b32 s17, v244, 8
	v_pk_mul_f32 v[34:35], v[34:35], v[146:147]
	v_pk_mul_f32 v[32:33], v[32:33], v[144:145]
	v_lshl_add_u64 v[48:49], v[46:47], 2, s[16:17]
	global_load_dwordx4 v[38:41], v[48:49], off nt
	global_load_dwordx4 v[42:45], v[48:49], off offset:16 nt
	ds_read_b32 v50, v3 offset:4736
	v_pk_mul_f32 v[30:31], v[30:31], v[142:143]
	v_pk_mul_f32 v[28:29], v[28:29], v[140:141]
	v_lshl_add_u64 v[46:47], v[46:47], 1, s[62:63]
	v_pk_mul_f32 v[26:27], v[26:27], v[138:139]
	v_pk_mul_f32 v[24:25], v[24:25], v[136:137]
	v_pk_mul_f32 v[22:23], v[22:23], v[134:135]
	v_pk_mul_f32 v[20:21], v[20:21], v[132:133]
	v_readlane_b32 s18, v244, 9
	v_readlane_b32 s19, v244, 10
	v_readlane_b32 s20, v244, 11
	v_readlane_b32 s21, v244, 12
	v_readlane_b32 s22, v244, 13
	v_readlane_b32 s23, v244, 14
	v_readlane_b32 s24, v244, 15
	v_readlane_b32 s25, v244, 16
	v_readlane_b32 s26, v244, 17
	v_readlane_b32 s27, v244, 18
	v_readlane_b32 s28, v244, 19
	v_readlane_b32 s29, v244, 20
	v_readlane_b32 s30, v244, 21
	v_readlane_b32 s31, v244, 22
	s_waitcnt vmcnt(1) lgkmcnt(0)
	v_pk_fma_f32 v[40:41], v[34:35], v[50:51], v[40:41] op_sel_hi:[1,0,1]
	v_pk_fma_f32 v[38:39], v[32:33], v[50:51], v[38:39] op_sel_hi:[1,0,1]
	s_waitcnt vmcnt(0)
	v_pk_fma_f32 v[44:45], v[30:31], v[50:51], v[44:45] op_sel_hi:[1,0,1]
	v_pk_fma_f32 v[42:43], v[28:29], v[50:51], v[42:43] op_sel_hi:[1,0,1]
	v_cvt_pk_bf16_f32 v28, v38, v39
	v_cvt_pk_bf16_f32 v29, v40, v41
	v_mul_f32_e32 v39, v39, v39
	v_cvt_pk_bf16_f32 v30, v42, v43
	v_cvt_pk_bf16_f32 v31, v44, v45
	global_store_dwordx4 v[46:47], v[28:31], off sc1
	global_load_dwordx4 v[28:31], v[48:49], off offset:512 nt
	s_nop 0
	global_load_dwordx4 v[32:35], v[48:49], off offset:528 nt
	v_mul_f32_e32 v41, v41, v41
	v_mul_f32_e32 v43, v43, v43
	v_mul_f32_e32 v45, v45, v45
	v_fmac_f32_e32 v39, v38, v38
	v_fmac_f32_e32 v41, v40, v40
	v_fmac_f32_e32 v43, v42, v42
	v_fmac_f32_e32 v45, v44, v44
	v_add_f32_e32 v38, v39, v41
	v_add_f32_e32 v39, v43, v45
	v_add_f32_e32 v38, v38, v39
	s_waitcnt vmcnt(1)
	v_pk_fma_f32 v[26:27], v[26:27], v[50:51], v[30:31] op_sel_hi:[1,0,1]
	v_pk_fma_f32 v[24:25], v[24:25], v[50:51], v[28:29] op_sel_hi:[1,0,1]
	s_waitcnt vmcnt(0)
	v_pk_fma_f32 v[28:29], v[22:23], v[50:51], v[34:35] op_sel_hi:[1,0,1]
	v_pk_fma_f32 v[30:31], v[20:21], v[50:51], v[32:33] op_sel_hi:[1,0,1]
	v_mul_f32_e32 v20, v25, v25
	v_mul_f32_e32 v21, v27, v27
	v_mul_f32_e32 v22, v31, v31
	v_mul_f32_e32 v23, v29, v29
	v_fmac_f32_e32 v20, v24, v24
	v_fmac_f32_e32 v21, v26, v26
	v_fmac_f32_e32 v22, v30, v30
	v_fmac_f32_e32 v23, v28, v28
	v_add_f32_e32 v20, v20, v21
	v_add_f32_e32 v21, v22, v23
	v_add_f32_e32 v20, v20, v21
	v_add_f32_e32 v20, v38, v20
	ds_bpermute_b32 v21, v153, v20
	v_cvt_pk_bf16_f32 v22, v24, v25
	v_cvt_pk_bf16_f32 v23, v26, v27
	v_cvt_pk_bf16_f32 v24, v30, v31
	v_cvt_pk_bf16_f32 v25, v28, v29
	s_waitcnt lgkmcnt(0)
	v_add_f32_e32 v20, v20, v21
	ds_bpermute_b32 v21, v154, v20
	global_store_dwordx4 v[46:47], v[22:25], off offset:256 sc1
	s_and_saveexec_b64 s[6:7], s[0:1]
	s_cbranch_execz .LBB0_727
	s_waitcnt lgkmcnt(0)
	v_add_f32_e32 v22, v20, v21
	v_lshlrev_b64 v[20:21], 6, v[36:37]
	v_lshl_add_u64 v[20:21], s[86:87], 0, v[20:21]
	v_lshl_add_u64 v[20:21], s[4:5], 2, v[20:21]
	v_lshl_add_u64 v[20:21], v[20:21], 0, s[10:11]
	global_store_dword v[20:21], v22, off
.LBB0_727:
	s_or_b64 exec, exec, s[6:7]
	v_add_u32_e32 v20, 0xb0, v150
	s_waitcnt lgkmcnt(0)
	v_ashrrev_i32_e32 v21, 31, v20
	v_lshlrev_b64 v[22:23], 10, v[20:21]
	v_readlane_b32 s16, v244, 7
	v_lshl_add_u64 v[30:31], v[22:23], 0, v[148:149]
	v_readlane_b32 s17, v244, 8
	v_pk_mul_f32 v[18:19], v[18:19], v[146:147]
	v_pk_mul_f32 v[16:17], v[16:17], v[144:145]
	v_lshl_add_u64 v[32:33], v[30:31], 2, s[16:17]
	global_load_dwordx4 v[22:25], v[32:33], off nt
	global_load_dwordx4 v[26:29], v[32:33], off offset:16 nt
	ds_read_b32 v34, v3 offset:4800
	v_pk_mul_f32 v[14:15], v[14:15], v[142:143]
	v_pk_mul_f32 v[12:13], v[12:13], v[140:141]
	v_lshl_add_u64 v[30:31], v[30:31], 1, s[62:63]
	v_pk_mul_f32 v[10:11], v[10:11], v[138:139]
	v_pk_mul_f32 v[8:9], v[8:9], v[136:137]
	v_pk_mul_f32 v[6:7], v[6:7], v[134:135]
	v_pk_mul_f32 v[4:5], v[4:5], v[132:133]
	v_readlane_b32 s18, v244, 9
	v_readlane_b32 s19, v244, 10
	v_readlane_b32 s20, v244, 11
	v_readlane_b32 s21, v244, 12
	v_readlane_b32 s22, v244, 13
	v_readlane_b32 s23, v244, 14
	v_readlane_b32 s24, v244, 15
	v_readlane_b32 s25, v244, 16
	v_readlane_b32 s26, v244, 17
	v_readlane_b32 s27, v244, 18
	v_readlane_b32 s28, v244, 19
	v_readlane_b32 s29, v244, 20
	v_readlane_b32 s30, v244, 21
	v_readlane_b32 s31, v244, 22
	s_waitcnt vmcnt(1) lgkmcnt(0)
	v_pk_fma_f32 v[24:25], v[18:19], v[34:35], v[24:25] op_sel_hi:[1,0,1]
	v_pk_fma_f32 v[22:23], v[16:17], v[34:35], v[22:23] op_sel_hi:[1,0,1]
	s_waitcnt vmcnt(0)
	v_pk_fma_f32 v[28:29], v[14:15], v[34:35], v[28:29] op_sel_hi:[1,0,1]
	v_pk_fma_f32 v[26:27], v[12:13], v[34:35], v[26:27] op_sel_hi:[1,0,1]
	v_cvt_pk_bf16_f32 v12, v22, v23
	v_cvt_pk_bf16_f32 v13, v24, v25
	v_mul_f32_e32 v3, v23, v23
	v_cvt_pk_bf16_f32 v14, v26, v27
	v_cvt_pk_bf16_f32 v15, v28, v29
	global_store_dwordx4 v[30:31], v[12:15], off sc1
	global_load_dwordx4 v[12:15], v[32:33], off offset:512 nt
	s_nop 0
	global_load_dwordx4 v[16:19], v[32:33], off offset:528 nt
	v_mul_f32_e32 v23, v25, v25
	v_mul_f32_e32 v25, v27, v27
	v_mul_f32_e32 v27, v29, v29
	v_fmac_f32_e32 v3, v22, v22
	v_fmac_f32_e32 v23, v24, v24
	v_fmac_f32_e32 v25, v26, v26
	v_fmac_f32_e32 v27, v28, v28
	v_add_f32_e32 v3, v3, v23
	v_add_f32_e32 v22, v25, v27
	v_add_f32_e32 v3, v3, v22
	s_waitcnt vmcnt(1)
	v_pk_fma_f32 v[10:11], v[10:11], v[34:35], v[14:15] op_sel_hi:[1,0,1]
	v_pk_fma_f32 v[8:9], v[8:9], v[34:35], v[12:13] op_sel_hi:[1,0,1]
	s_waitcnt vmcnt(0)
	v_pk_fma_f32 v[12:13], v[6:7], v[34:35], v[18:19] op_sel_hi:[1,0,1]
	v_pk_fma_f32 v[14:15], v[4:5], v[34:35], v[16:17] op_sel_hi:[1,0,1]
	v_mul_f32_e32 v4, v9, v9
	v_mul_f32_e32 v5, v11, v11
	v_mul_f32_e32 v6, v15, v15
	v_mul_f32_e32 v7, v13, v13
	v_fmac_f32_e32 v4, v8, v8
	v_fmac_f32_e32 v5, v10, v10
	v_fmac_f32_e32 v6, v14, v14
	v_fmac_f32_e32 v7, v12, v12
	v_add_f32_e32 v4, v4, v5
	v_add_f32_e32 v5, v6, v7
	v_add_f32_e32 v4, v4, v5
	v_add_f32_e32 v3, v3, v4
	ds_bpermute_b32 v4, v153, v3
	v_cvt_pk_bf16_f32 v6, v8, v9
	v_cvt_pk_bf16_f32 v7, v10, v11
	v_cvt_pk_bf16_f32 v8, v14, v15
	v_cvt_pk_bf16_f32 v9, v12, v13
	s_waitcnt lgkmcnt(0)
	v_add_f32_e32 v3, v3, v4
	ds_bpermute_b32 v4, v154, v3
	global_store_dwordx4 v[30:31], v[6:9], off offset:256 sc1
	s_and_saveexec_b64 s[6:7], s[0:1]
	s_cbranch_execz .LBB0_729
	s_waitcnt lgkmcnt(0)
	v_add_f32_e32 v3, v3, v4
	v_lshlrev_b64 v[4:5], 6, v[20:21]
	v_lshl_add_u64 v[4:5], s[86:87], 0, v[4:5]
	v_lshl_add_u64 v[4:5], s[4:5], 2, v[4:5]
	v_lshl_add_u64 v[4:5], v[4:5], 0, s[10:11]
	global_store_dword v[4:5], v3, off

.LBB0_823:
	v_lshl_add_u32 v150, s36, 8, v3
	v_ashrrev_i32_e32 v151, 31, v150
	v_lshlrev_b64 v[152:153], 13, v[150:151]
	ds_read_b32 v151, v155
	v_max_f32_e32 v124, v124, v124
	v_max_f32_e32 v124, 0, v124
	v_max_f32_e32 v125, v125, v125
	v_max_f32_e32 v126, v126, v126
	s_waitcnt lgkmcnt(0)
	v_mul_f32_e32 v124, v124, v151
	v_max_f32_e32 v125, 0, v125
	v_max_f32_e32 v126, 0, v126
	v_mul_f32_e32 v161, v124, v124
	v_max_f32_e32 v124, v129, v129
	v_mul_f32_e32 v125, v125, v151
	v_mul_f32_e32 v126, v126, v151
	v_lshl_or_b32 v148, s66, 8, v157
	v_max_f32_e32 v128, v128, v128
	v_max_f32_e32 v124, 0, v124
	v_mul_f32_e32 v129, v125, v125
	v_max_f32_e32 v125, v130, v130
	v_mul_f32_e32 v130, v126, v126
	v_max_f32_e32 v126, v131, v131
	v_max_f32_e32 v127, v127, v127
	v_ashrrev_i32_e32 v149, 31, v148
	v_max_f32_e32 v128, 0, v128
	v_mul_f32_e32 v124, v124, v151
	v_max_f32_e32 v125, 0, v125
	v_max_f32_e32 v126, 0, v126
	v_max_f32_e32 v127, 0, v127
	v_max_f32_e32 v116, v116, v116
	v_max_f32_e32 v117, v117, v117
	v_max_f32_e32 v118, v118, v118
	v_lshl_add_u64 v[162:163], s[10:11], 0, v[152:153]
	v_lshlrev_b64 v[152:153], 1, v[148:149]
	v_mul_f32_e32 v128, v128, v151
	v_mul_f32_e32 v124, v124, v124
	v_mul_f32_e32 v125, v125, v151
	v_mul_f32_e32 v126, v126, v151
	v_mul_f32_e32 v127, v127, v151
	v_max_f32_e32 v116, 0, v116
	v_max_f32_e32 v117, 0, v117
	v_max_f32_e32 v118, 0, v118
	v_lshl_add_u64 v[148:149], v[162:163], 0, v[152:153]
	v_mul_f32_e32 v128, v128, v128
	v_mul_f32_e32 v125, v125, v125
	v_mul_f32_e32 v126, v126, v126
	v_mul_f32_e32 v127, v127, v127
	v_cvt_pk_bf16_f32 v124, v128, v124
	v_mul_f32_e32 v116, v116, v151
	v_mul_f32_e32 v117, v117, v151
	v_mul_f32_e32 v118, v118, v151
	v_cvt_pk_bf16_f32 v125, v125, v126
	v_cvt_pk_bf16_f32 v126, v161, v129
	v_cvt_pk_bf16_f32 v127, v130, v127
	global_store_dwordx4 v[148:149], v[124:127], off sc1
	v_max_f32_e32 v120, v120, v120
	v_max_f32_e32 v119, v119, v119
	v_mul_f32_e32 v124, v116, v116
	v_max_f32_e32 v116, v121, v121
	v_mul_f32_e32 v121, v117, v117
	v_max_f32_e32 v117, v122, v122
	v_mul_f32_e32 v122, v118, v118
	v_max_f32_e32 v118, v123, v123
	v_max_f32_e32 v116, 0, v116
	v_max_f32_e32 v117, 0, v117
	v_max_f32_e32 v118, 0, v118
	v_max_f32_e32 v120, 0, v120
	v_mul_f32_e32 v116, v116, v151
	v_mul_f32_e32 v117, v117, v151
	v_mul_f32_e32 v118, v118, v151
	v_max_f32_e32 v119, 0, v119
	v_mul_f32_e32 v120, v120, v151
	v_mul_f32_e32 v116, v116, v116
	v_mul_f32_e32 v117, v117, v117
	v_mul_f32_e32 v119, v119, v151
	v_mul_f32_e32 v118, v118, v118
	v_mul_f32_e32 v120, v120, v120
	v_mul_f32_e32 v119, v119, v119
	v_cvt_pk_bf16_f32 v116, v120, v116
	v_cvt_pk_bf16_f32 v117, v117, v118
	v_cvt_pk_bf16_f32 v118, v124, v121
	v_cvt_pk_bf16_f32 v119, v122, v119
	global_store_dwordx4 v[148:149], v[116:119], off offset:256 sc1
	ds_read_b32 v118, v155 offset:64
	v_max_f32_e32 v108, v108, v108
	v_max_f32_e32 v108, 0, v108
	v_max_f32_e32 v109, v109, v109
	v_max_f32_e32 v110, v110, v110
	s_waitcnt lgkmcnt(0)
	v_mul_f32_e32 v108, v108, v118
	v_max_f32_e32 v109, 0, v109
	v_max_f32_e32 v110, 0, v110
	v_or_b32_e32 v116, 16, v150
	v_mul_f32_e32 v119, v108, v108
	v_max_f32_e32 v108, v113, v113
	v_mul_f32_e32 v109, v109, v118
	v_mul_f32_e32 v110, v110, v118
	v_ashrrev_i32_e32 v117, 31, v116
	v_max_f32_e32 v112, v112, v112
	v_max_f32_e32 v108, 0, v108
	v_mul_f32_e32 v113, v109, v109
	v_max_f32_e32 v109, v114, v114
	v_mul_f32_e32 v114, v110, v110
	v_max_f32_e32 v110, v115, v115
	v_max_f32_e32 v111, v111, v111
	v_lshlrev_b64 v[116:117], 13, v[116:117]
	v_max_f32_e32 v112, 0, v112
	v_mul_f32_e32 v108, v108, v118
	v_max_f32_e32 v109, 0, v109
	v_max_f32_e32 v110, 0, v110
	v_max_f32_e32 v111, 0, v111
	v_max_f32_e32 v100, v100, v100
	v_max_f32_e32 v101, v101, v101
	v_max_f32_e32 v102, v102, v102
	v_lshl_add_u64 v[116:117], s[10:11], 0, v[116:117]
	v_mul_f32_e32 v112, v112, v118
	v_mul_f32_e32 v108, v108, v108
	v_mul_f32_e32 v109, v109, v118
	v_mul_f32_e32 v110, v110, v118
	v_mul_f32_e32 v111, v111, v118
	v_max_f32_e32 v100, 0, v100
	v_max_f32_e32 v101, 0, v101
	v_max_f32_e32 v102, 0, v102
	v_lshl_add_u64 v[116:117], v[116:117], 0, v[152:153]
	v_mul_f32_e32 v112, v112, v112
	v_mul_f32_e32 v109, v109, v109
	v_mul_f32_e32 v110, v110, v110
	v_mul_f32_e32 v111, v111, v111
	v_cvt_pk_bf16_f32 v108, v112, v108
	v_mul_f32_e32 v100, v100, v118
	v_mul_f32_e32 v101, v101, v118
	v_mul_f32_e32 v102, v102, v118
	v_cvt_pk_bf16_f32 v109, v109, v110
	v_cvt_pk_bf16_f32 v110, v119, v113
	v_cvt_pk_bf16_f32 v111, v114, v111
	global_store_dwordx4 v[116:117], v[108:111], off sc1
	v_max_f32_e32 v104, v104, v104
	v_max_f32_e32 v103, v103, v103
	v_mul_f32_e32 v108, v100, v100
	v_max_f32_e32 v100, v105, v105
	v_mul_f32_e32 v105, v101, v101
	v_max_f32_e32 v101, v106, v106
	v_mul_f32_e32 v106, v102, v102
	v_max_f32_e32 v102, v107, v107
	v_max_f32_e32 v100, 0, v100
	v_max_f32_e32 v101, 0, v101
	v_max_f32_e32 v102, 0, v102
	v_max_f32_e32 v104, 0, v104
	v_mul_f32_e32 v100, v100, v118
	v_mul_f32_e32 v101, v101, v118
	v_mul_f32_e32 v102, v102, v118
	v_max_f32_e32 v103, 0, v103
	v_mul_f32_e32 v104, v104, v118
	v_mul_f32_e32 v100, v100, v100
	v_mul_f32_e32 v101, v101, v101
	v_mul_f32_e32 v103, v103, v118
	v_mul_f32_e32 v102, v102, v102
	v_mul_f32_e32 v104, v104, v104
	v_mul_f32_e32 v103, v103, v103
	v_cvt_pk_bf16_f32 v100, v104, v100
	v_cvt_pk_bf16_f32 v101, v101, v102
	v_cvt_pk_bf16_f32 v102, v108, v105
	v_cvt_pk_bf16_f32 v103, v106, v103
	global_store_dwordx4 v[116:117], v[100:103], off offset:256 sc1
	ds_read_b32 v102, v155 offset:128
	v_max_f32_e32 v92, v92, v92
	v_max_f32_e32 v92, 0, v92
	v_max_f32_e32 v93, v93, v93
	v_max_f32_e32 v94, v94, v94
	s_waitcnt lgkmcnt(0)
	v_mul_f32_e32 v92, v92, v102
	v_max_f32_e32 v93, 0, v93
	v_max_f32_e32 v94, 0, v94
	v_or_b32_e32 v100, 32, v150
	v_mul_f32_e32 v103, v92, v92
	v_max_f32_e32 v92, v97, v97
	v_mul_f32_e32 v93, v93, v102
	v_mul_f32_e32 v94, v94, v102
	v_ashrrev_i32_e32 v101, 31, v100
	v_max_f32_e32 v96, v96, v96
	v_max_f32_e32 v92, 0, v92
	v_mul_f32_e32 v97, v93, v93
	v_max_f32_e32 v93, v98, v98
	v_mul_f32_e32 v98, v94, v94
	v_max_f32_e32 v94, v99, v99
	v_max_f32_e32 v95, v95, v95
	v_lshlrev_b64 v[100:101], 13, v[100:101]
	v_max_f32_e32 v96, 0, v96
	v_mul_f32_e32 v92, v92, v102
	v_max_f32_e32 v93, 0, v93
	v_max_f32_e32 v94, 0, v94
	v_max_f32_e32 v95, 0, v95
	v_max_f32_e32 v84, v84, v84
	v_max_f32_e32 v85, v85, v85
	v_max_f32_e32 v86, v86, v86
	v_lshl_add_u64 v[100:101], s[10:11], 0, v[100:101]
	v_mul_f32_e32 v96, v96, v102
	v_mul_f32_e32 v92, v92, v92
	v_mul_f32_e32 v93, v93, v102
	v_mul_f32_e32 v94, v94, v102
	v_mul_f32_e32 v95, v95, v102
	v_max_f32_e32 v84, 0, v84
	v_max_f32_e32 v85, 0, v85
	v_max_f32_e32 v86, 0, v86
	v_lshl_add_u64 v[100:101], v[100:101], 0, v[152:153]
	v_mul_f32_e32 v96, v96, v96
	v_mul_f32_e32 v93, v93, v93
	v_mul_f32_e32 v94, v94, v94
	v_mul_f32_e32 v95, v95, v95
	v_cvt_pk_bf16_f32 v92, v96, v92
	v_mul_f32_e32 v84, v84, v102
	v_mul_f32_e32 v85, v85, v102
	v_mul_f32_e32 v86, v86, v102
	v_cvt_pk_bf16_f32 v93, v93, v94
	v_cvt_pk_bf16_f32 v94, v103, v97
	v_cvt_pk_bf16_f32 v95, v98, v95
	global_store_dwordx4 v[100:101], v[92:95], off sc1
	v_max_f32_e32 v88, v88, v88
	v_max_f32_e32 v87, v87, v87
	v_mul_f32_e32 v92, v84, v84
	v_max_f32_e32 v84, v89, v89
	v_mul_f32_e32 v89, v85, v85
	v_max_f32_e32 v85, v90, v90
	v_mul_f32_e32 v90, v86, v86
	v_max_f32_e32 v86, v91, v91
	v_max_f32_e32 v84, 0, v84
	v_max_f32_e32 v85, 0, v85
	v_max_f32_e32 v86, 0, v86
	v_max_f32_e32 v88, 0, v88
	v_mul_f32_e32 v84, v84, v102
	v_mul_f32_e32 v85, v85, v102
	v_mul_f32_e32 v86, v86, v102
	v_max_f32_e32 v87, 0, v87
	v_mul_f32_e32 v88, v88, v102
	v_mul_f32_e32 v84, v84, v84
	v_mul_f32_e32 v85, v85, v85
	v_mul_f32_e32 v87, v87, v102
	v_mul_f32_e32 v86, v86, v86
	v_mul_f32_e32 v88, v88, v88
	v_mul_f32_e32 v87, v87, v87
	v_cvt_pk_bf16_f32 v84, v88, v84
	v_cvt_pk_bf16_f32 v85, v85, v86
	v_cvt_pk_bf16_f32 v86, v92, v89
	v_cvt_pk_bf16_f32 v87, v90, v87
	global_store_dwordx4 v[100:101], v[84:87], off offset:256 sc1
	ds_read_b32 v86, v155 offset:192
	v_max_f32_e32 v76, v76, v76
	v_max_f32_e32 v76, 0, v76
	v_max_f32_e32 v77, v77, v77
	v_max_f32_e32 v78, v78, v78
	s_waitcnt lgkmcnt(0)
	v_mul_f32_e32 v76, v76, v86
	v_max_f32_e32 v77, 0, v77
	v_max_f32_e32 v78, 0, v78
	v_or_b32_e32 v84, 48, v150
	v_mul_f32_e32 v87, v76, v76
	v_max_f32_e32 v76, v81, v81
	v_mul_f32_e32 v77, v77, v86
	v_mul_f32_e32 v78, v78, v86
	v_ashrrev_i32_e32 v85, 31, v84
	v_max_f32_e32 v80, v80, v80
	v_max_f32_e32 v76, 0, v76
	v_mul_f32_e32 v81, v77, v77
	v_max_f32_e32 v77, v82, v82
	v_mul_f32_e32 v82, v78, v78
	v_max_f32_e32 v78, v83, v83
	v_max_f32_e32 v79, v79, v79
	v_lshlrev_b64 v[84:85], 13, v[84:85]
	v_max_f32_e32 v80, 0, v80
	v_mul_f32_e32 v76, v76, v86
	v_max_f32_e32 v77, 0, v77
	v_max_f32_e32 v78, 0, v78
	v_max_f32_e32 v79, 0, v79
	v_max_f32_e32 v68, v68, v68
	v_max_f32_e32 v69, v69, v69
	v_max_f32_e32 v70, v70, v70
	v_lshl_add_u64 v[84:85], s[10:11], 0, v[84:85]
	v_mul_f32_e32 v80, v80, v86
	v_mul_f32_e32 v76, v76, v76
	v_mul_f32_e32 v77, v77, v86
	v_mul_f32_e32 v78, v78, v86
	v_mul_f32_e32 v79, v79, v86
	v_max_f32_e32 v68, 0, v68
	v_max_f32_e32 v69, 0, v69
	v_max_f32_e32 v70, 0, v70
	v_lshl_add_u64 v[84:85], v[84:85], 0, v[152:153]
	v_mul_f32_e32 v80, v80, v80
	v_mul_f32_e32 v77, v77, v77
	v_mul_f32_e32 v78, v78, v78
	v_mul_f32_e32 v79, v79, v79
	v_cvt_pk_bf16_f32 v76, v80, v76
	v_mul_f32_e32 v68, v68, v86
	v_mul_f32_e32 v69, v69, v86
	v_mul_f32_e32 v70, v70, v86
	v_cvt_pk_bf16_f32 v77, v77, v78
	v_cvt_pk_bf16_f32 v78, v87, v81
	v_cvt_pk_bf16_f32 v79, v82, v79
	global_store_dwordx4 v[84:85], v[76:79], off sc1
	v_max_f32_e32 v72, v72, v72
	v_max_f32_e32 v71, v71, v71
	v_mul_f32_e32 v76, v68, v68
	v_max_f32_e32 v68, v73, v73
	v_mul_f32_e32 v73, v69, v69
	v_max_f32_e32 v69, v74, v74
	v_mul_f32_e32 v74, v70, v70
	v_max_f32_e32 v70, v75, v75
	v_max_f32_e32 v72, 0, v72
	v_max_f32_e32 v68, 0, v68
	v_max_f32_e32 v69, 0, v69
	v_max_f32_e32 v70, 0, v70
	v_max_f32_e32 v71, 0, v71
	v_mul_f32_e32 v72, v72, v86
	v_mul_f32_e32 v68, v68, v86
	v_mul_f32_e32 v69, v69, v86
	v_mul_f32_e32 v70, v70, v86
	v_mul_f32_e32 v71, v71, v86
	v_mul_f32_e32 v72, v72, v72
	v_mul_f32_e32 v68, v68, v68
	v_mul_f32_e32 v69, v69, v69
	v_mul_f32_e32 v70, v70, v70
	v_mul_f32_e32 v71, v71, v71
	v_cvt_pk_bf16_f32 v68, v72, v68
	v_cvt_pk_bf16_f32 v69, v69, v70
	v_cvt_pk_bf16_f32 v70, v76, v73
	v_cvt_pk_bf16_f32 v71, v74, v71
	ds_read_b32 v72, v156
	v_max_f32_e32 v60, v60, v60
	v_max_f32_e32 v60, 0, v60
	v_max_f32_e32 v61, v61, v61
	v_max_f32_e32 v62, v62, v62
	s_waitcnt lgkmcnt(0)
	v_mul_f32_e32 v60, v60, v72
	v_max_f32_e32 v61, 0, v61
	v_max_f32_e32 v62, 0, v62
	global_store_dwordx4 v[84:85], v[68:71], off offset:256 sc1
	v_max_f32_e32 v64, v64, v64
	v_mul_f32_e32 v61, v61, v72
	v_mul_f32_e32 v70, v60, v60
	v_max_f32_e32 v60, v65, v65
	v_mul_f32_e32 v62, v62, v72
	v_max_f32_e32 v64, 0, v64
	v_max_f32_e32 v60, 0, v60
	v_mul_f32_e32 v65, v61, v61
	v_max_f32_e32 v61, v66, v66
	v_mul_f32_e32 v66, v62, v62
	v_max_f32_e32 v62, v67, v67
	v_mul_f32_e32 v64, v64, v72
	v_mul_f32_e32 v60, v60, v72
	v_max_f32_e32 v61, 0, v61
	v_max_f32_e32 v62, 0, v62
	v_max_f32_e32 v63, v63, v63
	v_mul_f32_e32 v64, v64, v64
	v_mul_f32_e32 v60, v60, v60
	v_mul_f32_e32 v61, v61, v72
	v_mul_f32_e32 v62, v62, v72
	v_max_f32_e32 v63, 0, v63
	v_max_f32_e32 v52, v52, v52
	v_max_f32_e32 v53, v53, v53
	v_max_f32_e32 v54, v54, v54
	v_mul_f32_e32 v61, v61, v61
	v_mul_f32_e32 v63, v63, v72
	v_mul_f32_e32 v62, v62, v62
	v_cvt_pk_bf16_f32 v60, v64, v60
	v_add_co_u32_e32 v64, vcc, s60, v148
	v_max_f32_e32 v52, 0, v52
	v_max_f32_e32 v53, 0, v53
	v_max_f32_e32 v54, 0, v54
	v_mul_f32_e32 v63, v63, v63
	v_cvt_pk_bf16_f32 v61, v61, v62
	v_cvt_pk_bf16_f32 v62, v70, v65
	v_addc_co_u32_e32 v65, vcc, 0, v149, vcc
	v_mul_f32_e32 v52, v52, v72
	v_mul_f32_e32 v53, v53, v72
	v_mul_f32_e32 v54, v54, v72
	v_cvt_pk_bf16_f32 v63, v66, v63
	global_store_dwordx4 v[64:65], v[60:63], off sc1
	v_max_f32_e32 v56, v56, v56
	v_max_f32_e32 v55, v55, v55
	v_mul_f32_e32 v60, v52, v52
	v_max_f32_e32 v52, v57, v57
	v_mul_f32_e32 v57, v53, v53
	v_max_f32_e32 v53, v58, v58
	v_mul_f32_e32 v58, v54, v54
	v_max_f32_e32 v54, v59, v59
	v_max_f32_e32 v56, 0, v56
	v_max_f32_e32 v52, 0, v52
	v_max_f32_e32 v53, 0, v53
	v_max_f32_e32 v54, 0, v54
	v_max_f32_e32 v55, 0, v55
	v_mul_f32_e32 v56, v56, v72
	v_mul_f32_e32 v52, v52, v72
	v_mul_f32_e32 v53, v53, v72
	v_mul_f32_e32 v54, v54, v72
	v_mul_f32_e32 v55, v55, v72
	v_mul_f32_e32 v56, v56, v56
	v_mul_f32_e32 v52, v52, v52
	v_mul_f32_e32 v53, v53, v53
	v_mul_f32_e32 v54, v54, v54
	v_mul_f32_e32 v55, v55, v55
	v_cvt_pk_bf16_f32 v52, v56, v52
	v_cvt_pk_bf16_f32 v53, v53, v54
	v_cvt_pk_bf16_f32 v54, v60, v57
	v_cvt_pk_bf16_f32 v55, v58, v55
	ds_read_b32 v56, v155 offset:576
	v_max_f32_e32 v44, v44, v44
	v_max_f32_e32 v44, 0, v44
	v_max_f32_e32 v45, v45, v45
	v_max_f32_e32 v46, v46, v46
	v_lshl_add_u64 v[68:69], v[148:149], 0, s[18:19]
	s_waitcnt lgkmcnt(0)
	v_mul_f32_e32 v44, v44, v56
	v_max_f32_e32 v45, 0, v45
	v_max_f32_e32 v46, 0, v46
	global_store_dwordx4 v[68:69], v[52:55], off offset:256 sc1
	v_max_f32_e32 v48, v48, v48
	v_mul_f32_e32 v45, v45, v56
	v_mul_f32_e32 v54, v44, v44
	v_max_f32_e32 v44, v49, v49
	v_mul_f32_e32 v46, v46, v56
	v_max_f32_e32 v48, 0, v48
	v_max_f32_e32 v44, 0, v44
	v_mul_f32_e32 v49, v45, v45
	v_max_f32_e32 v45, v50, v50
	v_mul_f32_e32 v50, v46, v46
	v_max_f32_e32 v46, v51, v51
	v_mul_f32_e32 v48, v48, v56
	v_mul_f32_e32 v44, v44, v56
	v_max_f32_e32 v45, 0, v45
	v_max_f32_e32 v46, 0, v46
	v_max_f32_e32 v47, v47, v47
	v_mul_f32_e32 v48, v48, v48
	v_mul_f32_e32 v44, v44, v44
	v_mul_f32_e32 v45, v45, v56
	v_mul_f32_e32 v46, v46, v56
	v_max_f32_e32 v47, 0, v47
	v_max_f32_e32 v36, v36, v36
	v_max_f32_e32 v37, v37, v37
	v_max_f32_e32 v38, v38, v38
	v_mul_f32_e32 v45, v45, v45
	v_mul_f32_e32 v47, v47, v56
	v_mul_f32_e32 v46, v46, v46
	v_cvt_pk_bf16_f32 v44, v48, v44
	v_add_co_u32_e32 v48, vcc, s61, v148
	v_max_f32_e32 v36, 0, v36
	v_max_f32_e32 v37, 0, v37
	v_max_f32_e32 v38, 0, v38
	v_mul_f32_e32 v47, v47, v47
	v_cvt_pk_bf16_f32 v45, v45, v46
	v_cvt_pk_bf16_f32 v46, v54, v49
	v_addc_co_u32_e32 v49, vcc, 0, v149, vcc
	v_mul_f32_e32 v36, v36, v56
	v_mul_f32_e32 v37, v37, v56
	v_mul_f32_e32 v38, v38, v56
	v_cvt_pk_bf16_f32 v47, v50, v47
	global_store_dwordx4 v[48:49], v[44:47], off sc1
	v_max_f32_e32 v40, v40, v40
	v_max_f32_e32 v39, v39, v39
	v_mul_f32_e32 v44, v36, v36
	v_max_f32_e32 v36, v41, v41
	v_mul_f32_e32 v41, v37, v37
	v_max_f32_e32 v37, v42, v42
	v_mul_f32_e32 v42, v38, v38
	v_max_f32_e32 v38, v43, v43
	v_max_f32_e32 v40, 0, v40
	v_max_f32_e32 v36, 0, v36
	v_max_f32_e32 v37, 0, v37
	v_max_f32_e32 v38, 0, v38
	v_max_f32_e32 v39, 0, v39
	v_mul_f32_e32 v40, v40, v56
	v_mul_f32_e32 v36, v36, v56
	v_mul_f32_e32 v37, v37, v56
	v_mul_f32_e32 v38, v38, v56
	v_mul_f32_e32 v39, v39, v56
	v_mul_f32_e32 v40, v40, v40
	v_mul_f32_e32 v36, v36, v36
	v_mul_f32_e32 v37, v37, v37
	v_mul_f32_e32 v38, v38, v38
	v_mul_f32_e32 v39, v39, v39
	v_cvt_pk_bf16_f32 v36, v40, v36
	v_cvt_pk_bf16_f32 v37, v37, v38
	v_cvt_pk_bf16_f32 v38, v44, v41
	v_cvt_pk_bf16_f32 v39, v42, v39
	ds_read_b32 v40, v155 offset:640
	v_max_f32_e32 v28, v28, v28
	v_max_f32_e32 v28, 0, v28
	v_max_f32_e32 v29, v29, v29
	v_max_f32_e32 v30, v30, v30
	v_lshl_add_u64 v[52:53], v[148:149], 0, s[20:21]
	s_waitcnt lgkmcnt(0)
	v_mul_f32_e32 v28, v28, v40
	v_max_f32_e32 v29, 0, v29
	v_max_f32_e32 v30, 0, v30
	global_store_dwordx4 v[52:53], v[36:39], off offset:256 sc1
	v_max_f32_e32 v32, v32, v32
	v_mul_f32_e32 v29, v29, v40
	v_mul_f32_e32 v38, v28, v28
	v_max_f32_e32 v28, v33, v33
	v_mul_f32_e32 v30, v30, v40
	v_max_f32_e32 v32, 0, v32
	v_max_f32_e32 v28, 0, v28
	v_mul_f32_e32 v33, v29, v29
	v_max_f32_e32 v29, v34, v34
	v_mul_f32_e32 v34, v30, v30
	v_max_f32_e32 v30, v35, v35
	v_mul_f32_e32 v32, v32, v40
	v_mul_f32_e32 v28, v28, v40
	v_max_f32_e32 v29, 0, v29
	v_max_f32_e32 v30, 0, v30
	v_max_f32_e32 v31, v31, v31
	v_mul_f32_e32 v32, v32, v32
	v_mul_f32_e32 v28, v28, v28
	v_mul_f32_e32 v29, v29, v40
	v_mul_f32_e32 v30, v30, v40
	v_max_f32_e32 v31, 0, v31
	v_max_f32_e32 v20, v20, v20
	v_max_f32_e32 v21, v21, v21
	v_max_f32_e32 v22, v22, v22
	v_mul_f32_e32 v29, v29, v29
	v_mul_f32_e32 v31, v31, v40
	v_mul_f32_e32 v30, v30, v30
	v_cvt_pk_bf16_f32 v28, v32, v28
	v_add_co_u32_e32 v32, vcc, s64, v148
	v_max_f32_e32 v20, 0, v20
	v_max_f32_e32 v21, 0, v21
	v_max_f32_e32 v22, 0, v22
	v_mul_f32_e32 v31, v31, v31
	v_cvt_pk_bf16_f32 v29, v29, v30
	v_cvt_pk_bf16_f32 v30, v38, v33
	v_addc_co_u32_e32 v33, vcc, 0, v149, vcc
	v_mul_f32_e32 v20, v20, v40
	v_mul_f32_e32 v21, v21, v40
	v_mul_f32_e32 v22, v22, v40
	v_cvt_pk_bf16_f32 v31, v34, v31
	global_store_dwordx4 v[32:33], v[28:31], off sc1
	v_max_f32_e32 v24, v24, v24
	v_max_f32_e32 v23, v23, v23
	v_mul_f32_e32 v28, v20, v20
	v_max_f32_e32 v20, v25, v25
	v_mul_f32_e32 v25, v21, v21
	v_max_f32_e32 v21, v26, v26
	v_mul_f32_e32 v26, v22, v22
	v_max_f32_e32 v22, v27, v27
	v_max_f32_e32 v24, 0, v24
	v_max_f32_e32 v20, 0, v20
	v_max_f32_e32 v21, 0, v21
	v_max_f32_e32 v22, 0, v22
	v_max_f32_e32 v23, 0, v23
	v_mul_f32_e32 v24, v24, v40
	v_mul_f32_e32 v20, v20, v40
	v_mul_f32_e32 v21, v21, v40
	v_mul_f32_e32 v22, v22, v40
	v_mul_f32_e32 v23, v23, v40
	v_mul_f32_e32 v24, v24, v24
	v_mul_f32_e32 v20, v20, v20
	v_mul_f32_e32 v21, v21, v21
	v_mul_f32_e32 v22, v22, v22
	v_mul_f32_e32 v23, v23, v23
	v_cvt_pk_bf16_f32 v20, v24, v20
	v_cvt_pk_bf16_f32 v21, v21, v22
	v_cvt_pk_bf16_f32 v22, v28, v25
	v_cvt_pk_bf16_f32 v23, v26, v23
	ds_read_b32 v24, v155 offset:704
	v_max_f32_e32 v12, v12, v12
	v_max_f32_e32 v12, 0, v12
	v_max_f32_e32 v13, v13, v13
	v_max_f32_e32 v14, v14, v14
	v_lshl_add_u64 v[36:37], v[148:149], 0, s[22:23]
	s_waitcnt lgkmcnt(0)
	v_mul_f32_e32 v12, v12, v24
	v_max_f32_e32 v13, 0, v13
	v_max_f32_e32 v14, 0, v14
	global_store_dwordx4 v[36:37], v[20:23], off offset:256 sc1
	v_max_f32_e32 v16, v16, v16
	v_mul_f32_e32 v13, v13, v24
	v_mul_f32_e32 v22, v12, v12
	v_max_f32_e32 v12, v17, v17
	v_mul_f32_e32 v14, v14, v24
	v_max_f32_e32 v16, 0, v16
	v_max_f32_e32 v12, 0, v12
	v_mul_f32_e32 v17, v13, v13
	v_max_f32_e32 v13, v18, v18
	v_mul_f32_e32 v18, v14, v14
	v_max_f32_e32 v14, v19, v19
	v_mul_f32_e32 v16, v16, v24
	v_mul_f32_e32 v12, v12, v24
	v_max_f32_e32 v13, 0, v13
	v_max_f32_e32 v14, 0, v14
	v_max_f32_e32 v15, v15, v15
	v_mul_f32_e32 v16, v16, v16
	v_mul_f32_e32 v12, v12, v12
	v_mul_f32_e32 v13, v13, v24
	v_mul_f32_e32 v14, v14, v24
	v_max_f32_e32 v15, 0, v15
	v_max_f32_e32 v4, v4, v4
	v_max_f32_e32 v5, v5, v5
	v_max_f32_e32 v6, v6, v6
	v_mul_f32_e32 v13, v13, v13
	v_mul_f32_e32 v15, v15, v24
	v_mul_f32_e32 v14, v14, v14
	v_cvt_pk_bf16_f32 v12, v16, v12
	v_add_co_u32_e32 v16, vcc, s65, v148
	v_max_f32_e32 v4, 0, v4
	v_max_f32_e32 v5, 0, v5
	v_max_f32_e32 v6, 0, v6
	v_mul_f32_e32 v15, v15, v15
	v_cvt_pk_bf16_f32 v13, v13, v14
	v_cvt_pk_bf16_f32 v14, v22, v17
	v_addc_co_u32_e32 v17, vcc, 0, v149, vcc
	v_mul_f32_e32 v4, v4, v24
	v_mul_f32_e32 v5, v5, v24
	v_mul_f32_e32 v6, v6, v24
	v_cvt_pk_bf16_f32 v15, v18, v15
	global_store_dwordx4 v[16:17], v[12:15], off sc1
	v_max_f32_e32 v7, v7, v7
	v_max_f32_e32 v8, v8, v8
	v_mul_f32_e32 v12, v4, v4
	v_max_f32_e32 v4, v9, v9
	v_mul_f32_e32 v9, v5, v5
	v_max_f32_e32 v5, v10, v10
	v_mul_f32_e32 v10, v6, v6
	v_max_f32_e32 v6, v11, v11
	v_max_f32_e32 v4, 0, v4
	v_max_f32_e32 v5, 0, v5
	v_max_f32_e32 v6, 0, v6
	v_max_f32_e32 v7, 0, v7
	v_max_f32_e32 v8, 0, v8
	v_mul_f32_e32 v4, v4, v24
	v_mul_f32_e32 v5, v5, v24
	v_mul_f32_e32 v6, v6, v24
	v_mul_f32_e32 v7, v7, v24
	v_lshl_add_u64 v[20:21], v[148:149], 0, s[24:25]
	v_mul_f32_e32 v8, v8, v24
	v_mul_f32_e32 v4, v4, v4
	v_mul_f32_e32 v5, v5, v5
	v_mul_f32_e32 v6, v6, v6
	v_mul_f32_e32 v7, v7, v7
	s_andn2_b64 vcc, exec, s[0:1]
	s_mov_b64 s[0:1], -1
	v_mul_f32_e32 v8, v8, v8
	v_cvt_pk_bf16_f32 v4, v8, v4
	v_cvt_pk_bf16_f32 v5, v5, v6
	v_cvt_pk_bf16_f32 v6, v12, v9
	v_cvt_pk_bf16_f32 v7, v10, v7
	global_store_dwordx4 v[20:21], v[4:7], off offset:256 sc1
	s_cbranch_vccnz .LBB0_812
	s_andn2_b64 vcc, exec, s[8:9]
	s_cbranch_vccnz .LBB0_811
	s_barrier
	s_branch .LBB0_811

.LBB0_970:
	s_or_b64 exec, exec, s[16:17]
	s_waitcnt vmcnt(0) lgkmcnt(0)
	s_barrier
	v_lshl_add_u64 v[164:165], v[218:219], 2, s[56:57]
	global_load_dwordx4 v[180:183], v[164:165], off
	global_load_dwordx4 v[176:179], v[164:165], off offset:16
	global_load_dwordx4 v[168:171], v[164:165], off offset:512
	s_nop 0
	global_load_dwordx4 v[164:167], v[164:165], off offset:528
	v_lshl_add_u32 v227, v215, 2, 0
	ds_read_b32 v236, v227 offset:4096
	s_waitcnt vmcnt(0)
	v_lshlrev_b32_e32 v228, 16, v208
	v_and_b32_e32 v229, 0xffff0000, v208
	v_lshlrev_b32_e32 v208, 16, v209
	v_and_b32_e32 v209, 0xffff0000, v209
	v_lshlrev_b32_e32 v230, 16, v210
	v_and_b32_e32 v231, 0xffff0000, v210
	v_lshlrev_b32_e32 v210, 16, v211
	v_and_b32_e32 v211, 0xffff0000, v211
	v_lshlrev_b32_e32 v232, 16, v204
	v_and_b32_e32 v233, 0xffff0000, v204
	v_lshlrev_b32_e32 v204, 16, v205
	v_and_b32_e32 v205, 0xffff0000, v205
	v_lshlrev_b32_e32 v234, 16, v206
	v_and_b32_e32 v235, 0xffff0000, v206
	v_lshlrev_b32_e32 v206, 16, v207
	v_and_b32_e32 v207, 0xffff0000, v207
	v_add_u32_e32 v220, s20, v215
	v_ashrrev_i32_e32 v221, 31, v220
	v_lshlrev_b64 v[238:239], 11, v[220:221]
	s_lshl_b32 s4, s12, 2
	s_mov_b32 s7, 0
	s_ashr_i32 s5, s4, 31
	v_pk_mul_f32 v[150:151], v[150:151], v[182:183]
	v_pk_mul_f32 v[148:149], v[148:149], v[180:181]
	v_pk_mul_f32 v[146:147], v[146:147], v[178:179]
	v_pk_mul_f32 v[144:145], v[144:145], v[176:177]
	v_pk_mul_f32 v[142:143], v[142:143], v[170:171]
	v_pk_mul_f32 v[140:141], v[140:141], v[168:169]
	v_pk_mul_f32 v[138:139], v[138:139], v[166:167]
	v_pk_mul_f32 v[136:137], v[136:137], v[164:165]
	s_waitcnt lgkmcnt(0)
	v_pk_fma_f32 v[148:149], v[148:149], v[236:237], v[228:229] op_sel_hi:[1,0,1]
	v_pk_fma_f32 v[150:151], v[150:151], v[236:237], v[208:209] op_sel_hi:[1,0,1]
	v_pk_fma_f32 v[144:145], v[144:145], v[236:237], v[230:231] op_sel_hi:[1,0,1]
	v_pk_fma_f32 v[146:147], v[146:147], v[236:237], v[210:211] op_sel_hi:[1,0,1]
	v_pk_fma_f32 v[140:141], v[140:141], v[236:237], v[232:233] op_sel_hi:[1,0,1]
	v_pk_fma_f32 v[142:143], v[142:143], v[236:237], v[204:205] op_sel_hi:[1,0,1]
	v_pk_fma_f32 v[204:205], v[136:137], v[236:237], v[234:235] op_sel_hi:[1,0,1]
	v_pk_fma_f32 v[206:207], v[138:139], v[236:237], v[206:207] op_sel_hi:[1,0,1]
	v_mul_f32_e32 v208, v149, v149
	v_mul_f32_e32 v209, v151, v151
	v_mul_f32_e32 v210, v145, v145
	v_mul_f32_e32 v211, v147, v147
	v_cvt_pk_bf16_f32 v136, v148, v149
	v_cvt_pk_bf16_f32 v137, v150, v151
	v_cvt_pk_bf16_f32 v138, v144, v145
	v_cvt_pk_bf16_f32 v139, v146, v147
	v_mul_f32_e32 v145, v141, v141
	v_mul_f32_e32 v147, v143, v143
	v_mul_f32_e32 v149, v205, v205
	v_mul_f32_e32 v151, v207, v207
	v_fmac_f32_e32 v208, v148, v148
	v_fmac_f32_e32 v209, v150, v150
	v_fmac_f32_e32 v210, v144, v144
	v_fmac_f32_e32 v211, v146, v146
	v_fmac_f32_e32 v145, v140, v140
	v_fmac_f32_e32 v147, v142, v142
	v_fmac_f32_e32 v149, v204, v204
	v_fmac_f32_e32 v151, v206, v206
	v_add_f32_e32 v144, v208, v209
	v_add_f32_e32 v146, v210, v211
	v_add_f32_e32 v145, v145, v147
	v_add_f32_e32 v147, v149, v151
	v_add_f32_e32 v144, v144, v146
	v_add_f32_e32 v145, v145, v147
	v_add_f32_e32 v146, v144, v145
	ds_bpermute_b32 v147, v3, v146
	v_lshl_add_u64 v[144:145], s[62:63], 0, v[238:239]
	v_lshl_add_u64 v[144:145], v[218:219], 1, v[144:145]
	global_store_dwordx4 v[144:145], v[136:139], off sc1
	s_waitcnt lgkmcnt(0)
	s_nop 0
	v_add_f32_e32 v136, v146, v147
	ds_bpermute_b32 v137, v226, v136
	v_cvt_pk_bf16_f32 v138, v140, v141
	v_cvt_pk_bf16_f32 v139, v142, v143
	v_cvt_pk_bf16_f32 v140, v204, v205
	v_cvt_pk_bf16_f32 v141, v206, v207
	global_store_dwordx4 v[144:145], v[138:141], off offset:256 sc1
	s_and_saveexec_b64 s[10:11], s[0:1]
	s_cbranch_execz .LBB0_972
	s_waitcnt lgkmcnt(0)
	v_add_f32_e32 v138, v136, v137
	v_lshlrev_b64 v[136:137], 6, v[220:221]
	v_lshl_add_u64 v[136:137], s[86:87], 0, v[136:137]
	v_lshl_add_u64 v[136:137], s[4:5], 2, v[136:137]
	v_lshl_add_u64 v[136:137], v[136:137], 0, s[6:7]
	global_store_dword v[136:137], v138, off
.LBB0_972:
	s_or_b64 exec, exec, s[10:11]
	ds_read_b32 v138, v227 offset:4160
	v_lshlrev_b32_e32 v142, 16, v200
	v_and_b32_e32 v143, 0xffff0000, v200
	v_lshlrev_b32_e32 v144, 16, v201
	v_and_b32_e32 v145, 0xffff0000, v201
	v_pk_mul_f32 v[130:131], v[130:131], v[182:183]
	v_pk_mul_f32 v[128:129], v[128:129], v[180:181]
	v_lshlrev_b32_e32 v146, 16, v202
	v_and_b32_e32 v147, 0xffff0000, v202
	v_lshlrev_b32_e32 v148, 16, v203
	v_and_b32_e32 v149, 0xffff0000, v203
	s_waitcnt lgkmcnt(0)
	v_pk_fma_f32 v[130:131], v[130:131], v[138:139], v[144:145] op_sel_hi:[1,0,1]
	v_pk_fma_f32 v[128:129], v[128:129], v[138:139], v[142:143] op_sel_hi:[1,0,1]
	v_pk_mul_f32 v[126:127], v[126:127], v[178:179]
	v_pk_mul_f32 v[124:125], v[124:125], v[176:177]
	v_pk_fma_f32 v[142:143], v[126:127], v[138:139], v[148:149] op_sel_hi:[1,0,1]
	v_pk_fma_f32 v[126:127], v[124:125], v[138:139], v[146:147] op_sel_hi:[1,0,1]
	v_mul_f32_e32 v124, v129, v129
	v_mul_f32_e32 v125, v131, v131
	v_fmac_f32_e32 v124, v128, v128
	v_fmac_f32_e32 v125, v130, v130
	v_add_f32_e32 v124, v124, v125
	v_mul_f32_e32 v125, v127, v127
	v_mul_f32_e32 v139, v143, v143
	v_fmac_f32_e32 v125, v126, v126
	v_fmac_f32_e32 v139, v142, v142
	v_add_f32_e32 v125, v125, v139
	v_add_f32_e32 v139, v124, v125
	v_cvt_pk_bf16_f32 v124, v128, v129
	v_cvt_pk_bf16_f32 v125, v130, v131
	v_lshlrev_b32_e32 v128, 16, v196
	v_and_b32_e32 v129, 0xffff0000, v196
	v_lshlrev_b32_e32 v130, 16, v197
	v_and_b32_e32 v131, 0xffff0000, v197
	v_pk_mul_f32 v[118:119], v[118:119], v[170:171]
	v_pk_mul_f32 v[116:117], v[116:117], v[168:169]
	v_cvt_pk_bf16_f32 v126, v126, v127
	v_cvt_pk_bf16_f32 v127, v142, v143
	v_lshlrev_b32_e32 v142, 16, v198
	v_and_b32_e32 v143, 0xffff0000, v198
	v_pk_fma_f32 v[118:119], v[118:119], v[138:139], v[130:131] op_sel_hi:[1,0,1]
	v_pk_fma_f32 v[116:117], v[116:117], v[138:139], v[128:129] op_sel_hi:[1,0,1]
	v_pk_mul_f32 v[108:109], v[108:109], v[164:165]
	v_lshlrev_b32_e32 v144, 16, v199
	v_and_b32_e32 v145, 0xffff0000, v199
	v_pk_mul_f32 v[110:111], v[110:111], v[166:167]
	v_pk_fma_f32 v[128:129], v[108:109], v[138:139], v[142:143] op_sel_hi:[1,0,1]
	v_mul_f32_e32 v108, v117, v117
	v_mul_f32_e32 v109, v119, v119
	v_pk_fma_f32 v[110:111], v[110:111], v[138:139], v[144:145] op_sel_hi:[1,0,1]
	v_fmac_f32_e32 v108, v116, v116
	v_fmac_f32_e32 v109, v118, v118
	v_add_f32_e32 v108, v108, v109
	v_mul_f32_e32 v109, v129, v129
	v_mul_f32_e32 v130, v111, v111
	v_fmac_f32_e32 v109, v128, v128
	v_fmac_f32_e32 v130, v110, v110
	v_add_f32_e32 v109, v109, v130
	v_add_f32_e32 v108, v108, v109
	v_add_f32_e32 v138, v139, v108
	ds_bpermute_b32 v139, v3, v138
	v_add3_u32 v136, s20, v215, 16
	v_ashrrev_i32_e32 v137, 31, v136
	v_lshlrev_b64 v[140:141], 11, v[136:137]
	v_lshl_add_u64 v[108:109], s[62:63], 0, v[140:141]
	v_lshl_add_u64 v[130:131], v[218:219], 1, v[108:109]
	s_waitcnt lgkmcnt(0)
	v_add_f32_e32 v108, v138, v139
	ds_bpermute_b32 v109, v226, v108
	global_store_dwordx4 v[130:131], v[124:127], off sc1
	v_cvt_pk_bf16_f32 v116, v116, v117
	v_cvt_pk_bf16_f32 v117, v118, v119
	v_cvt_pk_bf16_f32 v118, v128, v129
	v_cvt_pk_bf16_f32 v119, v110, v111
	global_store_dwordx4 v[130:131], v[116:119], off offset:256 sc1
	s_and_saveexec_b64 s[10:11], s[0:1]
	s_cbranch_execz .LBB0_974
	s_waitcnt lgkmcnt(0)
	v_add_f32_e32 v110, v108, v109
	v_lshlrev_b64 v[108:109], 6, v[136:137]
	v_lshl_add_u64 v[108:109], s[86:87], 0, v[108:109]
	v_lshl_add_u64 v[108:109], s[4:5], 2, v[108:109]
	v_lshl_add_u64 v[108:109], v[108:109], 0, s[6:7]
	global_store_dword v[108:109], v110, off
.LBB0_974:
	s_or_b64 exec, exec, s[10:11]
	ds_read_b32 v110, v227 offset:4224
	v_lshlrev_b32_e32 v118, 16, v192
	v_and_b32_e32 v119, 0xffff0000, v192
	v_lshlrev_b32_e32 v124, 16, v193
	v_and_b32_e32 v125, 0xffff0000, v193
	v_pk_mul_f32 v[106:107], v[106:107], v[182:183]
	v_pk_mul_f32 v[104:105], v[104:105], v[180:181]
	v_lshlrev_b32_e32 v126, 16, v194
	v_and_b32_e32 v127, 0xffff0000, v194
	v_lshlrev_b32_e32 v128, 16, v195
	v_and_b32_e32 v129, 0xffff0000, v195
	s_waitcnt lgkmcnt(0)
	v_pk_fma_f32 v[106:107], v[106:107], v[110:111], v[124:125] op_sel_hi:[1,0,1]
	v_pk_fma_f32 v[104:105], v[104:105], v[110:111], v[118:119] op_sel_hi:[1,0,1]
	v_pk_mul_f32 v[98:99], v[98:99], v[178:179]
	v_pk_mul_f32 v[96:97], v[96:97], v[176:177]
	v_pk_fma_f32 v[118:119], v[98:99], v[110:111], v[128:129] op_sel_hi:[1,0,1]
	v_pk_fma_f32 v[98:99], v[96:97], v[110:111], v[126:127] op_sel_hi:[1,0,1]
	v_mul_f32_e32 v96, v105, v105
	v_mul_f32_e32 v97, v107, v107
	v_fmac_f32_e32 v96, v104, v104
	v_fmac_f32_e32 v97, v106, v106
	v_add_f32_e32 v96, v96, v97
	v_mul_f32_e32 v97, v99, v99
	v_mul_f32_e32 v111, v119, v119
	v_fmac_f32_e32 v97, v98, v98
	v_fmac_f32_e32 v111, v118, v118
	v_add_f32_e32 v97, v97, v111
	v_add_f32_e32 v111, v96, v97
	v_cvt_pk_bf16_f32 v96, v104, v105
	v_cvt_pk_bf16_f32 v97, v106, v107
	v_lshlrev_b32_e32 v104, 16, v188
	v_and_b32_e32 v105, 0xffff0000, v188
	v_lshlrev_b32_e32 v106, 16, v189
	v_and_b32_e32 v107, 0xffff0000, v189
	v_pk_mul_f32 v[90:91], v[90:91], v[170:171]
	v_pk_mul_f32 v[88:89], v[88:89], v[168:169]
	v_cvt_pk_bf16_f32 v98, v98, v99
	v_cvt_pk_bf16_f32 v99, v118, v119
	v_lshlrev_b32_e32 v118, 16, v190
	v_and_b32_e32 v119, 0xffff0000, v190
	v_pk_fma_f32 v[90:91], v[90:91], v[110:111], v[106:107] op_sel_hi:[1,0,1]
	v_pk_fma_f32 v[88:89], v[88:89], v[110:111], v[104:105] op_sel_hi:[1,0,1]
	v_pk_mul_f32 v[84:85], v[84:85], v[164:165]
	v_lshlrev_b32_e32 v124, 16, v191
	v_and_b32_e32 v125, 0xffff0000, v191
	v_pk_mul_f32 v[86:87], v[86:87], v[166:167]
	v_pk_fma_f32 v[106:107], v[84:85], v[110:111], v[118:119] op_sel_hi:[1,0,1]
	v_mul_f32_e32 v84, v89, v89
	v_mul_f32_e32 v85, v91, v91
	v_pk_fma_f32 v[104:105], v[86:87], v[110:111], v[124:125] op_sel_hi:[1,0,1]
	v_fmac_f32_e32 v84, v88, v88
	v_fmac_f32_e32 v85, v90, v90
	v_add_f32_e32 v84, v84, v85
	v_mul_f32_e32 v85, v107, v107
	v_mul_f32_e32 v86, v105, v105
	v_fmac_f32_e32 v85, v106, v106
	v_fmac_f32_e32 v86, v104, v104
	v_add_f32_e32 v85, v85, v86
	v_add_f32_e32 v84, v84, v85
	v_add_f32_e32 v87, v111, v84
	ds_bpermute_b32 v118, v3, v87
	v_add3_u32 v108, s20, v215, 32
	v_ashrrev_i32_e32 v109, 31, v108
	v_lshlrev_b64 v[116:117], 11, v[108:109]
	v_lshl_add_u64 v[84:85], s[62:63], 0, v[116:117]
	v_lshl_add_u64 v[110:111], v[218:219], 1, v[84:85]
	s_waitcnt lgkmcnt(0)
	v_add_f32_e32 v84, v87, v118
	ds_bpermute_b32 v85, v226, v84
	global_store_dwordx4 v[110:111], v[96:99], off sc1
	v_cvt_pk_bf16_f32 v86, v88, v89
	v_cvt_pk_bf16_f32 v87, v90, v91
	v_cvt_pk_bf16_f32 v88, v106, v107
	v_cvt_pk_bf16_f32 v89, v104, v105
	global_store_dwordx4 v[110:111], v[86:89], off offset:256 sc1
	s_and_saveexec_b64 s[10:11], s[0:1]
	s_cbranch_execz .LBB0_976
	s_waitcnt lgkmcnt(0)
	v_add_f32_e32 v86, v84, v85
	v_lshlrev_b64 v[84:85], 6, v[108:109]
	v_lshl_add_u64 v[84:85], s[86:87], 0, v[84:85]
	v_lshl_add_u64 v[84:85], s[4:5], 2, v[84:85]
	v_lshl_add_u64 v[84:85], v[84:85], 0, s[6:7]
	global_store_dword v[84:85], v86, off
.LBB0_976:
	s_or_b64 exec, exec, s[10:11]
	ds_read_b32 v86, v227 offset:4288
	v_lshlrev_b32_e32 v90, 16, v184
	v_and_b32_e32 v91, 0xffff0000, v184
	v_lshlrev_b32_e32 v96, 16, v185
	v_and_b32_e32 v97, 0xffff0000, v185
	v_pk_mul_f32 v[82:83], v[82:83], v[182:183]
	v_pk_mul_f32 v[80:81], v[80:81], v[180:181]
	v_lshlrev_b32_e32 v98, 16, v186
	v_and_b32_e32 v99, 0xffff0000, v186
	v_lshlrev_b32_e32 v104, 16, v187
	v_and_b32_e32 v105, 0xffff0000, v187
	s_waitcnt lgkmcnt(0)
	v_pk_fma_f32 v[82:83], v[82:83], v[86:87], v[96:97] op_sel_hi:[1,0,1]
	v_pk_fma_f32 v[80:81], v[80:81], v[86:87], v[90:91] op_sel_hi:[1,0,1]
	v_pk_mul_f32 v[78:79], v[78:79], v[178:179]
	v_pk_mul_f32 v[76:77], v[76:77], v[176:177]
	v_pk_fma_f32 v[90:91], v[78:79], v[86:87], v[104:105] op_sel_hi:[1,0,1]
	v_pk_fma_f32 v[78:79], v[76:77], v[86:87], v[98:99] op_sel_hi:[1,0,1]
	v_mul_f32_e32 v76, v81, v81
	v_mul_f32_e32 v77, v83, v83
	v_fmac_f32_e32 v76, v80, v80
	v_fmac_f32_e32 v77, v82, v82
	v_add_f32_e32 v76, v76, v77
	v_mul_f32_e32 v77, v79, v79
	v_mul_f32_e32 v87, v91, v91
	v_fmac_f32_e32 v77, v78, v78
	v_fmac_f32_e32 v87, v90, v90
	v_add_f32_e32 v77, v77, v87
	v_add_f32_e32 v87, v76, v77
	v_cvt_pk_bf16_f32 v76, v80, v81
	v_cvt_pk_bf16_f32 v77, v82, v83
	v_lshlrev_b32_e32 v80, 16, v172
	v_and_b32_e32 v81, 0xffff0000, v172
	v_lshlrev_b32_e32 v82, 16, v173
	v_and_b32_e32 v83, 0xffff0000, v173
	v_pk_mul_f32 v[74:75], v[74:75], v[170:171]
	v_pk_mul_f32 v[72:73], v[72:73], v[168:169]
	v_cvt_pk_bf16_f32 v78, v78, v79
	v_cvt_pk_bf16_f32 v79, v90, v91
	v_lshlrev_b32_e32 v90, 16, v174
	v_and_b32_e32 v91, 0xffff0000, v174
	v_pk_fma_f32 v[74:75], v[74:75], v[86:87], v[82:83] op_sel_hi:[1,0,1]
	v_pk_fma_f32 v[72:73], v[72:73], v[86:87], v[80:81] op_sel_hi:[1,0,1]
	v_pk_mul_f32 v[68:69], v[68:69], v[164:165]
	v_lshlrev_b32_e32 v96, 16, v175
	v_and_b32_e32 v97, 0xffff0000, v175
	v_pk_mul_f32 v[70:71], v[70:71], v[166:167]
	v_pk_fma_f32 v[82:83], v[68:69], v[86:87], v[90:91] op_sel_hi:[1,0,1]
	v_mul_f32_e32 v68, v73, v73
	v_mul_f32_e32 v69, v75, v75
	v_pk_fma_f32 v[80:81], v[70:71], v[86:87], v[96:97] op_sel_hi:[1,0,1]
	v_fmac_f32_e32 v68, v72, v72
	v_fmac_f32_e32 v69, v74, v74
	v_add_f32_e32 v68, v68, v69
	v_mul_f32_e32 v69, v83, v83
	v_mul_f32_e32 v70, v81, v81
	v_fmac_f32_e32 v69, v82, v82
	v_fmac_f32_e32 v70, v80, v80
	v_add_f32_e32 v69, v69, v70
	v_add_f32_e32 v68, v68, v69
	v_add_f32_e32 v71, v87, v68
	ds_bpermute_b32 v90, v3, v71
	v_add3_u32 v84, s20, v215, 48
	v_ashrrev_i32_e32 v85, 31, v84
	v_lshlrev_b64 v[88:89], 11, v[84:85]
	v_lshl_add_u64 v[68:69], s[62:63], 0, v[88:89]
	v_lshl_add_u64 v[86:87], v[218:219], 1, v[68:69]
	s_waitcnt lgkmcnt(0)
	v_add_f32_e32 v68, v71, v90
	ds_bpermute_b32 v69, v226, v68
	global_store_dwordx4 v[86:87], v[76:79], off sc1
	v_cvt_pk_bf16_f32 v70, v72, v73
	v_cvt_pk_bf16_f32 v71, v74, v75
	v_cvt_pk_bf16_f32 v72, v82, v83
	v_cvt_pk_bf16_f32 v73, v80, v81
	global_store_dwordx4 v[86:87], v[70:73], off offset:256 sc1
	s_and_saveexec_b64 s[10:11], s[0:1]
	s_cbranch_execz .LBB0_978
	s_waitcnt lgkmcnt(0)
	v_add_f32_e32 v70, v68, v69
	v_lshlrev_b64 v[68:69], 6, v[84:85]
	v_lshl_add_u64 v[68:69], s[86:87], 0, v[68:69]
	v_lshl_add_u64 v[68:69], s[4:5], 2, v[68:69]
	v_lshl_add_u64 v[68:69], v[68:69], 0, s[6:7]
	global_store_dword v[68:69], v70, off
.LBB0_978:
	s_or_b64 exec, exec, s[10:11]
	ds_read_b32 v70, v227 offset:4608
	v_lshlrev_b32_e32 v74, 16, v160
	v_and_b32_e32 v75, 0xffff0000, v160
	v_lshlrev_b32_e32 v76, 16, v161
	v_and_b32_e32 v77, 0xffff0000, v161
	v_pk_mul_f32 v[66:67], v[66:67], v[182:183]
	v_pk_mul_f32 v[64:65], v[64:65], v[180:181]
	v_lshlrev_b32_e32 v78, 16, v162
	v_and_b32_e32 v79, 0xffff0000, v162
	v_lshlrev_b32_e32 v80, 16, v163
	v_and_b32_e32 v81, 0xffff0000, v163
	s_waitcnt lgkmcnt(0)
	v_pk_fma_f32 v[66:67], v[66:67], v[70:71], v[76:77] op_sel_hi:[1,0,1]
	v_pk_fma_f32 v[64:65], v[64:65], v[70:71], v[74:75] op_sel_hi:[1,0,1]
	v_pk_mul_f32 v[62:63], v[62:63], v[178:179]
	v_pk_mul_f32 v[60:61], v[60:61], v[176:177]
	v_pk_fma_f32 v[74:75], v[62:63], v[70:71], v[80:81] op_sel_hi:[1,0,1]
	v_pk_fma_f32 v[62:63], v[60:61], v[70:71], v[78:79] op_sel_hi:[1,0,1]
	v_mul_f32_e32 v60, v65, v65
	v_mul_f32_e32 v61, v67, v67
	v_fmac_f32_e32 v60, v64, v64
	v_fmac_f32_e32 v61, v66, v66
	v_add_f32_e32 v60, v60, v61
	v_mul_f32_e32 v61, v63, v63
	v_mul_f32_e32 v71, v75, v75
	v_fmac_f32_e32 v61, v62, v62
	v_fmac_f32_e32 v71, v74, v74
	v_add_f32_e32 v61, v61, v71
	v_add_f32_e32 v71, v60, v61
	v_cvt_pk_bf16_f32 v60, v64, v65
	v_cvt_pk_bf16_f32 v61, v66, v67
	v_lshlrev_b32_e32 v64, 16, v156
	v_and_b32_e32 v65, 0xffff0000, v156
	v_lshlrev_b32_e32 v66, 16, v157
	v_and_b32_e32 v67, 0xffff0000, v157
	v_pk_mul_f32 v[58:59], v[58:59], v[170:171]
	v_pk_mul_f32 v[56:57], v[56:57], v[168:169]
	v_cvt_pk_bf16_f32 v62, v62, v63
	v_cvt_pk_bf16_f32 v63, v74, v75
	v_lshlrev_b32_e32 v74, 16, v158
	v_and_b32_e32 v75, 0xffff0000, v158
	v_pk_fma_f32 v[58:59], v[58:59], v[70:71], v[66:67] op_sel_hi:[1,0,1]
	v_pk_fma_f32 v[56:57], v[56:57], v[70:71], v[64:65] op_sel_hi:[1,0,1]
	v_pk_mul_f32 v[52:53], v[52:53], v[164:165]
	v_lshlrev_b32_e32 v76, 16, v159
	v_and_b32_e32 v77, 0xffff0000, v159
	v_pk_mul_f32 v[54:55], v[54:55], v[166:167]
	v_pk_fma_f32 v[66:67], v[52:53], v[70:71], v[74:75] op_sel_hi:[1,0,1]
	v_mul_f32_e32 v52, v57, v57
	v_mul_f32_e32 v53, v59, v59
	v_pk_fma_f32 v[64:65], v[54:55], v[70:71], v[76:77] op_sel_hi:[1,0,1]
	v_fmac_f32_e32 v52, v56, v56
	v_fmac_f32_e32 v53, v58, v58
	v_add_f32_e32 v52, v52, v53
	v_mul_f32_e32 v53, v67, v67
	v_mul_f32_e32 v54, v65, v65
	v_fmac_f32_e32 v53, v66, v66
	v_fmac_f32_e32 v54, v64, v64
	v_add_f32_e32 v53, v53, v54
	v_add_f32_e32 v52, v52, v53
	v_add_f32_e32 v55, v71, v52
	ds_bpermute_b32 v74, v3, v55
	v_add_u32_e32 v68, 0x80, v220
	v_ashrrev_i32_e32 v69, 31, v68
	v_lshlrev_b64 v[72:73], 11, v[68:69]
	v_lshl_add_u64 v[52:53], s[62:63], 0, v[72:73]
	v_lshl_add_u64 v[70:71], v[218:219], 1, v[52:53]
	s_waitcnt lgkmcnt(0)
	v_add_f32_e32 v52, v55, v74
	ds_bpermute_b32 v53, v226, v52
	global_store_dwordx4 v[70:71], v[60:63], off sc1
	v_cvt_pk_bf16_f32 v54, v56, v57
	v_cvt_pk_bf16_f32 v55, v58, v59
	v_cvt_pk_bf16_f32 v56, v66, v67
	v_cvt_pk_bf16_f32 v57, v64, v65
	global_store_dwordx4 v[70:71], v[54:57], off offset:256 sc1
	s_and_saveexec_b64 s[10:11], s[0:1]
	s_cbranch_execz .LBB0_980
	s_waitcnt lgkmcnt(0)
	v_add_f32_e32 v54, v52, v53
	v_lshlrev_b64 v[52:53], 6, v[68:69]
	v_lshl_add_u64 v[52:53], s[86:87], 0, v[52:53]
	v_lshl_add_u64 v[52:53], s[4:5], 2, v[52:53]
	v_lshl_add_u64 v[52:53], v[52:53], 0, s[6:7]
	global_store_dword v[52:53], v54, off
.LBB0_980:
	s_or_b64 exec, exec, s[10:11]
	ds_read_b32 v54, v227 offset:4672
	v_lshlrev_b32_e32 v58, 16, v152
	v_and_b32_e32 v59, 0xffff0000, v152
	v_lshlrev_b32_e32 v60, 16, v153
	v_and_b32_e32 v61, 0xffff0000, v153
	v_pk_mul_f32 v[50:51], v[50:51], v[182:183]
	v_pk_mul_f32 v[48:49], v[48:49], v[180:181]
	v_lshlrev_b32_e32 v62, 16, v154
	v_and_b32_e32 v63, 0xffff0000, v154
	v_lshlrev_b32_e32 v64, 16, v155
	v_and_b32_e32 v65, 0xffff0000, v155
	s_waitcnt lgkmcnt(0)
	v_pk_fma_f32 v[50:51], v[50:51], v[54:55], v[60:61] op_sel_hi:[1,0,1]
	v_pk_fma_f32 v[48:49], v[48:49], v[54:55], v[58:59] op_sel_hi:[1,0,1]
	v_pk_mul_f32 v[46:47], v[46:47], v[178:179]
	v_pk_mul_f32 v[44:45], v[44:45], v[176:177]
	v_pk_fma_f32 v[58:59], v[46:47], v[54:55], v[64:65] op_sel_hi:[1,0,1]
	v_pk_fma_f32 v[46:47], v[44:45], v[54:55], v[62:63] op_sel_hi:[1,0,1]
	v_mul_f32_e32 v44, v49, v49
	v_mul_f32_e32 v45, v51, v51
	v_fmac_f32_e32 v44, v48, v48
	v_fmac_f32_e32 v45, v50, v50
	v_add_f32_e32 v44, v44, v45
	v_mul_f32_e32 v45, v47, v47
	v_mul_f32_e32 v55, v59, v59
	v_fmac_f32_e32 v45, v46, v46
	v_fmac_f32_e32 v55, v58, v58
	v_add_f32_e32 v45, v45, v55
	v_add_f32_e32 v55, v44, v45
	v_cvt_pk_bf16_f32 v44, v48, v49
	v_cvt_pk_bf16_f32 v45, v50, v51
	v_lshlrev_b32_e32 v48, 16, v132
	v_and_b32_e32 v49, 0xffff0000, v132
	v_lshlrev_b32_e32 v50, 16, v133
	v_and_b32_e32 v51, 0xffff0000, v133
	v_pk_mul_f32 v[42:43], v[42:43], v[170:171]
	v_pk_mul_f32 v[40:41], v[40:41], v[168:169]
	v_cvt_pk_bf16_f32 v46, v46, v47
	v_cvt_pk_bf16_f32 v47, v58, v59
	v_lshlrev_b32_e32 v58, 16, v134
	v_and_b32_e32 v59, 0xffff0000, v134
	v_pk_fma_f32 v[42:43], v[42:43], v[54:55], v[50:51] op_sel_hi:[1,0,1]
	v_pk_fma_f32 v[40:41], v[40:41], v[54:55], v[48:49] op_sel_hi:[1,0,1]
	v_pk_mul_f32 v[36:37], v[36:37], v[164:165]
	v_lshlrev_b32_e32 v60, 16, v135
	v_and_b32_e32 v61, 0xffff0000, v135
	v_pk_mul_f32 v[38:39], v[38:39], v[166:167]
	v_pk_fma_f32 v[50:51], v[36:37], v[54:55], v[58:59] op_sel_hi:[1,0,1]
	v_mul_f32_e32 v36, v41, v41
	v_mul_f32_e32 v37, v43, v43
	v_pk_fma_f32 v[48:49], v[38:39], v[54:55], v[60:61] op_sel_hi:[1,0,1]
	v_fmac_f32_e32 v36, v40, v40
	v_fmac_f32_e32 v37, v42, v42
	v_add_f32_e32 v36, v36, v37
	v_mul_f32_e32 v37, v51, v51
	v_mul_f32_e32 v38, v49, v49
	v_fmac_f32_e32 v37, v50, v50
	v_fmac_f32_e32 v38, v48, v48
	v_add_f32_e32 v37, v37, v38
	v_add_f32_e32 v36, v36, v37
	v_add_f32_e32 v39, v55, v36
	ds_bpermute_b32 v58, v3, v39
	v_add_u32_e32 v52, 0x90, v220
	v_ashrrev_i32_e32 v53, 31, v52
	v_lshlrev_b64 v[56:57], 11, v[52:53]
	v_lshl_add_u64 v[36:37], s[62:63], 0, v[56:57]
	v_lshl_add_u64 v[54:55], v[218:219], 1, v[36:37]
	s_waitcnt lgkmcnt(0)
	v_add_f32_e32 v36, v39, v58
	ds_bpermute_b32 v37, v226, v36
	global_store_dwordx4 v[54:55], v[44:47], off sc1
	v_cvt_pk_bf16_f32 v38, v40, v41
	v_cvt_pk_bf16_f32 v39, v42, v43
	v_cvt_pk_bf16_f32 v40, v50, v51
	v_cvt_pk_bf16_f32 v41, v48, v49
	global_store_dwordx4 v[54:55], v[38:41], off offset:256 sc1
	s_and_saveexec_b64 s[10:11], s[0:1]
	s_cbranch_execz .LBB0_982
	s_waitcnt lgkmcnt(0)
	v_add_f32_e32 v38, v36, v37
	v_lshlrev_b64 v[36:37], 6, v[52:53]
	v_lshl_add_u64 v[36:37], s[86:87], 0, v[36:37]
	v_lshl_add_u64 v[36:37], s[4:5], 2, v[36:37]
	v_lshl_add_u64 v[36:37], v[36:37], 0, s[6:7]
	global_store_dword v[36:37], v38, off
.LBB0_982:
	s_or_b64 exec, exec, s[10:11]
	ds_read_b32 v38, v227 offset:4736
	v_lshlrev_b32_e32 v42, 16, v120
	v_and_b32_e32 v43, 0xffff0000, v120
	v_lshlrev_b32_e32 v44, 16, v121
	v_and_b32_e32 v45, 0xffff0000, v121
	v_pk_mul_f32 v[34:35], v[34:35], v[182:183]
	v_pk_mul_f32 v[32:33], v[32:33], v[180:181]
	v_lshlrev_b32_e32 v46, 16, v122
	v_and_b32_e32 v47, 0xffff0000, v122
	v_lshlrev_b32_e32 v48, 16, v123
	v_and_b32_e32 v49, 0xffff0000, v123
	s_waitcnt lgkmcnt(0)
	v_pk_fma_f32 v[34:35], v[34:35], v[38:39], v[44:45] op_sel_hi:[1,0,1]
	v_pk_fma_f32 v[32:33], v[32:33], v[38:39], v[42:43] op_sel_hi:[1,0,1]
	v_pk_mul_f32 v[30:31], v[30:31], v[178:179]
	v_pk_mul_f32 v[28:29], v[28:29], v[176:177]
	v_pk_fma_f32 v[42:43], v[30:31], v[38:39], v[48:49] op_sel_hi:[1,0,1]
	v_pk_fma_f32 v[30:31], v[28:29], v[38:39], v[46:47] op_sel_hi:[1,0,1]
	v_mul_f32_e32 v28, v33, v33
	v_mul_f32_e32 v29, v35, v35
	v_fmac_f32_e32 v28, v32, v32
	v_fmac_f32_e32 v29, v34, v34
	v_add_f32_e32 v28, v28, v29
	v_mul_f32_e32 v29, v31, v31
	v_mul_f32_e32 v39, v43, v43
	v_fmac_f32_e32 v29, v30, v30
	v_fmac_f32_e32 v39, v42, v42
	v_add_f32_e32 v29, v29, v39
	v_add_f32_e32 v39, v28, v29
	v_cvt_pk_bf16_f32 v28, v32, v33
	v_cvt_pk_bf16_f32 v29, v34, v35
	v_lshlrev_b32_e32 v32, 16, v112
	v_and_b32_e32 v33, 0xffff0000, v112
	v_lshlrev_b32_e32 v34, 16, v113
	v_and_b32_e32 v35, 0xffff0000, v113
	v_pk_mul_f32 v[26:27], v[26:27], v[170:171]
	v_pk_mul_f32 v[24:25], v[24:25], v[168:169]
	v_cvt_pk_bf16_f32 v30, v30, v31
	v_cvt_pk_bf16_f32 v31, v42, v43
	v_lshlrev_b32_e32 v42, 16, v114
	v_and_b32_e32 v43, 0xffff0000, v114
	v_pk_fma_f32 v[26:27], v[26:27], v[38:39], v[34:35] op_sel_hi:[1,0,1]
	v_pk_fma_f32 v[24:25], v[24:25], v[38:39], v[32:33] op_sel_hi:[1,0,1]
	v_pk_mul_f32 v[20:21], v[20:21], v[164:165]
	v_lshlrev_b32_e32 v44, 16, v115
	v_and_b32_e32 v45, 0xffff0000, v115
	v_pk_mul_f32 v[22:23], v[22:23], v[166:167]
	v_pk_fma_f32 v[34:35], v[20:21], v[38:39], v[42:43] op_sel_hi:[1,0,1]
	v_mul_f32_e32 v20, v25, v25
	v_mul_f32_e32 v21, v27, v27
	v_pk_fma_f32 v[32:33], v[22:23], v[38:39], v[44:45] op_sel_hi:[1,0,1]
	v_fmac_f32_e32 v20, v24, v24
	v_fmac_f32_e32 v21, v26, v26
	v_add_f32_e32 v20, v20, v21
	v_mul_f32_e32 v21, v35, v35
	v_mul_f32_e32 v22, v33, v33
	v_fmac_f32_e32 v21, v34, v34
	v_fmac_f32_e32 v22, v32, v32
	v_add_f32_e32 v21, v21, v22
	v_add_f32_e32 v20, v20, v21
	v_add_f32_e32 v23, v39, v20
	ds_bpermute_b32 v42, v3, v23
	v_add_u32_e32 v36, 0xa0, v220
	v_ashrrev_i32_e32 v37, 31, v36
	v_lshlrev_b64 v[40:41], 11, v[36:37]
	v_lshl_add_u64 v[20:21], s[62:63], 0, v[40:41]
	v_lshl_add_u64 v[38:39], v[218:219], 1, v[20:21]
	s_waitcnt lgkmcnt(0)
	v_add_f32_e32 v20, v23, v42
	ds_bpermute_b32 v21, v226, v20
	global_store_dwordx4 v[38:39], v[28:31], off sc1
	v_cvt_pk_bf16_f32 v22, v24, v25
	v_cvt_pk_bf16_f32 v23, v26, v27
	v_cvt_pk_bf16_f32 v24, v34, v35
	v_cvt_pk_bf16_f32 v25, v32, v33
	global_store_dwordx4 v[38:39], v[22:25], off offset:256 sc1
	s_and_saveexec_b64 s[10:11], s[0:1]
	s_cbranch_execz .LBB0_984
	s_waitcnt lgkmcnt(0)
	v_add_f32_e32 v22, v20, v21
	v_lshlrev_b64 v[20:21], 6, v[36:37]
	v_lshl_add_u64 v[20:21], s[86:87], 0, v[20:21]
	v_lshl_add_u64 v[20:21], s[4:5], 2, v[20:21]
	v_lshl_add_u64 v[20:21], v[20:21], 0, s[6:7]
	global_store_dword v[20:21], v22, off
.LBB0_984:
	s_or_b64 exec, exec, s[10:11]
	ds_read_b32 v22, v227 offset:4800
	v_lshlrev_b32_e32 v26, 16, v100
	v_and_b32_e32 v27, 0xffff0000, v100
	v_lshlrev_b32_e32 v28, 16, v101
	v_and_b32_e32 v29, 0xffff0000, v101
	v_pk_mul_f32 v[18:19], v[18:19], v[182:183]
	v_pk_mul_f32 v[16:17], v[16:17], v[180:181]
	v_lshlrev_b32_e32 v30, 16, v102
	v_and_b32_e32 v31, 0xffff0000, v102
	v_lshlrev_b32_e32 v32, 16, v103
	v_and_b32_e32 v33, 0xffff0000, v103
	s_waitcnt lgkmcnt(0)
	v_pk_fma_f32 v[18:19], v[18:19], v[22:23], v[28:29] op_sel_hi:[1,0,1]
	v_pk_fma_f32 v[16:17], v[16:17], v[22:23], v[26:27] op_sel_hi:[1,0,1]
	v_pk_mul_f32 v[14:15], v[14:15], v[178:179]
	v_pk_mul_f32 v[12:13], v[12:13], v[176:177]
	v_pk_fma_f32 v[26:27], v[14:15], v[22:23], v[32:33] op_sel_hi:[1,0,1]
	v_pk_fma_f32 v[14:15], v[12:13], v[22:23], v[30:31] op_sel_hi:[1,0,1]
	v_mul_f32_e32 v12, v17, v17
	v_mul_f32_e32 v13, v19, v19
	v_fmac_f32_e32 v12, v16, v16
	v_fmac_f32_e32 v13, v18, v18
	v_add_f32_e32 v12, v12, v13
	v_mul_f32_e32 v13, v15, v15
	v_mul_f32_e32 v23, v27, v27
	v_fmac_f32_e32 v13, v14, v14
	v_fmac_f32_e32 v23, v26, v26
	v_add_f32_e32 v13, v13, v23
	v_add_f32_e32 v23, v12, v13
	v_cvt_pk_bf16_f32 v12, v16, v17
	v_cvt_pk_bf16_f32 v13, v18, v19
	v_lshlrev_b32_e32 v16, 16, v92
	v_and_b32_e32 v17, 0xffff0000, v92
	v_lshlrev_b32_e32 v18, 16, v93
	v_and_b32_e32 v19, 0xffff0000, v93
	v_pk_mul_f32 v[10:11], v[10:11], v[170:171]
	v_pk_mul_f32 v[8:9], v[8:9], v[168:169]
	v_cvt_pk_bf16_f32 v14, v14, v15
	v_cvt_pk_bf16_f32 v15, v26, v27
	v_lshlrev_b32_e32 v26, 16, v94
	v_and_b32_e32 v27, 0xffff0000, v94
	v_pk_fma_f32 v[10:11], v[10:11], v[22:23], v[18:19] op_sel_hi:[1,0,1]
	v_pk_fma_f32 v[8:9], v[8:9], v[22:23], v[16:17] op_sel_hi:[1,0,1]
	v_pk_mul_f32 v[4:5], v[4:5], v[164:165]
	v_lshlrev_b32_e32 v28, 16, v95
	v_and_b32_e32 v29, 0xffff0000, v95
	v_pk_mul_f32 v[6:7], v[6:7], v[166:167]
	v_pk_fma_f32 v[18:19], v[4:5], v[22:23], v[26:27] op_sel_hi:[1,0,1]
	v_mul_f32_e32 v4, v9, v9
	v_mul_f32_e32 v5, v11, v11
	v_pk_fma_f32 v[16:17], v[6:7], v[22:23], v[28:29] op_sel_hi:[1,0,1]
	v_fmac_f32_e32 v4, v8, v8
	v_fmac_f32_e32 v5, v10, v10
	v_add_f32_e32 v4, v4, v5
	v_mul_f32_e32 v5, v19, v19
	v_mul_f32_e32 v6, v17, v17
	v_fmac_f32_e32 v5, v18, v18
	v_fmac_f32_e32 v6, v16, v16
	v_add_f32_e32 v5, v5, v6
	v_add_f32_e32 v4, v4, v5
	v_add_f32_e32 v7, v23, v4
	ds_bpermute_b32 v3, v3, v7
	v_add_u32_e32 v20, 0xb0, v220
	v_ashrrev_i32_e32 v21, 31, v20
	v_lshlrev_b64 v[24:25], 11, v[20:21]
	v_lshl_add_u64 v[4:5], s[62:63], 0, v[24:25]
	s_waitcnt lgkmcnt(0)
	v_add_f32_e32 v3, v7, v3
	v_lshl_add_u64 v[22:23], v[218:219], 1, v[4:5]
	ds_bpermute_b32 v4, v226, v3
	global_store_dwordx4 v[22:23], v[12:15], off sc1
	v_cvt_pk_bf16_f32 v6, v8, v9
	v_cvt_pk_bf16_f32 v7, v10, v11
	v_cvt_pk_bf16_f32 v8, v18, v19
	v_cvt_pk_bf16_f32 v9, v16, v17
	global_store_dwordx4 v[22:23], v[6:9], off offset:256 sc1
	s_and_saveexec_b64 s[10:11], s[0:1]
	s_cbranch_execz .LBB0_986
	s_waitcnt lgkmcnt(0)
	v_add_f32_e32 v3, v3, v4
	v_lshlrev_b64 v[4:5], 6, v[20:21]
	v_lshl_add_u64 v[4:5], s[86:87], 0, v[4:5]
	v_lshl_add_u64 v[4:5], s[4:5], 2, v[4:5]
	v_lshl_add_u64 v[4:5], v[4:5], 0, s[6:7]
	global_store_dword v[4:5], v3, off

.LBB0_1134:
	s_lshl_b32 s39, s46, 8
	s_and_b32 s39, s39, 0x100
	s_cmp_eq_u32 s37, 1
	ds_read_b32 v152, v157
	s_cselect_b64 vcc, -1, 0
	v_lshl_add_u32 v148, s44, 8, v156
	v_cndmask_b32_e32 v149, 1.0, v163, vcc
	v_cndmask_b32_e64 v166, v149, v164, s[4:5]
	v_ashrrev_i32_e32 v149, 31, v148
	v_or_b32_e32 v165, s39, v159
	v_lshlrev_b64 v[150:151], 9, v[148:149]
	s_cmp_lg_u64 s[58:59], 0
	v_or_b32_e32 v150, v150, v165
	s_waitcnt lgkmcnt(0)
	v_mul_f32_e32 v154, v166, v152
	s_cselect_b64 s[44:45], -1, 0
	s_cmp_eq_u64 s[58:59], 0
	v_lshl_add_u64 v[152:153], v[150:151], 1, s[48:49]
	v_lshl_add_u64 v[150:151], v[150:151], 2, s[58:59]
	v_pk_mul_f32 v[130:131], v[130:131], v[154:155] op_sel_hi:[1,0]
	v_pk_mul_f32 v[128:129], v[128:129], v[154:155] op_sel_hi:[1,0]
	v_pk_mul_f32 v[126:127], v[126:127], v[154:155] op_sel_hi:[1,0]
	v_pk_mul_f32 v[124:125], v[124:125], v[154:155] op_sel_hi:[1,0]
	v_cvt_pk_bf16_f32 v168, v128, v129
	v_cvt_pk_bf16_f32 v169, v130, v131
	s_nop 0
	v_cvt_pk_bf16_f32 v170, v124, v125
	v_cvt_pk_bf16_f32 v171, v126, v127
	global_store_dwordx4 v[152:153], v[168:171], off sc1
	s_cbranch_scc1 .LBB0_1136
	global_store_dwordx4 v[150:151], v[128:131], off nt
	global_store_dwordx4 v[150:151], v[124:127], off offset:16 nt
.LBB0_1136:
	v_mov_b32_e32 v155, v154
	s_nop 0
	v_mov_b32_e32 v124, v154
	v_mov_b32_e32 v125, v154
	v_cndmask_b32_e64 v128, 0, 1, s[44:45]
	v_pk_mul_f32 v[122:123], v[122:123], v[124:125]
	v_pk_mul_f32 v[120:121], v[120:121], v[154:155]
	v_pk_mul_f32 v[118:119], v[118:119], v[124:125]
	v_pk_mul_f32 v[116:117], v[116:117], v[154:155]
	v_cmp_ne_u32_e64 s[4:5], 1, v128
	s_andn2_b64 vcc, exec, s[44:45]
	v_cvt_pk_bf16_f32 v124, v120, v121
	v_cvt_pk_bf16_f32 v125, v122, v123
	v_cvt_pk_bf16_f32 v126, v116, v117
	v_cvt_pk_bf16_f32 v127, v118, v119
	global_store_dwordx4 v[152:153], v[124:127], off offset:256 sc1
	s_cbranch_vccnz .LBB0_1138
	global_store_dwordx4 v[150:151], v[120:123], off offset:512 nt
	global_store_dwordx4 v[150:151], v[116:119], off offset:528 nt
.LBB0_1138:
	ds_read_b32 v118, v157 offset:64
	s_nop 0
	v_or_b32_e32 v116, 16, v148
	v_ashrrev_i32_e32 v117, 31, v116
	v_lshlrev_b64 v[116:117], 9, v[116:117]
	v_or_b32_e32 v116, v116, v165
	s_waitcnt lgkmcnt(0)
	v_mul_f32_e32 v120, v166, v118
	v_lshl_add_u64 v[118:119], v[116:117], 1, s[48:49]
	v_lshl_add_u64 v[116:117], v[116:117], 2, s[58:59]
	v_pk_mul_f32 v[114:115], v[114:115], v[120:121] op_sel_hi:[1,0]
	v_pk_mul_f32 v[112:113], v[112:113], v[120:121] op_sel_hi:[1,0]
	v_pk_mul_f32 v[110:111], v[110:111], v[120:121] op_sel_hi:[1,0]
	v_pk_mul_f32 v[108:109], v[108:109], v[120:121] op_sel_hi:[1,0]
	s_and_b64 vcc, exec, s[4:5]
	v_cvt_pk_bf16_f32 v122, v112, v113
	v_cvt_pk_bf16_f32 v123, v114, v115
	v_cvt_pk_bf16_f32 v124, v108, v109
	v_cvt_pk_bf16_f32 v125, v110, v111
	global_store_dwordx4 v[118:119], v[122:125], off sc1
	s_cbranch_vccnz .LBB0_1140
	global_store_dwordx4 v[116:117], v[112:115], off nt
	global_store_dwordx4 v[116:117], v[108:111], off offset:16 nt
.LBB0_1140:
	v_mov_b32_e32 v121, v120
	s_nop 0
	v_mov_b32_e32 v108, v120
	v_mov_b32_e32 v109, v120
	v_pk_mul_f32 v[106:107], v[106:107], v[108:109]
	v_pk_mul_f32 v[104:105], v[104:105], v[120:121]
	v_pk_mul_f32 v[102:103], v[102:103], v[108:109]
	v_pk_mul_f32 v[100:101], v[100:101], v[120:121]
	s_and_b64 vcc, exec, s[4:5]
	v_cvt_pk_bf16_f32 v108, v104, v105
	v_cvt_pk_bf16_f32 v109, v106, v107
	v_cvt_pk_bf16_f32 v110, v100, v101
	v_cvt_pk_bf16_f32 v111, v102, v103
	global_store_dwordx4 v[118:119], v[108:111], off offset:256 sc1
	s_cbranch_vccnz .LBB0_1142
	global_store_dwordx4 v[116:117], v[104:107], off offset:512 nt
	global_store_dwordx4 v[116:117], v[100:103], off offset:528 nt
.LBB0_1142:
	ds_read_b32 v102, v157 offset:128
	s_nop 0
	v_or_b32_e32 v100, 32, v148
	v_ashrrev_i32_e32 v101, 31, v100
	v_lshlrev_b64 v[100:101], 9, v[100:101]
	v_or_b32_e32 v100, v100, v165
	s_waitcnt lgkmcnt(0)
	v_mul_f32_e32 v104, v166, v102
	v_lshl_add_u64 v[102:103], v[100:101], 1, s[48:49]
	v_lshl_add_u64 v[100:101], v[100:101], 2, s[58:59]
	v_pk_mul_f32 v[98:99], v[98:99], v[104:105] op_sel_hi:[1,0]
	v_pk_mul_f32 v[96:97], v[96:97], v[104:105] op_sel_hi:[1,0]
	v_pk_mul_f32 v[94:95], v[94:95], v[104:105] op_sel_hi:[1,0]
	v_pk_mul_f32 v[92:93], v[92:93], v[104:105] op_sel_hi:[1,0]
	s_and_b64 vcc, exec, s[4:5]
	v_cvt_pk_bf16_f32 v106, v96, v97
	v_cvt_pk_bf16_f32 v107, v98, v99
	v_cvt_pk_bf16_f32 v108, v92, v93
	v_cvt_pk_bf16_f32 v109, v94, v95
	global_store_dwordx4 v[102:103], v[106:109], off sc1
	s_cbranch_vccnz .LBB0_1144
	global_store_dwordx4 v[100:101], v[96:99], off nt
	global_store_dwordx4 v[100:101], v[92:95], off offset:16 nt
.LBB0_1144:
	v_mov_b32_e32 v105, v104
	s_nop 0
	v_mov_b32_e32 v92, v104
	v_mov_b32_e32 v93, v104
	v_pk_mul_f32 v[90:91], v[90:91], v[92:93]
	v_pk_mul_f32 v[88:89], v[88:89], v[104:105]
	v_pk_mul_f32 v[86:87], v[86:87], v[92:93]
	v_pk_mul_f32 v[84:85], v[84:85], v[104:105]
	s_and_b64 vcc, exec, s[4:5]
	v_cvt_pk_bf16_f32 v92, v88, v89
	v_cvt_pk_bf16_f32 v93, v90, v91
	v_cvt_pk_bf16_f32 v94, v84, v85
	v_cvt_pk_bf16_f32 v95, v86, v87
	global_store_dwordx4 v[102:103], v[92:95], off offset:256 sc1
	s_cbranch_vccnz .LBB0_1146
	global_store_dwordx4 v[100:101], v[88:91], off offset:512 nt
	global_store_dwordx4 v[100:101], v[84:87], off offset:528 nt
.LBB0_1146:
	ds_read_b32 v86, v157 offset:192
	s_nop 0
	v_or_b32_e32 v84, 48, v148
	v_ashrrev_i32_e32 v85, 31, v84
	v_lshlrev_b64 v[84:85], 9, v[84:85]
	v_or_b32_e32 v84, v84, v165
	s_waitcnt lgkmcnt(0)
	v_mul_f32_e32 v88, v166, v86
	v_lshl_add_u64 v[86:87], v[84:85], 1, s[48:49]
	v_lshl_add_u64 v[84:85], v[84:85], 2, s[58:59]
	v_pk_mul_f32 v[82:83], v[82:83], v[88:89] op_sel_hi:[1,0]
	v_pk_mul_f32 v[80:81], v[80:81], v[88:89] op_sel_hi:[1,0]
	v_pk_mul_f32 v[78:79], v[78:79], v[88:89] op_sel_hi:[1,0]
	v_pk_mul_f32 v[76:77], v[76:77], v[88:89] op_sel_hi:[1,0]
	s_and_b64 vcc, exec, s[4:5]
	v_cvt_pk_bf16_f32 v90, v80, v81
	v_cvt_pk_bf16_f32 v91, v82, v83
	v_cvt_pk_bf16_f32 v92, v76, v77
	v_cvt_pk_bf16_f32 v93, v78, v79
	global_store_dwordx4 v[86:87], v[90:93], off sc1
	s_cbranch_vccnz .LBB0_1148
	global_store_dwordx4 v[84:85], v[80:83], off nt
	global_store_dwordx4 v[84:85], v[76:79], off offset:16 nt
.LBB0_1148:
	v_mov_b32_e32 v89, v88
	s_nop 0
	v_mov_b32_e32 v76, v88
	v_mov_b32_e32 v77, v88
	v_pk_mul_f32 v[74:75], v[74:75], v[76:77]
	v_pk_mul_f32 v[72:73], v[72:73], v[88:89]
	v_pk_mul_f32 v[70:71], v[70:71], v[76:77]
	v_pk_mul_f32 v[68:69], v[68:69], v[88:89]
	s_and_b64 vcc, exec, s[4:5]
	v_cvt_pk_bf16_f32 v76, v72, v73
	v_cvt_pk_bf16_f32 v77, v74, v75
	v_cvt_pk_bf16_f32 v78, v68, v69
	v_cvt_pk_bf16_f32 v79, v70, v71
	global_store_dwordx4 v[86:87], v[76:79], off offset:256 sc1
	s_cbranch_vccnz .LBB0_1150
	global_store_dwordx4 v[84:85], v[72:75], off offset:512 nt
	global_store_dwordx4 v[84:85], v[68:71], off offset:528 nt
.LBB0_1150:
	ds_read_b32 v72, v158
	s_nop 0
	v_lshlrev_b64 v[68:69], 9, v[148:149]
	v_or_b32_e32 v68, v68, v165
	v_lshl_add_u64 v[68:69], v[68:69], 0, s[26:27]
	v_lshl_add_u64 v[70:71], v[68:69], 1, s[48:49]
	s_waitcnt lgkmcnt(0)
	v_mul_f32_e32 v72, v166, v72
	v_lshl_add_u64 v[68:69], v[68:69], 2, s[58:59]
	v_pk_mul_f32 v[66:67], v[66:67], v[72:73] op_sel_hi:[1,0]
	v_pk_mul_f32 v[64:65], v[64:65], v[72:73] op_sel_hi:[1,0]
	v_pk_mul_f32 v[62:63], v[62:63], v[72:73] op_sel_hi:[1,0]
	v_pk_mul_f32 v[60:61], v[60:61], v[72:73] op_sel_hi:[1,0]
	s_and_b64 vcc, exec, s[4:5]
	v_cvt_pk_bf16_f32 v74, v64, v65
	v_cvt_pk_bf16_f32 v75, v66, v67
	v_cvt_pk_bf16_f32 v76, v60, v61
	v_cvt_pk_bf16_f32 v77, v62, v63
	global_store_dwordx4 v[70:71], v[74:77], off sc1
	s_cbranch_vccnz .LBB0_1152
	global_store_dwordx4 v[68:69], v[64:67], off nt
	global_store_dwordx4 v[68:69], v[60:63], off offset:16 nt
.LBB0_1152:
	v_mov_b32_e32 v73, v72
	s_nop 0
	v_mov_b32_e32 v60, v72
	v_mov_b32_e32 v61, v72
	v_pk_mul_f32 v[58:59], v[58:59], v[60:61]
	v_pk_mul_f32 v[56:57], v[56:57], v[72:73]
	v_pk_mul_f32 v[54:55], v[54:55], v[60:61]
	v_pk_mul_f32 v[52:53], v[52:53], v[72:73]
	s_and_b64 vcc, exec, s[4:5]
	v_cvt_pk_bf16_f32 v60, v56, v57
	v_cvt_pk_bf16_f32 v61, v58, v59
	v_cvt_pk_bf16_f32 v62, v52, v53
	v_cvt_pk_bf16_f32 v63, v54, v55
	global_store_dwordx4 v[70:71], v[60:63], off offset:256 sc1
	s_cbranch_vccnz .LBB0_1154
	global_store_dwordx4 v[68:69], v[56:59], off offset:512 nt
	global_store_dwordx4 v[68:69], v[52:55], off offset:528 nt
.LBB0_1154:
	ds_read_b32 v56, v157 offset:576
	s_nop 0
	v_lshlrev_b64 v[52:53], 9, v[148:149]
	v_or_b32_e32 v52, v52, v165
	v_lshl_add_u64 v[52:53], v[52:53], 0, s[28:29]
	v_lshl_add_u64 v[54:55], v[52:53], 1, s[48:49]
	s_waitcnt lgkmcnt(0)
	v_mul_f32_e32 v56, v166, v56
	v_lshl_add_u64 v[52:53], v[52:53], 2, s[58:59]
	v_pk_mul_f32 v[50:51], v[50:51], v[56:57] op_sel_hi:[1,0]
	v_pk_mul_f32 v[48:49], v[48:49], v[56:57] op_sel_hi:[1,0]
	v_pk_mul_f32 v[46:47], v[46:47], v[56:57] op_sel_hi:[1,0]
	v_pk_mul_f32 v[44:45], v[44:45], v[56:57] op_sel_hi:[1,0]
	s_and_b64 vcc, exec, s[4:5]
	v_cvt_pk_bf16_f32 v58, v48, v49
	v_cvt_pk_bf16_f32 v59, v50, v51
	v_cvt_pk_bf16_f32 v60, v44, v45
	v_cvt_pk_bf16_f32 v61, v46, v47
	global_store_dwordx4 v[54:55], v[58:61], off sc1
	s_cbranch_vccnz .LBB0_1156
	global_store_dwordx4 v[52:53], v[48:51], off nt
	global_store_dwordx4 v[52:53], v[44:47], off offset:16 nt
.LBB0_1156:
	v_mov_b32_e32 v57, v56
	s_nop 0
	v_mov_b32_e32 v44, v56
	v_mov_b32_e32 v45, v56
	v_pk_mul_f32 v[42:43], v[42:43], v[44:45]
	v_pk_mul_f32 v[40:41], v[40:41], v[56:57]
	v_pk_mul_f32 v[38:39], v[38:39], v[44:45]
	v_pk_mul_f32 v[36:37], v[36:37], v[56:57]
	s_and_b64 vcc, exec, s[4:5]
	v_cvt_pk_bf16_f32 v44, v40, v41
	v_cvt_pk_bf16_f32 v45, v42, v43
	v_cvt_pk_bf16_f32 v46, v36, v37
	v_cvt_pk_bf16_f32 v47, v38, v39
	global_store_dwordx4 v[54:55], v[44:47], off offset:256 sc1
	s_cbranch_vccnz .LBB0_1158
	global_store_dwordx4 v[52:53], v[40:43], off offset:512 nt
	global_store_dwordx4 v[52:53], v[36:39], off offset:528 nt
.LBB0_1158:
	ds_read_b32 v40, v157 offset:640
	s_nop 0
	v_lshlrev_b64 v[36:37], 9, v[148:149]
	v_or_b32_e32 v36, v36, v165
	v_lshl_add_u64 v[36:37], v[36:37], 0, s[30:31]
	v_lshl_add_u64 v[38:39], v[36:37], 1, s[48:49]
	s_waitcnt lgkmcnt(0)
	v_mul_f32_e32 v40, v166, v40
	v_lshl_add_u64 v[36:37], v[36:37], 2, s[58:59]
	v_pk_mul_f32 v[34:35], v[34:35], v[40:41] op_sel_hi:[1,0]
	v_pk_mul_f32 v[32:33], v[32:33], v[40:41] op_sel_hi:[1,0]
	v_pk_mul_f32 v[30:31], v[30:31], v[40:41] op_sel_hi:[1,0]
	v_pk_mul_f32 v[28:29], v[28:29], v[40:41] op_sel_hi:[1,0]
	s_and_b64 vcc, exec, s[4:5]
	v_cvt_pk_bf16_f32 v42, v32, v33
	v_cvt_pk_bf16_f32 v43, v34, v35
	v_cvt_pk_bf16_f32 v44, v28, v29
	v_cvt_pk_bf16_f32 v45, v30, v31
	global_store_dwordx4 v[38:39], v[42:45], off sc1
	s_cbranch_vccnz .LBB0_1160
	global_store_dwordx4 v[36:37], v[32:35], off nt
	global_store_dwordx4 v[36:37], v[28:31], off offset:16 nt
.LBB0_1160:
	v_mov_b32_e32 v41, v40
	s_nop 0
	v_mov_b32_e32 v28, v40
	v_mov_b32_e32 v29, v40
	v_pk_mul_f32 v[26:27], v[26:27], v[28:29]
	v_pk_mul_f32 v[24:25], v[24:25], v[40:41]
	v_pk_mul_f32 v[22:23], v[22:23], v[28:29]
	v_pk_mul_f32 v[20:21], v[20:21], v[40:41]
	s_and_b64 vcc, exec, s[4:5]
	v_cvt_pk_bf16_f32 v28, v24, v25
	v_cvt_pk_bf16_f32 v29, v26, v27
	v_cvt_pk_bf16_f32 v30, v20, v21
	v_cvt_pk_bf16_f32 v31, v22, v23
	global_store_dwordx4 v[38:39], v[28:31], off offset:256 sc1
	s_cbranch_vccnz .LBB0_1162
	global_store_dwordx4 v[36:37], v[24:27], off offset:512 nt
	global_store_dwordx4 v[36:37], v[20:23], off offset:528 nt
.LBB0_1162:
	ds_read_b32 v24, v157 offset:704
	s_nop 0
	v_lshlrev_b64 v[20:21], 9, v[148:149]
	v_or_b32_e32 v20, v20, v165
	v_lshl_add_u64 v[20:21], v[20:21], 0, s[34:35]
	v_lshl_add_u64 v[22:23], v[20:21], 1, s[48:49]
	s_waitcnt lgkmcnt(0)
	v_mul_f32_e32 v24, v166, v24
	v_lshl_add_u64 v[20:21], v[20:21], 2, s[58:59]
	v_pk_mul_f32 v[18:19], v[18:19], v[24:25] op_sel_hi:[1,0]
	v_pk_mul_f32 v[16:17], v[16:17], v[24:25] op_sel_hi:[1,0]
	v_pk_mul_f32 v[14:15], v[14:15], v[24:25] op_sel_hi:[1,0]
	v_pk_mul_f32 v[12:13], v[12:13], v[24:25] op_sel_hi:[1,0]
	s_and_b64 vcc, exec, s[4:5]
	v_cvt_pk_bf16_f32 v26, v16, v17
	v_cvt_pk_bf16_f32 v27, v18, v19
	v_cvt_pk_bf16_f32 v28, v12, v13
	v_cvt_pk_bf16_f32 v29, v14, v15
	global_store_dwordx4 v[22:23], v[26:29], off sc1
	s_cbranch_vccnz .LBB0_1164
	global_store_dwordx4 v[20:21], v[16:19], off nt
	global_store_dwordx4 v[20:21], v[12:15], off offset:16 nt
.LBB0_1164:
	v_mov_b32_e32 v25, v24
	s_nop 0
	v_mov_b32_e32 v12, v24
	v_mov_b32_e32 v13, v24
	v_pk_mul_f32 v[10:11], v[10:11], v[12:13]
	v_pk_mul_f32 v[8:9], v[8:9], v[24:25]
	v_pk_mul_f32 v[6:7], v[6:7], v[12:13]
	v_pk_mul_f32 v[4:5], v[4:5], v[24:25]
	s_and_b64 vcc, exec, s[4:5]
	v_cvt_pk_bf16_f32 v12, v8, v9
	v_cvt_pk_bf16_f32 v13, v10, v11
	v_cvt_pk_bf16_f32 v14, v4, v5
	v_cvt_pk_bf16_f32 v15, v6, v7
	global_store_dwordx4 v[22:23], v[12:15], off offset:256 sc1
	s_cbranch_vccnz .LBB0_1166
	global_store_dwordx4 v[20:21], v[8:11], off offset:512 nt
	global_store_dwordx4 v[20:21], v[4:7], off offset:528 nt

.LBB0_1646:
	s_or_b64 exec, exec, s[12:13]
	v_lshl_add_u64 v[162:163], v[210:211], 2, s[52:53]
	s_mov_b64 s[4:5], 0x1000
	v_lshl_add_u64 v[164:165], v[162:163], 0, s[4:5]
	v_add_co_u32_e32 v162, vcc, 0x1000, v162
	s_waitcnt vmcnt(0) lgkmcnt(0)
	s_barrier
	s_nop 0
	v_addc_co_u32_e32 v163, vcc, 0, v163, vcc
	global_load_dwordx4 v[174:177], v[164:165], off offset:16
	global_load_dwordx4 v[166:169], v[164:165], off offset:512
	global_load_dwordx4 v[178:181], v[162:163], off
	s_nop 0
	global_load_dwordx4 v[162:165], v[164:165], off offset:528
	v_lshl_add_u32 v225, v216, 2, 0
	ds_read_b32 v234, v225 offset:4096
	s_waitcnt vmcnt(0)
	v_lshlrev_b32_e32 v226, 16, v206
	v_and_b32_e32 v227, 0xffff0000, v206
	v_lshlrev_b32_e32 v206, 16, v207
	v_and_b32_e32 v207, 0xffff0000, v207
	v_lshlrev_b32_e32 v228, 16, v208
	v_and_b32_e32 v229, 0xffff0000, v208
	v_lshlrev_b32_e32 v208, 16, v209
	v_and_b32_e32 v209, 0xffff0000, v209
	v_lshlrev_b32_e32 v230, 16, v202
	v_and_b32_e32 v231, 0xffff0000, v202
	v_lshlrev_b32_e32 v202, 16, v203
	v_and_b32_e32 v203, 0xffff0000, v203
	v_lshlrev_b32_e32 v232, 16, v204
	v_and_b32_e32 v233, 0xffff0000, v204
	v_lshlrev_b32_e32 v204, 16, v205
	v_and_b32_e32 v205, 0xffff0000, v205
	v_add_u32_e32 v214, s20, v216
	v_ashrrev_i32_e32 v215, 31, v214
	v_lshlrev_b64 v[236:237], 11, v[214:215]
	s_lshl_b32 s4, s6, 2
	s_mov_b32 s11, 0
	s_ashr_i32 s5, s4, 31
	v_pk_mul_f32 v[128:129], v[128:129], v[176:177]
	v_pk_mul_f32 v[126:127], v[126:127], v[174:175]
	v_pk_mul_f32 v[120:121], v[120:121], v[168:169]
	v_pk_mul_f32 v[118:119], v[118:119], v[166:167]
	v_pk_mul_f32 v[124:125], v[124:125], v[180:181]
	v_pk_mul_f32 v[122:123], v[122:123], v[178:179]
	v_pk_mul_f32 v[116:117], v[116:117], v[164:165]
	v_pk_mul_f32 v[114:115], v[114:115], v[162:163]
	s_waitcnt lgkmcnt(0)
	v_pk_fma_f32 v[126:127], v[126:127], v[234:235], v[228:229] op_sel_hi:[1,0,1]
	v_pk_fma_f32 v[128:129], v[128:129], v[234:235], v[208:209] op_sel_hi:[1,0,1]
	v_pk_fma_f32 v[118:119], v[118:119], v[234:235], v[230:231] op_sel_hi:[1,0,1]
	v_pk_fma_f32 v[120:121], v[120:121], v[234:235], v[202:203] op_sel_hi:[1,0,1]
	v_pk_fma_f32 v[124:125], v[124:125], v[234:235], v[206:207] op_sel_hi:[1,0,1]
	v_pk_fma_f32 v[122:123], v[122:123], v[234:235], v[226:227] op_sel_hi:[1,0,1]
	v_pk_fma_f32 v[202:203], v[114:115], v[234:235], v[232:233] op_sel_hi:[1,0,1]
	v_pk_fma_f32 v[204:205], v[116:117], v[234:235], v[204:205] op_sel_hi:[1,0,1]
	v_mul_f32_e32 v206, v127, v127
	v_mul_f32_e32 v207, v129, v129
	v_mul_f32_e32 v208, v119, v119
	v_mul_f32_e32 v209, v121, v121
	v_mul_f32_e32 v226, v123, v123
	v_mul_f32_e32 v227, v125, v125
	v_cvt_pk_bf16_f32 v114, v122, v123
	v_cvt_pk_bf16_f32 v115, v124, v125
	v_mul_f32_e32 v123, v203, v203
	v_mul_f32_e32 v125, v205, v205
	v_fmac_f32_e32 v206, v126, v126
	v_fmac_f32_e32 v207, v128, v128
	v_fmac_f32_e32 v208, v118, v118
	v_fmac_f32_e32 v209, v120, v120
	v_fmac_f32_e32 v226, v122, v122
	v_fmac_f32_e32 v227, v124, v124
	v_fmac_f32_e32 v123, v202, v202
	v_fmac_f32_e32 v125, v204, v204
	v_cvt_pk_bf16_f32 v116, v126, v127
	v_add_f32_e32 v122, v206, v207
	v_add_f32_e32 v124, v208, v209
	v_add_f32_e32 v126, v226, v227
	v_add_f32_e32 v123, v123, v125
	v_add_f32_e32 v122, v126, v122
	v_add_f32_e32 v123, v124, v123
	v_add_f32_e32 v124, v122, v123
	ds_bpermute_b32 v125, v220, v124
	v_lshl_add_u64 v[122:123], s[62:63], 0, v[236:237]
	v_lshl_add_u64 v[122:123], v[210:211], 1, v[122:123]
	v_cvt_pk_bf16_f32 v117, v128, v129
	global_store_dwordx4 v[122:123], v[114:117], off sc1
	s_waitcnt lgkmcnt(0)
	s_nop 0
	v_add_f32_e32 v114, v124, v125
	ds_bpermute_b32 v115, v221, v114
	v_cvt_pk_bf16_f32 v116, v118, v119
	v_cvt_pk_bf16_f32 v117, v120, v121
	v_cvt_pk_bf16_f32 v118, v202, v203
	v_cvt_pk_bf16_f32 v119, v204, v205
	global_store_dwordx4 v[122:123], v[116:119], off offset:256 sc1
	s_and_saveexec_b64 s[6:7], s[0:1]
	s_cbranch_execz .LBB0_1648
	s_waitcnt lgkmcnt(0)
	v_add_f32_e32 v116, v114, v115
	v_lshlrev_b64 v[114:115], 6, v[214:215]
	v_lshl_add_u64 v[114:115], s[86:87], 0, v[114:115]
	v_lshl_add_u64 v[114:115], s[4:5], 2, v[114:115]
	v_lshl_add_u64 v[114:115], v[114:115], 0, s[10:11]
	global_store_dword v[114:115], v116, off
.LBB0_1648:
	s_or_b64 exec, exec, s[6:7]
	ds_read_b32 v116, v225 offset:4160
	v_lshlrev_b32_e32 v120, 16, v198
	v_and_b32_e32 v121, 0xffff0000, v198
	v_lshlrev_b32_e32 v122, 16, v199
	v_and_b32_e32 v123, 0xffff0000, v199
	v_pk_mul_f32 v[112:113], v[112:113], v[180:181]
	v_pk_mul_f32 v[110:111], v[110:111], v[178:179]
	v_lshlrev_b32_e32 v124, 16, v200
	v_and_b32_e32 v125, 0xffff0000, v200
	v_lshlrev_b32_e32 v126, 16, v201
	v_and_b32_e32 v127, 0xffff0000, v201
	s_waitcnt lgkmcnt(0)
	v_pk_fma_f32 v[112:113], v[112:113], v[116:117], v[122:123] op_sel_hi:[1,0,1]
	v_pk_fma_f32 v[110:111], v[110:111], v[116:117], v[120:121] op_sel_hi:[1,0,1]
	v_pk_mul_f32 v[108:109], v[108:109], v[176:177]
	v_pk_mul_f32 v[106:107], v[106:107], v[174:175]
	v_pk_fma_f32 v[120:121], v[108:109], v[116:117], v[126:127] op_sel_hi:[1,0,1]
	v_pk_fma_f32 v[108:109], v[106:107], v[116:117], v[124:125] op_sel_hi:[1,0,1]
	v_mul_f32_e32 v106, v111, v111
	v_mul_f32_e32 v107, v113, v113
	v_fmac_f32_e32 v106, v110, v110
	v_fmac_f32_e32 v107, v112, v112
	v_add_f32_e32 v106, v106, v107
	v_mul_f32_e32 v107, v109, v109
	v_mul_f32_e32 v117, v121, v121
	v_fmac_f32_e32 v107, v108, v108
	v_fmac_f32_e32 v117, v120, v120
	v_add_f32_e32 v107, v107, v117
	v_add_f32_e32 v117, v106, v107
	v_cvt_pk_bf16_f32 v106, v110, v111
	v_cvt_pk_bf16_f32 v107, v112, v113
	v_lshlrev_b32_e32 v110, 16, v194
	v_and_b32_e32 v111, 0xffff0000, v194
	v_lshlrev_b32_e32 v112, 16, v195
	v_and_b32_e32 v113, 0xffff0000, v195
	v_pk_mul_f32 v[104:105], v[104:105], v[168:169]
	v_pk_mul_f32 v[102:103], v[102:103], v[166:167]
	v_cvt_pk_bf16_f32 v108, v108, v109
	v_cvt_pk_bf16_f32 v109, v120, v121
	v_lshlrev_b32_e32 v120, 16, v196
	v_and_b32_e32 v121, 0xffff0000, v196
	v_pk_fma_f32 v[104:105], v[104:105], v[116:117], v[112:113] op_sel_hi:[1,0,1]
	v_pk_fma_f32 v[102:103], v[102:103], v[116:117], v[110:111] op_sel_hi:[1,0,1]
	v_pk_mul_f32 v[98:99], v[98:99], v[162:163]
	v_lshlrev_b32_e32 v122, 16, v197
	v_and_b32_e32 v123, 0xffff0000, v197
	v_pk_mul_f32 v[100:101], v[100:101], v[164:165]
	v_pk_fma_f32 v[112:113], v[98:99], v[116:117], v[120:121] op_sel_hi:[1,0,1]
	v_mul_f32_e32 v98, v103, v103
	v_mul_f32_e32 v99, v105, v105
	v_pk_fma_f32 v[110:111], v[100:101], v[116:117], v[122:123] op_sel_hi:[1,0,1]
	v_fmac_f32_e32 v98, v102, v102
	v_fmac_f32_e32 v99, v104, v104
	v_add_f32_e32 v98, v98, v99
	v_mul_f32_e32 v99, v113, v113
	v_mul_f32_e32 v100, v111, v111
	v_fmac_f32_e32 v99, v112, v112
	v_fmac_f32_e32 v100, v110, v110
	v_add_f32_e32 v99, v99, v100
	v_add_f32_e32 v98, v98, v99
	v_add_f32_e32 v101, v117, v98
	ds_bpermute_b32 v120, v220, v101
	v_add3_u32 v114, s20, v216, 16
	v_ashrrev_i32_e32 v115, 31, v114
	v_lshlrev_b64 v[118:119], 11, v[114:115]
	v_lshl_add_u64 v[98:99], s[62:63], 0, v[118:119]
	v_lshl_add_u64 v[116:117], v[210:211], 1, v[98:99]
	s_waitcnt lgkmcnt(0)
	v_add_f32_e32 v98, v101, v120
	ds_bpermute_b32 v99, v221, v98
	global_store_dwordx4 v[116:117], v[106:109], off sc1
	v_cvt_pk_bf16_f32 v100, v102, v103
	v_cvt_pk_bf16_f32 v101, v104, v105
	v_cvt_pk_bf16_f32 v102, v112, v113
	v_cvt_pk_bf16_f32 v103, v110, v111
	global_store_dwordx4 v[116:117], v[100:103], off offset:256 sc1
	s_and_saveexec_b64 s[6:7], s[0:1]
	s_cbranch_execz .LBB0_1650
	s_waitcnt lgkmcnt(0)
	v_add_f32_e32 v100, v98, v99
	v_lshlrev_b64 v[98:99], 6, v[114:115]
	v_lshl_add_u64 v[98:99], s[86:87], 0, v[98:99]
	v_lshl_add_u64 v[98:99], s[4:5], 2, v[98:99]
	v_lshl_add_u64 v[98:99], v[98:99], 0, s[10:11]
	global_store_dword v[98:99], v100, off
.LBB0_1650:
	s_or_b64 exec, exec, s[6:7]
	ds_read_b32 v100, v225 offset:4224
	v_lshlrev_b32_e32 v104, 16, v190
	v_and_b32_e32 v105, 0xffff0000, v190
	v_lshlrev_b32_e32 v106, 16, v191
	v_and_b32_e32 v107, 0xffff0000, v191
	v_pk_mul_f32 v[96:97], v[96:97], v[180:181]
	v_pk_mul_f32 v[94:95], v[94:95], v[178:179]
	v_lshlrev_b32_e32 v108, 16, v192
	v_and_b32_e32 v109, 0xffff0000, v192
	v_lshlrev_b32_e32 v110, 16, v193
	v_and_b32_e32 v111, 0xffff0000, v193
	s_waitcnt lgkmcnt(0)
	v_pk_fma_f32 v[96:97], v[96:97], v[100:101], v[106:107] op_sel_hi:[1,0,1]
	v_pk_fma_f32 v[94:95], v[94:95], v[100:101], v[104:105] op_sel_hi:[1,0,1]
	v_pk_mul_f32 v[92:93], v[92:93], v[176:177]
	v_pk_mul_f32 v[90:91], v[90:91], v[174:175]
	v_pk_fma_f32 v[104:105], v[92:93], v[100:101], v[110:111] op_sel_hi:[1,0,1]
	v_pk_fma_f32 v[92:93], v[90:91], v[100:101], v[108:109] op_sel_hi:[1,0,1]
	v_mul_f32_e32 v90, v95, v95
	v_mul_f32_e32 v91, v97, v97
	v_fmac_f32_e32 v90, v94, v94
	v_fmac_f32_e32 v91, v96, v96
	v_add_f32_e32 v90, v90, v91
	v_mul_f32_e32 v91, v93, v93
	v_mul_f32_e32 v101, v105, v105
	v_fmac_f32_e32 v91, v92, v92
	v_fmac_f32_e32 v101, v104, v104
	v_add_f32_e32 v91, v91, v101
	v_add_f32_e32 v101, v90, v91
	v_cvt_pk_bf16_f32 v90, v94, v95
	v_cvt_pk_bf16_f32 v91, v96, v97
	v_lshlrev_b32_e32 v94, 16, v186
	v_and_b32_e32 v95, 0xffff0000, v186
	v_lshlrev_b32_e32 v96, 16, v187
	v_and_b32_e32 v97, 0xffff0000, v187
	v_pk_mul_f32 v[88:89], v[88:89], v[168:169]
	v_pk_mul_f32 v[86:87], v[86:87], v[166:167]
	v_cvt_pk_bf16_f32 v92, v92, v93
	v_cvt_pk_bf16_f32 v93, v104, v105
	v_lshlrev_b32_e32 v104, 16, v188
	v_and_b32_e32 v105, 0xffff0000, v188
	v_pk_fma_f32 v[88:89], v[88:89], v[100:101], v[96:97] op_sel_hi:[1,0,1]
	v_pk_fma_f32 v[86:87], v[86:87], v[100:101], v[94:95] op_sel_hi:[1,0,1]
	v_pk_mul_f32 v[82:83], v[82:83], v[162:163]
	v_lshlrev_b32_e32 v106, 16, v189
	v_and_b32_e32 v107, 0xffff0000, v189
	v_pk_mul_f32 v[84:85], v[84:85], v[164:165]
	v_pk_fma_f32 v[96:97], v[82:83], v[100:101], v[104:105] op_sel_hi:[1,0,1]
	v_mul_f32_e32 v82, v87, v87
	v_mul_f32_e32 v83, v89, v89
	v_pk_fma_f32 v[94:95], v[84:85], v[100:101], v[106:107] op_sel_hi:[1,0,1]
	v_fmac_f32_e32 v82, v86, v86
	v_fmac_f32_e32 v83, v88, v88
	v_add_f32_e32 v82, v82, v83
	v_mul_f32_e32 v83, v97, v97
	v_mul_f32_e32 v84, v95, v95
	v_fmac_f32_e32 v83, v96, v96
	v_fmac_f32_e32 v84, v94, v94
	v_add_f32_e32 v83, v83, v84
	v_add_f32_e32 v82, v82, v83
	v_add_f32_e32 v85, v101, v82
	ds_bpermute_b32 v104, v220, v85
	v_add3_u32 v98, s20, v216, 32
	v_ashrrev_i32_e32 v99, 31, v98
	v_lshlrev_b64 v[102:103], 11, v[98:99]
	v_lshl_add_u64 v[82:83], s[62:63], 0, v[102:103]
	v_lshl_add_u64 v[100:101], v[210:211], 1, v[82:83]
	s_waitcnt lgkmcnt(0)
	v_add_f32_e32 v82, v85, v104
	ds_bpermute_b32 v83, v221, v82
	global_store_dwordx4 v[100:101], v[90:93], off sc1
	v_cvt_pk_bf16_f32 v84, v86, v87
	v_cvt_pk_bf16_f32 v85, v88, v89
	v_cvt_pk_bf16_f32 v86, v96, v97
	v_cvt_pk_bf16_f32 v87, v94, v95
	global_store_dwordx4 v[100:101], v[84:87], off offset:256 sc1
	s_and_saveexec_b64 s[6:7], s[0:1]
	s_cbranch_execz .LBB0_1652
	s_waitcnt lgkmcnt(0)
	v_add_f32_e32 v84, v82, v83
	v_lshlrev_b64 v[82:83], 6, v[98:99]
	v_lshl_add_u64 v[82:83], s[86:87], 0, v[82:83]
	v_lshl_add_u64 v[82:83], s[4:5], 2, v[82:83]
	v_lshl_add_u64 v[82:83], v[82:83], 0, s[10:11]
	global_store_dword v[82:83], v84, off
.LBB0_1652:
	s_or_b64 exec, exec, s[6:7]
	ds_read_b32 v84, v225 offset:4288
	v_lshlrev_b32_e32 v88, 16, v182
	v_and_b32_e32 v89, 0xffff0000, v182
	v_lshlrev_b32_e32 v90, 16, v183
	v_and_b32_e32 v91, 0xffff0000, v183
	v_pk_mul_f32 v[80:81], v[80:81], v[180:181]
	v_pk_mul_f32 v[78:79], v[78:79], v[178:179]
	v_lshlrev_b32_e32 v92, 16, v184
	v_and_b32_e32 v93, 0xffff0000, v184
	v_lshlrev_b32_e32 v94, 16, v185
	v_and_b32_e32 v95, 0xffff0000, v185
	s_waitcnt lgkmcnt(0)
	v_pk_fma_f32 v[80:81], v[80:81], v[84:85], v[90:91] op_sel_hi:[1,0,1]
	v_pk_fma_f32 v[78:79], v[78:79], v[84:85], v[88:89] op_sel_hi:[1,0,1]
	v_pk_mul_f32 v[76:77], v[76:77], v[176:177]
	v_pk_mul_f32 v[74:75], v[74:75], v[174:175]
	v_pk_fma_f32 v[88:89], v[76:77], v[84:85], v[94:95] op_sel_hi:[1,0,1]
	v_pk_fma_f32 v[76:77], v[74:75], v[84:85], v[92:93] op_sel_hi:[1,0,1]
	v_mul_f32_e32 v74, v79, v79
	v_mul_f32_e32 v75, v81, v81
	v_fmac_f32_e32 v74, v78, v78
	v_fmac_f32_e32 v75, v80, v80
	v_add_f32_e32 v74, v74, v75
	v_mul_f32_e32 v75, v77, v77
	v_mul_f32_e32 v85, v89, v89
	v_fmac_f32_e32 v75, v76, v76
	v_fmac_f32_e32 v85, v88, v88
	v_add_f32_e32 v75, v75, v85
	v_add_f32_e32 v85, v74, v75
	v_cvt_pk_bf16_f32 v74, v78, v79
	v_cvt_pk_bf16_f32 v75, v80, v81
	v_lshlrev_b32_e32 v78, 16, v170
	v_and_b32_e32 v79, 0xffff0000, v170
	v_lshlrev_b32_e32 v80, 16, v171
	v_and_b32_e32 v81, 0xffff0000, v171
	v_pk_mul_f32 v[72:73], v[72:73], v[168:169]
	v_pk_mul_f32 v[70:71], v[70:71], v[166:167]
	v_cvt_pk_bf16_f32 v76, v76, v77
	v_cvt_pk_bf16_f32 v77, v88, v89
	v_lshlrev_b32_e32 v88, 16, v172
	v_and_b32_e32 v89, 0xffff0000, v172
	v_pk_fma_f32 v[72:73], v[72:73], v[84:85], v[80:81] op_sel_hi:[1,0,1]
	v_pk_fma_f32 v[70:71], v[70:71], v[84:85], v[78:79] op_sel_hi:[1,0,1]
	v_pk_mul_f32 v[66:67], v[66:67], v[162:163]
	v_lshlrev_b32_e32 v90, 16, v173
	v_and_b32_e32 v91, 0xffff0000, v173
	v_pk_mul_f32 v[68:69], v[68:69], v[164:165]
	v_pk_fma_f32 v[80:81], v[66:67], v[84:85], v[88:89] op_sel_hi:[1,0,1]
	v_mul_f32_e32 v66, v71, v71
	v_mul_f32_e32 v67, v73, v73
	v_pk_fma_f32 v[78:79], v[68:69], v[84:85], v[90:91] op_sel_hi:[1,0,1]
	v_fmac_f32_e32 v66, v70, v70
	v_fmac_f32_e32 v67, v72, v72
	v_add_f32_e32 v66, v66, v67
	v_mul_f32_e32 v67, v81, v81
	v_mul_f32_e32 v68, v79, v79
	v_fmac_f32_e32 v67, v80, v80
	v_fmac_f32_e32 v68, v78, v78
	v_add_f32_e32 v67, v67, v68
	v_add_f32_e32 v66, v66, v67
	v_add_f32_e32 v69, v85, v66
	ds_bpermute_b32 v88, v220, v69
	v_add3_u32 v82, s20, v216, 48
	v_ashrrev_i32_e32 v83, 31, v82
	v_lshlrev_b64 v[86:87], 11, v[82:83]
	v_lshl_add_u64 v[66:67], s[62:63], 0, v[86:87]
	v_lshl_add_u64 v[84:85], v[210:211], 1, v[66:67]
	s_waitcnt lgkmcnt(0)
	v_add_f32_e32 v66, v69, v88
	ds_bpermute_b32 v67, v221, v66
	global_store_dwordx4 v[84:85], v[74:77], off sc1
	v_cvt_pk_bf16_f32 v68, v70, v71
	v_cvt_pk_bf16_f32 v69, v72, v73
	v_cvt_pk_bf16_f32 v70, v80, v81
	v_cvt_pk_bf16_f32 v71, v78, v79
	global_store_dwordx4 v[84:85], v[68:71], off offset:256 sc1
	s_and_saveexec_b64 s[6:7], s[0:1]
	s_cbranch_execz .LBB0_1654
	s_waitcnt lgkmcnt(0)
	v_add_f32_e32 v68, v66, v67
	v_lshlrev_b64 v[66:67], 6, v[82:83]
	v_lshl_add_u64 v[66:67], s[86:87], 0, v[66:67]
	v_lshl_add_u64 v[66:67], s[4:5], 2, v[66:67]
	v_lshl_add_u64 v[66:67], v[66:67], 0, s[10:11]
	global_store_dword v[66:67], v68, off
.LBB0_1654:
	s_or_b64 exec, exec, s[6:7]
	ds_read_b32 v68, v225 offset:4608
	v_lshlrev_b32_e32 v72, 16, v158
	v_and_b32_e32 v73, 0xffff0000, v158
	v_lshlrev_b32_e32 v74, 16, v159
	v_and_b32_e32 v75, 0xffff0000, v159
	v_pk_mul_f32 v[64:65], v[64:65], v[180:181]
	v_pk_mul_f32 v[62:63], v[62:63], v[178:179]
	v_lshlrev_b32_e32 v76, 16, v160
	v_and_b32_e32 v77, 0xffff0000, v160
	v_lshlrev_b32_e32 v78, 16, v161
	v_and_b32_e32 v79, 0xffff0000, v161
	s_waitcnt lgkmcnt(0)
	v_pk_fma_f32 v[64:65], v[64:65], v[68:69], v[74:75] op_sel_hi:[1,0,1]
	v_pk_fma_f32 v[62:63], v[62:63], v[68:69], v[72:73] op_sel_hi:[1,0,1]
	v_pk_mul_f32 v[60:61], v[60:61], v[176:177]
	v_pk_mul_f32 v[58:59], v[58:59], v[174:175]
	v_pk_fma_f32 v[72:73], v[60:61], v[68:69], v[78:79] op_sel_hi:[1,0,1]
	v_pk_fma_f32 v[60:61], v[58:59], v[68:69], v[76:77] op_sel_hi:[1,0,1]
	v_mul_f32_e32 v58, v63, v63
	v_mul_f32_e32 v59, v65, v65
	v_fmac_f32_e32 v58, v62, v62
	v_fmac_f32_e32 v59, v64, v64
	v_add_f32_e32 v58, v58, v59
	v_mul_f32_e32 v59, v61, v61
	v_mul_f32_e32 v69, v73, v73
	v_fmac_f32_e32 v59, v60, v60
	v_fmac_f32_e32 v69, v72, v72
	v_add_f32_e32 v59, v59, v69
	v_add_f32_e32 v69, v58, v59
	v_cvt_pk_bf16_f32 v58, v62, v63
	v_cvt_pk_bf16_f32 v59, v64, v65
	v_lshlrev_b32_e32 v62, 16, v154
	v_and_b32_e32 v63, 0xffff0000, v154
	v_lshlrev_b32_e32 v64, 16, v155
	v_and_b32_e32 v65, 0xffff0000, v155
	v_pk_mul_f32 v[56:57], v[56:57], v[168:169]
	v_pk_mul_f32 v[54:55], v[54:55], v[166:167]
	v_cvt_pk_bf16_f32 v60, v60, v61
	v_cvt_pk_bf16_f32 v61, v72, v73
	v_lshlrev_b32_e32 v72, 16, v156
	v_and_b32_e32 v73, 0xffff0000, v156
	v_pk_fma_f32 v[56:57], v[56:57], v[68:69], v[64:65] op_sel_hi:[1,0,1]
	v_pk_fma_f32 v[54:55], v[54:55], v[68:69], v[62:63] op_sel_hi:[1,0,1]
	v_pk_mul_f32 v[50:51], v[50:51], v[162:163]
	v_lshlrev_b32_e32 v74, 16, v157
	v_and_b32_e32 v75, 0xffff0000, v157
	v_pk_mul_f32 v[52:53], v[52:53], v[164:165]
	v_pk_fma_f32 v[64:65], v[50:51], v[68:69], v[72:73] op_sel_hi:[1,0,1]
	v_mul_f32_e32 v50, v55, v55
	v_mul_f32_e32 v51, v57, v57
	v_pk_fma_f32 v[62:63], v[52:53], v[68:69], v[74:75] op_sel_hi:[1,0,1]
	v_fmac_f32_e32 v50, v54, v54
	v_fmac_f32_e32 v51, v56, v56
	v_add_f32_e32 v50, v50, v51
	v_mul_f32_e32 v51, v65, v65
	v_mul_f32_e32 v52, v63, v63
	v_fmac_f32_e32 v51, v64, v64
	v_fmac_f32_e32 v52, v62, v62
	v_add_f32_e32 v51, v51, v52
	v_add_f32_e32 v50, v50, v51
	v_add_f32_e32 v53, v69, v50
	ds_bpermute_b32 v72, v220, v53
	v_add_u32_e32 v66, 0x80, v214
	v_ashrrev_i32_e32 v67, 31, v66
	v_lshlrev_b64 v[70:71], 11, v[66:67]
	v_lshl_add_u64 v[50:51], s[62:63], 0, v[70:71]
	v_lshl_add_u64 v[68:69], v[210:211], 1, v[50:51]
	s_waitcnt lgkmcnt(0)
	v_add_f32_e32 v50, v53, v72
	ds_bpermute_b32 v51, v221, v50
	global_store_dwordx4 v[68:69], v[58:61], off sc1
	v_cvt_pk_bf16_f32 v52, v54, v55
	v_cvt_pk_bf16_f32 v53, v56, v57
	v_cvt_pk_bf16_f32 v54, v64, v65
	v_cvt_pk_bf16_f32 v55, v62, v63
	global_store_dwordx4 v[68:69], v[52:55], off offset:256 sc1
	s_and_saveexec_b64 s[6:7], s[0:1]
	s_cbranch_execz .LBB0_1656
	s_waitcnt lgkmcnt(0)
	v_add_f32_e32 v52, v50, v51
	v_lshlrev_b64 v[50:51], 6, v[66:67]
	v_lshl_add_u64 v[50:51], s[86:87], 0, v[50:51]
	v_lshl_add_u64 v[50:51], s[4:5], 2, v[50:51]
	v_lshl_add_u64 v[50:51], v[50:51], 0, s[10:11]
	global_store_dword v[50:51], v52, off
.LBB0_1656:
	s_or_b64 exec, exec, s[6:7]
	ds_read_b32 v52, v225 offset:4672
	v_lshlrev_b32_e32 v56, 16, v150
	v_and_b32_e32 v57, 0xffff0000, v150
	v_lshlrev_b32_e32 v58, 16, v151
	v_and_b32_e32 v59, 0xffff0000, v151
	v_pk_mul_f32 v[48:49], v[48:49], v[180:181]
	v_pk_mul_f32 v[46:47], v[46:47], v[178:179]
	v_lshlrev_b32_e32 v60, 16, v152
	v_and_b32_e32 v61, 0xffff0000, v152
	v_lshlrev_b32_e32 v62, 16, v153
	v_and_b32_e32 v63, 0xffff0000, v153
	s_waitcnt lgkmcnt(0)
	v_pk_fma_f32 v[48:49], v[48:49], v[52:53], v[58:59] op_sel_hi:[1,0,1]
	v_pk_fma_f32 v[46:47], v[46:47], v[52:53], v[56:57] op_sel_hi:[1,0,1]
	v_pk_mul_f32 v[44:45], v[44:45], v[176:177]
	v_pk_mul_f32 v[42:43], v[42:43], v[174:175]
	v_pk_fma_f32 v[56:57], v[44:45], v[52:53], v[62:63] op_sel_hi:[1,0,1]
	v_pk_fma_f32 v[44:45], v[42:43], v[52:53], v[60:61] op_sel_hi:[1,0,1]
	v_mul_f32_e32 v42, v47, v47
	v_mul_f32_e32 v43, v49, v49
	v_fmac_f32_e32 v42, v46, v46
	v_fmac_f32_e32 v43, v48, v48
	v_add_f32_e32 v42, v42, v43
	v_mul_f32_e32 v43, v45, v45
	v_mul_f32_e32 v53, v57, v57
	v_fmac_f32_e32 v43, v44, v44
	v_fmac_f32_e32 v53, v56, v56
	v_add_f32_e32 v43, v43, v53
	v_add_f32_e32 v53, v42, v43
	v_cvt_pk_bf16_f32 v42, v46, v47
	v_cvt_pk_bf16_f32 v43, v48, v49
	v_lshlrev_b32_e32 v46, 16, v146
	v_and_b32_e32 v47, 0xffff0000, v146
	v_lshlrev_b32_e32 v48, 16, v147
	v_and_b32_e32 v49, 0xffff0000, v147
	v_pk_mul_f32 v[40:41], v[40:41], v[168:169]
	v_pk_mul_f32 v[38:39], v[38:39], v[166:167]
	v_cvt_pk_bf16_f32 v44, v44, v45
	v_cvt_pk_bf16_f32 v45, v56, v57
	v_lshlrev_b32_e32 v56, 16, v148
	v_and_b32_e32 v57, 0xffff0000, v148
	v_pk_fma_f32 v[40:41], v[40:41], v[52:53], v[48:49] op_sel_hi:[1,0,1]
	v_pk_fma_f32 v[38:39], v[38:39], v[52:53], v[46:47] op_sel_hi:[1,0,1]
	v_pk_mul_f32 v[34:35], v[34:35], v[162:163]
	v_lshlrev_b32_e32 v58, 16, v149
	v_and_b32_e32 v59, 0xffff0000, v149
	v_pk_mul_f32 v[36:37], v[36:37], v[164:165]
	v_pk_fma_f32 v[48:49], v[34:35], v[52:53], v[56:57] op_sel_hi:[1,0,1]
	v_mul_f32_e32 v34, v39, v39
	v_mul_f32_e32 v35, v41, v41
	v_pk_fma_f32 v[46:47], v[36:37], v[52:53], v[58:59] op_sel_hi:[1,0,1]
	v_fmac_f32_e32 v34, v38, v38
	v_fmac_f32_e32 v35, v40, v40
	v_add_f32_e32 v34, v34, v35
	v_mul_f32_e32 v35, v49, v49
	v_mul_f32_e32 v36, v47, v47
	v_fmac_f32_e32 v35, v48, v48
	v_fmac_f32_e32 v36, v46, v46
	v_add_f32_e32 v35, v35, v36
	v_add_f32_e32 v34, v34, v35
	v_add_f32_e32 v37, v53, v34
	ds_bpermute_b32 v56, v220, v37
	v_add_u32_e32 v50, 0x90, v214
	v_ashrrev_i32_e32 v51, 31, v50
	v_lshlrev_b64 v[54:55], 11, v[50:51]
	v_lshl_add_u64 v[34:35], s[62:63], 0, v[54:55]
	v_lshl_add_u64 v[52:53], v[210:211], 1, v[34:35]
	s_waitcnt lgkmcnt(0)
	v_add_f32_e32 v34, v37, v56
	ds_bpermute_b32 v35, v221, v34
	global_store_dwordx4 v[52:53], v[42:45], off sc1
	v_cvt_pk_bf16_f32 v36, v38, v39
	v_cvt_pk_bf16_f32 v37, v40, v41
	v_cvt_pk_bf16_f32 v38, v48, v49
	v_cvt_pk_bf16_f32 v39, v46, v47
	global_store_dwordx4 v[52:53], v[36:39], off offset:256 sc1
	s_and_saveexec_b64 s[6:7], s[0:1]
	s_cbranch_execz .LBB0_1658
	s_waitcnt lgkmcnt(0)
	v_add_f32_e32 v36, v34, v35
	v_lshlrev_b64 v[34:35], 6, v[50:51]
	v_lshl_add_u64 v[34:35], s[86:87], 0, v[34:35]
	v_lshl_add_u64 v[34:35], s[4:5], 2, v[34:35]
	v_lshl_add_u64 v[34:35], v[34:35], 0, s[10:11]
	global_store_dword v[34:35], v36, off
.LBB0_1658:
	s_or_b64 exec, exec, s[6:7]
	ds_read_b32 v36, v225 offset:4736
	v_lshlrev_b32_e32 v40, 16, v142
	v_and_b32_e32 v41, 0xffff0000, v142
	v_lshlrev_b32_e32 v42, 16, v143
	v_and_b32_e32 v43, 0xffff0000, v143
	v_pk_mul_f32 v[32:33], v[32:33], v[180:181]
	v_pk_mul_f32 v[30:31], v[30:31], v[178:179]
	v_lshlrev_b32_e32 v44, 16, v144
	v_and_b32_e32 v45, 0xffff0000, v144
	v_lshlrev_b32_e32 v46, 16, v145
	v_and_b32_e32 v47, 0xffff0000, v145
	s_waitcnt lgkmcnt(0)
	v_pk_fma_f32 v[32:33], v[32:33], v[36:37], v[42:43] op_sel_hi:[1,0,1]
	v_pk_fma_f32 v[30:31], v[30:31], v[36:37], v[40:41] op_sel_hi:[1,0,1]
	v_pk_mul_f32 v[28:29], v[28:29], v[176:177]
	v_pk_mul_f32 v[26:27], v[26:27], v[174:175]
	v_pk_fma_f32 v[40:41], v[28:29], v[36:37], v[46:47] op_sel_hi:[1,0,1]
	v_pk_fma_f32 v[28:29], v[26:27], v[36:37], v[44:45] op_sel_hi:[1,0,1]
	v_mul_f32_e32 v26, v31, v31
	v_mul_f32_e32 v27, v33, v33
	v_fmac_f32_e32 v26, v30, v30
	v_fmac_f32_e32 v27, v32, v32
	v_add_f32_e32 v26, v26, v27
	v_mul_f32_e32 v27, v29, v29
	v_mul_f32_e32 v37, v41, v41
	v_fmac_f32_e32 v27, v28, v28
	v_fmac_f32_e32 v37, v40, v40
	v_add_f32_e32 v27, v27, v37
	v_add_f32_e32 v37, v26, v27
	v_cvt_pk_bf16_f32 v26, v30, v31
	v_cvt_pk_bf16_f32 v27, v32, v33
	v_lshlrev_b32_e32 v30, 16, v138
	v_and_b32_e32 v31, 0xffff0000, v138
	v_lshlrev_b32_e32 v32, 16, v139
	v_and_b32_e32 v33, 0xffff0000, v139
	v_pk_mul_f32 v[24:25], v[24:25], v[168:169]
	v_pk_mul_f32 v[22:23], v[22:23], v[166:167]
	v_cvt_pk_bf16_f32 v28, v28, v29
	v_cvt_pk_bf16_f32 v29, v40, v41
	v_lshlrev_b32_e32 v40, 16, v140
	v_and_b32_e32 v41, 0xffff0000, v140
	v_pk_fma_f32 v[24:25], v[24:25], v[36:37], v[32:33] op_sel_hi:[1,0,1]
	v_pk_fma_f32 v[22:23], v[22:23], v[36:37], v[30:31] op_sel_hi:[1,0,1]
	v_pk_mul_f32 v[18:19], v[18:19], v[162:163]
	v_lshlrev_b32_e32 v42, 16, v141
	v_and_b32_e32 v43, 0xffff0000, v141
	v_pk_mul_f32 v[20:21], v[20:21], v[164:165]
	v_pk_fma_f32 v[32:33], v[18:19], v[36:37], v[40:41] op_sel_hi:[1,0,1]
	v_mul_f32_e32 v18, v23, v23
	v_mul_f32_e32 v19, v25, v25
	v_pk_fma_f32 v[30:31], v[20:21], v[36:37], v[42:43] op_sel_hi:[1,0,1]
	v_fmac_f32_e32 v18, v22, v22
	v_fmac_f32_e32 v19, v24, v24
	v_add_f32_e32 v18, v18, v19
	v_mul_f32_e32 v19, v33, v33
	v_mul_f32_e32 v20, v31, v31
	v_fmac_f32_e32 v19, v32, v32
	v_fmac_f32_e32 v20, v30, v30
	v_add_f32_e32 v19, v19, v20
	v_add_f32_e32 v18, v18, v19
	v_add_f32_e32 v21, v37, v18
	ds_bpermute_b32 v40, v220, v21
	v_add_u32_e32 v34, 0xa0, v214
	v_ashrrev_i32_e32 v35, 31, v34
	v_lshlrev_b64 v[38:39], 11, v[34:35]
	v_lshl_add_u64 v[18:19], s[62:63], 0, v[38:39]
	v_lshl_add_u64 v[36:37], v[210:211], 1, v[18:19]
	s_waitcnt lgkmcnt(0)
	v_add_f32_e32 v18, v21, v40
	ds_bpermute_b32 v19, v221, v18
	global_store_dwordx4 v[36:37], v[26:29], off sc1
	v_cvt_pk_bf16_f32 v20, v22, v23
	v_cvt_pk_bf16_f32 v21, v24, v25
	v_cvt_pk_bf16_f32 v22, v32, v33
	v_cvt_pk_bf16_f32 v23, v30, v31
	global_store_dwordx4 v[36:37], v[20:23], off offset:256 sc1
	s_and_saveexec_b64 s[6:7], s[0:1]
	s_cbranch_execz .LBB0_1660
	s_waitcnt lgkmcnt(0)
	v_add_f32_e32 v20, v18, v19
	v_lshlrev_b64 v[18:19], 6, v[34:35]
	v_lshl_add_u64 v[18:19], s[86:87], 0, v[18:19]
	v_lshl_add_u64 v[18:19], s[4:5], 2, v[18:19]
	v_lshl_add_u64 v[18:19], v[18:19], 0, s[10:11]
	global_store_dword v[18:19], v20, off
.LBB0_1660:
	s_or_b64 exec, exec, s[6:7]
	ds_read_b32 v20, v225 offset:4800
	v_lshlrev_b32_e32 v24, 16, v134
	v_and_b32_e32 v25, 0xffff0000, v134
	v_lshlrev_b32_e32 v26, 16, v135
	v_and_b32_e32 v27, 0xffff0000, v135
	v_pk_mul_f32 v[16:17], v[16:17], v[180:181]
	v_pk_mul_f32 v[14:15], v[14:15], v[178:179]
	v_lshlrev_b32_e32 v28, 16, v136
	v_and_b32_e32 v29, 0xffff0000, v136
	v_lshlrev_b32_e32 v30, 16, v137
	v_and_b32_e32 v31, 0xffff0000, v137
	s_waitcnt lgkmcnt(0)
	v_pk_fma_f32 v[16:17], v[16:17], v[20:21], v[26:27] op_sel_hi:[1,0,1]
	v_pk_fma_f32 v[14:15], v[14:15], v[20:21], v[24:25] op_sel_hi:[1,0,1]
	v_pk_mul_f32 v[12:13], v[12:13], v[176:177]
	v_pk_mul_f32 v[10:11], v[10:11], v[174:175]
	v_pk_fma_f32 v[24:25], v[12:13], v[20:21], v[30:31] op_sel_hi:[1,0,1]
	v_pk_fma_f32 v[12:13], v[10:11], v[20:21], v[28:29] op_sel_hi:[1,0,1]
	v_mul_f32_e32 v10, v15, v15
	v_mul_f32_e32 v11, v17, v17
	v_fmac_f32_e32 v10, v14, v14
	v_fmac_f32_e32 v11, v16, v16
	v_add_f32_e32 v10, v10, v11
	v_mul_f32_e32 v11, v13, v13
	v_mul_f32_e32 v21, v25, v25
	v_fmac_f32_e32 v11, v12, v12
	v_fmac_f32_e32 v21, v24, v24
	v_add_f32_e32 v11, v11, v21
	v_add_f32_e32 v21, v10, v11
	v_cvt_pk_bf16_f32 v10, v14, v15
	v_cvt_pk_bf16_f32 v11, v16, v17
	v_lshlrev_b32_e32 v14, 16, v130
	v_and_b32_e32 v15, 0xffff0000, v130
	v_lshlrev_b32_e32 v16, 16, v131
	v_and_b32_e32 v17, 0xffff0000, v131
	v_pk_mul_f32 v[8:9], v[8:9], v[168:169]
	v_pk_mul_f32 v[6:7], v[6:7], v[166:167]
	v_cvt_pk_bf16_f32 v12, v12, v13
	v_cvt_pk_bf16_f32 v13, v24, v25
	v_lshlrev_b32_e32 v24, 16, v132
	v_and_b32_e32 v25, 0xffff0000, v132
	v_pk_fma_f32 v[8:9], v[8:9], v[20:21], v[16:17] op_sel_hi:[1,0,1]
	v_pk_fma_f32 v[6:7], v[6:7], v[20:21], v[14:15] op_sel_hi:[1,0,1]
	v_pk_mul_f32 v[2:3], v[2:3], v[162:163]
	v_lshlrev_b32_e32 v26, 16, v133
	v_and_b32_e32 v27, 0xffff0000, v133
	v_pk_mul_f32 v[4:5], v[4:5], v[164:165]
	v_pk_fma_f32 v[16:17], v[2:3], v[20:21], v[24:25] op_sel_hi:[1,0,1]
	v_mul_f32_e32 v2, v7, v7
	v_mul_f32_e32 v3, v9, v9
	v_pk_fma_f32 v[14:15], v[4:5], v[20:21], v[26:27] op_sel_hi:[1,0,1]
	v_fmac_f32_e32 v2, v6, v6
	v_fmac_f32_e32 v3, v8, v8
	v_add_f32_e32 v2, v2, v3
	v_mul_f32_e32 v3, v17, v17
	v_mul_f32_e32 v4, v15, v15
	v_fmac_f32_e32 v3, v16, v16
	v_fmac_f32_e32 v4, v14, v14
	v_add_f32_e32 v3, v3, v4
	v_add_f32_e32 v2, v2, v3
	v_add_f32_e32 v5, v21, v2
	ds_bpermute_b32 v24, v220, v5
	v_add_u32_e32 v18, 0xb0, v214
	v_ashrrev_i32_e32 v19, 31, v18
	v_lshlrev_b64 v[22:23], 11, v[18:19]
	v_lshl_add_u64 v[2:3], s[62:63], 0, v[22:23]
	v_lshl_add_u64 v[20:21], v[210:211], 1, v[2:3]
	s_waitcnt lgkmcnt(0)
	v_add_f32_e32 v2, v5, v24
	ds_bpermute_b32 v3, v221, v2
	global_store_dwordx4 v[20:21], v[10:13], off sc1
	v_cvt_pk_bf16_f32 v4, v6, v7
	v_cvt_pk_bf16_f32 v5, v8, v9
	v_cvt_pk_bf16_f32 v6, v16, v17
	v_cvt_pk_bf16_f32 v7, v14, v15
	global_store_dwordx4 v[20:21], v[4:7], off offset:256 sc1
	s_and_saveexec_b64 s[6:7], s[0:1]
	s_cbranch_execz .LBB0_1662
	s_waitcnt lgkmcnt(0)
	v_add_f32_e32 v4, v2, v3
	v_lshlrev_b64 v[2:3], 6, v[18:19]
	v_lshl_add_u64 v[2:3], s[86:87], 0, v[2:3]
	v_lshl_add_u64 v[2:3], s[4:5], 2, v[2:3]
	v_lshl_add_u64 v[2:3], v[2:3], 0, s[10:11]
	global_store_dword v[2:3], v4, off

.LBB0_1756:
	v_lshl_add_u32 v148, s34, 8, v152
	v_ashrrev_i32_e32 v149, 31, v148
	v_lshlrev_b64 v[150:151], 13, v[148:149]
	ds_read_b32 v149, v154
	v_lshl_or_b32 v146, s58, 8, v156
	v_max_f32_e32 v122, v122, v122
	v_ashrrev_i32_e32 v147, 31, v146
	v_max_f32_e32 v122, 0, v122
	v_max_f32_e32 v123, v123, v123
	v_max_f32_e32 v124, v124, v124
	v_lshl_add_u64 v[160:161], s[10:11], 0, v[150:151]
	v_lshlrev_b64 v[150:151], 1, v[146:147]
	s_waitcnt lgkmcnt(0)
	v_mul_f32_e32 v122, v122, v149
	v_max_f32_e32 v123, 0, v123
	v_max_f32_e32 v124, 0, v124
	v_lshl_add_u64 v[146:147], v[160:161], 0, v[150:151]
	v_mul_f32_e32 v160, v122, v122
	v_max_f32_e32 v122, v127, v127
	v_mul_f32_e32 v123, v123, v149
	v_mul_f32_e32 v124, v124, v149
	v_max_f32_e32 v126, v126, v126
	v_max_f32_e32 v122, 0, v122
	v_mul_f32_e32 v127, v123, v123
	v_max_f32_e32 v123, v128, v128
	v_mul_f32_e32 v128, v124, v124
	v_max_f32_e32 v124, v129, v129
	v_max_f32_e32 v125, v125, v125
	v_max_f32_e32 v126, 0, v126
	v_mul_f32_e32 v122, v122, v149
	v_max_f32_e32 v123, 0, v123
	v_max_f32_e32 v124, 0, v124
	v_max_f32_e32 v125, 0, v125
	v_max_f32_e32 v114, v114, v114
	v_max_f32_e32 v115, v115, v115
	v_max_f32_e32 v116, v116, v116
	v_mul_f32_e32 v126, v126, v149
	v_mul_f32_e32 v122, v122, v122
	v_mul_f32_e32 v123, v123, v149
	v_mul_f32_e32 v124, v124, v149
	v_mul_f32_e32 v125, v125, v149
	v_max_f32_e32 v114, 0, v114
	v_max_f32_e32 v115, 0, v115
	v_max_f32_e32 v116, 0, v116
	v_mul_f32_e32 v126, v126, v126
	v_mul_f32_e32 v123, v123, v123
	v_mul_f32_e32 v124, v124, v124
	v_mul_f32_e32 v125, v125, v125
	v_cvt_pk_bf16_f32 v122, v126, v122
	v_mul_f32_e32 v114, v114, v149
	v_mul_f32_e32 v115, v115, v149
	v_mul_f32_e32 v116, v116, v149
	v_cvt_pk_bf16_f32 v123, v123, v124
	v_cvt_pk_bf16_f32 v124, v160, v127
	v_cvt_pk_bf16_f32 v125, v128, v125
	global_store_dwordx4 v[146:147], v[122:125], off sc1
	v_max_f32_e32 v118, v118, v118
	v_max_f32_e32 v117, v117, v117
	v_mul_f32_e32 v122, v114, v114
	v_max_f32_e32 v114, v119, v119
	v_mul_f32_e32 v119, v115, v115
	v_max_f32_e32 v115, v120, v120
	v_mul_f32_e32 v120, v116, v116
	v_max_f32_e32 v116, v121, v121
	v_max_f32_e32 v114, 0, v114
	v_max_f32_e32 v115, 0, v115
	v_max_f32_e32 v116, 0, v116
	v_max_f32_e32 v118, 0, v118
	v_mul_f32_e32 v114, v114, v149
	v_mul_f32_e32 v115, v115, v149
	v_mul_f32_e32 v116, v116, v149
	v_max_f32_e32 v117, 0, v117
	v_mul_f32_e32 v118, v118, v149
	v_mul_f32_e32 v114, v114, v114
	v_mul_f32_e32 v115, v115, v115
	v_mul_f32_e32 v117, v117, v149
	v_mul_f32_e32 v116, v116, v116
	v_mul_f32_e32 v118, v118, v118
	v_mul_f32_e32 v117, v117, v117
	v_cvt_pk_bf16_f32 v114, v118, v114
	v_cvt_pk_bf16_f32 v115, v115, v116
	v_cvt_pk_bf16_f32 v116, v122, v119
	v_cvt_pk_bf16_f32 v117, v120, v117
	global_store_dwordx4 v[146:147], v[114:117], off offset:256 sc1
	ds_read_b32 v116, v154 offset:64
	v_max_f32_e32 v106, v106, v106
	v_max_f32_e32 v106, 0, v106
	v_max_f32_e32 v107, v107, v107
	v_max_f32_e32 v108, v108, v108
	s_waitcnt lgkmcnt(0)
	v_mul_f32_e32 v106, v106, v116
	v_max_f32_e32 v107, 0, v107
	v_max_f32_e32 v108, 0, v108
	v_or_b32_e32 v114, 16, v148
	v_mul_f32_e32 v117, v106, v106
	v_max_f32_e32 v106, v111, v111
	v_mul_f32_e32 v107, v107, v116
	v_mul_f32_e32 v108, v108, v116
	v_ashrrev_i32_e32 v115, 31, v114
	v_max_f32_e32 v110, v110, v110
	v_max_f32_e32 v106, 0, v106
	v_mul_f32_e32 v111, v107, v107
	v_max_f32_e32 v107, v112, v112
	v_mul_f32_e32 v112, v108, v108
	v_max_f32_e32 v108, v113, v113
	v_max_f32_e32 v109, v109, v109
	v_lshlrev_b64 v[114:115], 13, v[114:115]
	v_max_f32_e32 v110, 0, v110
	v_mul_f32_e32 v106, v106, v116
	v_max_f32_e32 v107, 0, v107
	v_max_f32_e32 v108, 0, v108
	v_max_f32_e32 v109, 0, v109
	v_max_f32_e32 v98, v98, v98
	v_max_f32_e32 v99, v99, v99
	v_max_f32_e32 v100, v100, v100
	v_lshl_add_u64 v[114:115], s[10:11], 0, v[114:115]
	v_mul_f32_e32 v110, v110, v116
	v_mul_f32_e32 v106, v106, v106
	v_mul_f32_e32 v107, v107, v116
	v_mul_f32_e32 v108, v108, v116
	v_mul_f32_e32 v109, v109, v116
	v_max_f32_e32 v98, 0, v98
	v_max_f32_e32 v99, 0, v99
	v_max_f32_e32 v100, 0, v100
	v_lshl_add_u64 v[114:115], v[114:115], 0, v[150:151]
	v_mul_f32_e32 v110, v110, v110
	v_mul_f32_e32 v107, v107, v107
	v_mul_f32_e32 v108, v108, v108
	v_mul_f32_e32 v109, v109, v109
	v_cvt_pk_bf16_f32 v106, v110, v106
	v_mul_f32_e32 v98, v98, v116
	v_mul_f32_e32 v99, v99, v116
	v_mul_f32_e32 v100, v100, v116
	v_cvt_pk_bf16_f32 v107, v107, v108
	v_cvt_pk_bf16_f32 v108, v117, v111
	v_cvt_pk_bf16_f32 v109, v112, v109
	global_store_dwordx4 v[114:115], v[106:109], off sc1
	v_max_f32_e32 v102, v102, v102
	v_max_f32_e32 v101, v101, v101
	v_mul_f32_e32 v106, v98, v98
	v_max_f32_e32 v98, v103, v103
	v_mul_f32_e32 v103, v99, v99
	v_max_f32_e32 v99, v104, v104
	v_mul_f32_e32 v104, v100, v100
	v_max_f32_e32 v100, v105, v105
	v_max_f32_e32 v98, 0, v98
	v_max_f32_e32 v99, 0, v99
	v_max_f32_e32 v100, 0, v100
	v_max_f32_e32 v102, 0, v102
	v_mul_f32_e32 v98, v98, v116
	v_mul_f32_e32 v99, v99, v116
	v_mul_f32_e32 v100, v100, v116
	v_max_f32_e32 v101, 0, v101
	v_mul_f32_e32 v102, v102, v116
	v_mul_f32_e32 v98, v98, v98
	v_mul_f32_e32 v99, v99, v99
	v_mul_f32_e32 v101, v101, v116
	v_mul_f32_e32 v100, v100, v100
	v_mul_f32_e32 v102, v102, v102
	v_mul_f32_e32 v101, v101, v101
	v_cvt_pk_bf16_f32 v98, v102, v98
	v_cvt_pk_bf16_f32 v99, v99, v100
	v_cvt_pk_bf16_f32 v100, v106, v103
	v_cvt_pk_bf16_f32 v101, v104, v101
	global_store_dwordx4 v[114:115], v[98:101], off offset:256 sc1
	ds_read_b32 v100, v154 offset:128
	v_max_f32_e32 v90, v90, v90
	v_max_f32_e32 v90, 0, v90
	v_max_f32_e32 v91, v91, v91
	v_max_f32_e32 v92, v92, v92
	s_waitcnt lgkmcnt(0)
	v_mul_f32_e32 v90, v90, v100
	v_max_f32_e32 v91, 0, v91
	v_max_f32_e32 v92, 0, v92
	v_or_b32_e32 v98, 32, v148
	v_mul_f32_e32 v101, v90, v90
	v_max_f32_e32 v90, v95, v95
	v_mul_f32_e32 v91, v91, v100
	v_mul_f32_e32 v92, v92, v100
	v_ashrrev_i32_e32 v99, 31, v98
	v_max_f32_e32 v94, v94, v94
	v_max_f32_e32 v90, 0, v90
	v_mul_f32_e32 v95, v91, v91
	v_max_f32_e32 v91, v96, v96
	v_mul_f32_e32 v96, v92, v92
	v_max_f32_e32 v92, v97, v97
	v_max_f32_e32 v93, v93, v93
	v_lshlrev_b64 v[98:99], 13, v[98:99]
	v_max_f32_e32 v94, 0, v94
	v_mul_f32_e32 v90, v90, v100
	v_max_f32_e32 v91, 0, v91
	v_max_f32_e32 v92, 0, v92
	v_max_f32_e32 v93, 0, v93
	v_max_f32_e32 v82, v82, v82
	v_max_f32_e32 v83, v83, v83
	v_max_f32_e32 v84, v84, v84
	v_lshl_add_u64 v[98:99], s[10:11], 0, v[98:99]
	v_mul_f32_e32 v94, v94, v100
	v_mul_f32_e32 v90, v90, v90
	v_mul_f32_e32 v91, v91, v100
	v_mul_f32_e32 v92, v92, v100
	v_mul_f32_e32 v93, v93, v100
	v_max_f32_e32 v82, 0, v82
	v_max_f32_e32 v83, 0, v83
	v_max_f32_e32 v84, 0, v84
	v_lshl_add_u64 v[98:99], v[98:99], 0, v[150:151]
	v_mul_f32_e32 v94, v94, v94
	v_mul_f32_e32 v91, v91, v91
	v_mul_f32_e32 v92, v92, v92
	v_mul_f32_e32 v93, v93, v93
	v_cvt_pk_bf16_f32 v90, v94, v90
	v_mul_f32_e32 v82, v82, v100
	v_mul_f32_e32 v83, v83, v100
	v_mul_f32_e32 v84, v84, v100
	v_cvt_pk_bf16_f32 v91, v91, v92
	v_cvt_pk_bf16_f32 v92, v101, v95
	v_cvt_pk_bf16_f32 v93, v96, v93
	global_store_dwordx4 v[98:99], v[90:93], off sc1
	v_max_f32_e32 v86, v86, v86
	v_max_f32_e32 v85, v85, v85
	v_mul_f32_e32 v90, v82, v82
	v_max_f32_e32 v82, v87, v87
	v_mul_f32_e32 v87, v83, v83
	v_max_f32_e32 v83, v88, v88
	v_mul_f32_e32 v88, v84, v84
	v_max_f32_e32 v84, v89, v89
	v_max_f32_e32 v82, 0, v82
	v_max_f32_e32 v83, 0, v83
	v_max_f32_e32 v84, 0, v84
	v_max_f32_e32 v86, 0, v86
	v_mul_f32_e32 v82, v82, v100
	v_mul_f32_e32 v83, v83, v100
	v_mul_f32_e32 v84, v84, v100
	v_max_f32_e32 v85, 0, v85
	v_mul_f32_e32 v86, v86, v100
	v_mul_f32_e32 v82, v82, v82
	v_mul_f32_e32 v83, v83, v83
	v_mul_f32_e32 v85, v85, v100
	v_mul_f32_e32 v84, v84, v84
	v_mul_f32_e32 v86, v86, v86
	v_mul_f32_e32 v85, v85, v85
	v_cvt_pk_bf16_f32 v82, v86, v82
	v_cvt_pk_bf16_f32 v83, v83, v84
	v_cvt_pk_bf16_f32 v84, v90, v87
	v_cvt_pk_bf16_f32 v85, v88, v85
	global_store_dwordx4 v[98:99], v[82:85], off offset:256 sc1
	ds_read_b32 v84, v154 offset:192
	v_max_f32_e32 v74, v74, v74
	v_max_f32_e32 v74, 0, v74
	v_max_f32_e32 v75, v75, v75
	v_max_f32_e32 v76, v76, v76
	s_waitcnt lgkmcnt(0)
	v_mul_f32_e32 v74, v74, v84
	v_max_f32_e32 v75, 0, v75
	v_max_f32_e32 v76, 0, v76
	v_or_b32_e32 v82, 48, v148
	v_mul_f32_e32 v85, v74, v74
	v_max_f32_e32 v74, v79, v79
	v_mul_f32_e32 v75, v75, v84
	v_mul_f32_e32 v76, v76, v84
	v_ashrrev_i32_e32 v83, 31, v82
	v_max_f32_e32 v78, v78, v78
	v_max_f32_e32 v74, 0, v74
	v_mul_f32_e32 v79, v75, v75
	v_max_f32_e32 v75, v80, v80
	v_mul_f32_e32 v80, v76, v76
	v_max_f32_e32 v76, v81, v81
	v_max_f32_e32 v77, v77, v77
	v_lshlrev_b64 v[82:83], 13, v[82:83]
	v_max_f32_e32 v78, 0, v78
	v_mul_f32_e32 v74, v74, v84
	v_max_f32_e32 v75, 0, v75
	v_max_f32_e32 v76, 0, v76
	v_max_f32_e32 v77, 0, v77
	v_max_f32_e32 v66, v66, v66
	v_max_f32_e32 v67, v67, v67
	v_max_f32_e32 v68, v68, v68
	v_lshl_add_u64 v[82:83], s[10:11], 0, v[82:83]
	v_mul_f32_e32 v78, v78, v84
	v_mul_f32_e32 v74, v74, v74
	v_mul_f32_e32 v75, v75, v84
	v_mul_f32_e32 v76, v76, v84
	v_mul_f32_e32 v77, v77, v84
	v_max_f32_e32 v66, 0, v66
	v_max_f32_e32 v67, 0, v67
	v_max_f32_e32 v68, 0, v68
	v_lshl_add_u64 v[82:83], v[82:83], 0, v[150:151]
	v_mul_f32_e32 v78, v78, v78
	v_mul_f32_e32 v75, v75, v75
	v_mul_f32_e32 v76, v76, v76
	v_mul_f32_e32 v77, v77, v77
	v_cvt_pk_bf16_f32 v74, v78, v74
	v_mul_f32_e32 v66, v66, v84
	v_mul_f32_e32 v67, v67, v84
	v_mul_f32_e32 v68, v68, v84
	v_cvt_pk_bf16_f32 v75, v75, v76
	v_cvt_pk_bf16_f32 v76, v85, v79
	v_cvt_pk_bf16_f32 v77, v80, v77
	global_store_dwordx4 v[82:83], v[74:77], off sc1
	v_max_f32_e32 v70, v70, v70
	v_max_f32_e32 v69, v69, v69
	v_mul_f32_e32 v74, v66, v66
	v_max_f32_e32 v66, v71, v71
	v_mul_f32_e32 v71, v67, v67
	v_max_f32_e32 v67, v72, v72
	v_mul_f32_e32 v72, v68, v68
	v_max_f32_e32 v68, v73, v73
	v_max_f32_e32 v70, 0, v70
	v_max_f32_e32 v66, 0, v66
	v_max_f32_e32 v67, 0, v67
	v_max_f32_e32 v68, 0, v68
	v_max_f32_e32 v69, 0, v69
	v_mul_f32_e32 v70, v70, v84
	v_mul_f32_e32 v66, v66, v84
	v_mul_f32_e32 v67, v67, v84
	v_mul_f32_e32 v68, v68, v84
	v_mul_f32_e32 v69, v69, v84
	v_mul_f32_e32 v70, v70, v70
	v_mul_f32_e32 v66, v66, v66
	v_mul_f32_e32 v67, v67, v67
	v_mul_f32_e32 v68, v68, v68
	v_mul_f32_e32 v69, v69, v69
	v_cvt_pk_bf16_f32 v66, v70, v66
	v_cvt_pk_bf16_f32 v67, v67, v68
	v_cvt_pk_bf16_f32 v68, v74, v71
	v_cvt_pk_bf16_f32 v69, v72, v69
	ds_read_b32 v70, v155
	v_max_f32_e32 v58, v58, v58
	v_max_f32_e32 v58, 0, v58
	v_max_f32_e32 v59, v59, v59
	v_max_f32_e32 v60, v60, v60
	s_waitcnt lgkmcnt(0)
	v_mul_f32_e32 v58, v58, v70
	v_max_f32_e32 v59, 0, v59
	v_max_f32_e32 v60, 0, v60
	global_store_dwordx4 v[82:83], v[66:69], off offset:256 sc1
	v_max_f32_e32 v62, v62, v62
	v_mul_f32_e32 v59, v59, v70
	v_mul_f32_e32 v68, v58, v58
	v_max_f32_e32 v58, v63, v63
	v_mul_f32_e32 v60, v60, v70
	v_max_f32_e32 v62, 0, v62
	v_max_f32_e32 v58, 0, v58
	v_mul_f32_e32 v63, v59, v59
	v_max_f32_e32 v59, v64, v64
	v_mul_f32_e32 v64, v60, v60
	v_max_f32_e32 v60, v65, v65
	v_mul_f32_e32 v62, v62, v70
	v_mul_f32_e32 v58, v58, v70
	v_max_f32_e32 v59, 0, v59
	v_max_f32_e32 v60, 0, v60
	v_max_f32_e32 v61, v61, v61
	v_mul_f32_e32 v62, v62, v62
	v_mul_f32_e32 v58, v58, v58
	v_mul_f32_e32 v59, v59, v70
	v_mul_f32_e32 v60, v60, v70
	v_max_f32_e32 v61, 0, v61
	v_max_f32_e32 v50, v50, v50
	v_max_f32_e32 v51, v51, v51
	v_max_f32_e32 v52, v52, v52
	v_mul_f32_e32 v59, v59, v59
	v_mul_f32_e32 v61, v61, v70
	v_mul_f32_e32 v60, v60, v60
	v_cvt_pk_bf16_f32 v58, v62, v58
	v_add_co_u32_e32 v62, vcc, s52, v146
	v_max_f32_e32 v50, 0, v50
	v_max_f32_e32 v51, 0, v51
	v_max_f32_e32 v52, 0, v52
	v_mul_f32_e32 v61, v61, v61
	v_cvt_pk_bf16_f32 v59, v59, v60
	v_cvt_pk_bf16_f32 v60, v68, v63
	v_addc_co_u32_e32 v63, vcc, 0, v147, vcc
	v_mul_f32_e32 v50, v50, v70
	v_mul_f32_e32 v51, v51, v70
	v_mul_f32_e32 v52, v52, v70
	v_cvt_pk_bf16_f32 v61, v64, v61
	global_store_dwordx4 v[62:63], v[58:61], off sc1
	v_max_f32_e32 v54, v54, v54
	v_max_f32_e32 v53, v53, v53
	v_mul_f32_e32 v58, v50, v50
	v_max_f32_e32 v50, v55, v55
	v_mul_f32_e32 v55, v51, v51
	v_max_f32_e32 v51, v56, v56
	v_mul_f32_e32 v56, v52, v52
	v_max_f32_e32 v52, v57, v57
	v_max_f32_e32 v54, 0, v54
	v_max_f32_e32 v50, 0, v50
	v_max_f32_e32 v51, 0, v51
	v_max_f32_e32 v52, 0, v52
	v_max_f32_e32 v53, 0, v53
	v_mul_f32_e32 v54, v54, v70
	v_mul_f32_e32 v50, v50, v70
	v_mul_f32_e32 v51, v51, v70
	v_mul_f32_e32 v52, v52, v70
	v_mul_f32_e32 v53, v53, v70
	v_mul_f32_e32 v54, v54, v54
	v_mul_f32_e32 v50, v50, v50
	v_mul_f32_e32 v51, v51, v51
	v_mul_f32_e32 v52, v52, v52
	v_mul_f32_e32 v53, v53, v53
	v_cvt_pk_bf16_f32 v50, v54, v50
	v_cvt_pk_bf16_f32 v51, v51, v52
	v_cvt_pk_bf16_f32 v52, v58, v55
	v_cvt_pk_bf16_f32 v53, v56, v53
	ds_read_b32 v54, v154 offset:576
	v_max_f32_e32 v42, v42, v42
	v_max_f32_e32 v42, 0, v42
	v_max_f32_e32 v43, v43, v43
	v_max_f32_e32 v44, v44, v44
	v_lshl_add_u64 v[66:67], v[146:147], 0, s[16:17]
	s_waitcnt lgkmcnt(0)
	v_mul_f32_e32 v42, v42, v54
	v_max_f32_e32 v43, 0, v43
	v_max_f32_e32 v44, 0, v44
	global_store_dwordx4 v[66:67], v[50:53], off offset:256 sc1
	v_max_f32_e32 v46, v46, v46
	v_mul_f32_e32 v43, v43, v54
	v_mul_f32_e32 v52, v42, v42
	v_max_f32_e32 v42, v47, v47
	v_mul_f32_e32 v44, v44, v54
	v_max_f32_e32 v46, 0, v46
	v_max_f32_e32 v42, 0, v42
	v_mul_f32_e32 v47, v43, v43
	v_max_f32_e32 v43, v48, v48
	v_mul_f32_e32 v48, v44, v44
	v_max_f32_e32 v44, v49, v49
	v_mul_f32_e32 v46, v46, v54
	v_mul_f32_e32 v42, v42, v54
	v_max_f32_e32 v43, 0, v43
	v_max_f32_e32 v44, 0, v44
	v_max_f32_e32 v45, v45, v45
	v_mul_f32_e32 v46, v46, v46
	v_mul_f32_e32 v42, v42, v42
	v_mul_f32_e32 v43, v43, v54
	v_mul_f32_e32 v44, v44, v54
	v_max_f32_e32 v45, 0, v45
	v_max_f32_e32 v34, v34, v34
	v_max_f32_e32 v35, v35, v35
	v_max_f32_e32 v36, v36, v36
	v_mul_f32_e32 v43, v43, v43
	v_mul_f32_e32 v45, v45, v54
	v_mul_f32_e32 v44, v44, v44
	v_cvt_pk_bf16_f32 v42, v46, v42
	v_add_co_u32_e32 v46, vcc, s53, v146
	v_max_f32_e32 v34, 0, v34
	v_max_f32_e32 v35, 0, v35
	v_max_f32_e32 v36, 0, v36
	v_mul_f32_e32 v45, v45, v45
	v_cvt_pk_bf16_f32 v43, v43, v44
	v_cvt_pk_bf16_f32 v44, v52, v47
	v_addc_co_u32_e32 v47, vcc, 0, v147, vcc
	v_mul_f32_e32 v34, v34, v54
	v_mul_f32_e32 v35, v35, v54
	v_mul_f32_e32 v36, v36, v54
	v_cvt_pk_bf16_f32 v45, v48, v45
	global_store_dwordx4 v[46:47], v[42:45], off sc1
	v_max_f32_e32 v38, v38, v38
	v_max_f32_e32 v37, v37, v37
	v_mul_f32_e32 v42, v34, v34
	v_max_f32_e32 v34, v39, v39
	v_mul_f32_e32 v39, v35, v35
	v_max_f32_e32 v35, v40, v40
	v_mul_f32_e32 v40, v36, v36
	v_max_f32_e32 v36, v41, v41
	v_max_f32_e32 v38, 0, v38
	v_max_f32_e32 v34, 0, v34
	v_max_f32_e32 v35, 0, v35
	v_max_f32_e32 v36, 0, v36
	v_max_f32_e32 v37, 0, v37
	v_mul_f32_e32 v38, v38, v54
	v_mul_f32_e32 v34, v34, v54
	v_mul_f32_e32 v35, v35, v54
	v_mul_f32_e32 v36, v36, v54
	v_mul_f32_e32 v37, v37, v54
	v_mul_f32_e32 v38, v38, v38
	v_mul_f32_e32 v34, v34, v34
	v_mul_f32_e32 v35, v35, v35
	v_mul_f32_e32 v36, v36, v36
	v_mul_f32_e32 v37, v37, v37
	v_cvt_pk_bf16_f32 v34, v38, v34
	v_cvt_pk_bf16_f32 v35, v35, v36
	v_cvt_pk_bf16_f32 v36, v42, v39
	v_cvt_pk_bf16_f32 v37, v40, v37
	ds_read_b32 v38, v154 offset:640
	v_max_f32_e32 v26, v26, v26
	v_max_f32_e32 v26, 0, v26
	v_max_f32_e32 v27, v27, v27
	v_max_f32_e32 v28, v28, v28
	v_lshl_add_u64 v[50:51], v[146:147], 0, s[18:19]
	s_waitcnt lgkmcnt(0)
	v_mul_f32_e32 v26, v26, v38
	v_max_f32_e32 v27, 0, v27
	v_max_f32_e32 v28, 0, v28
	global_store_dwordx4 v[50:51], v[34:37], off offset:256 sc1
	v_max_f32_e32 v30, v30, v30
	v_mul_f32_e32 v27, v27, v38
	v_mul_f32_e32 v36, v26, v26
	v_max_f32_e32 v26, v31, v31
	v_mul_f32_e32 v28, v28, v38
	v_max_f32_e32 v30, 0, v30
	v_max_f32_e32 v26, 0, v26
	v_mul_f32_e32 v31, v27, v27
	v_max_f32_e32 v27, v32, v32
	v_mul_f32_e32 v32, v28, v28
	v_max_f32_e32 v28, v33, v33
	v_mul_f32_e32 v30, v30, v38
	v_mul_f32_e32 v26, v26, v38
	v_max_f32_e32 v27, 0, v27
	v_max_f32_e32 v28, 0, v28
	v_max_f32_e32 v29, v29, v29
	v_mul_f32_e32 v30, v30, v30
	v_mul_f32_e32 v26, v26, v26
	v_mul_f32_e32 v27, v27, v38
	v_mul_f32_e32 v28, v28, v38
	v_max_f32_e32 v29, 0, v29
	v_max_f32_e32 v18, v18, v18
	v_max_f32_e32 v19, v19, v19
	v_max_f32_e32 v20, v20, v20
	v_mul_f32_e32 v27, v27, v27
	v_mul_f32_e32 v29, v29, v38
	v_mul_f32_e32 v28, v28, v28
	v_cvt_pk_bf16_f32 v26, v30, v26
	v_add_co_u32_e32 v30, vcc, s54, v146
	v_max_f32_e32 v18, 0, v18
	v_max_f32_e32 v19, 0, v19
	v_max_f32_e32 v20, 0, v20
	v_mul_f32_e32 v29, v29, v29
	v_cvt_pk_bf16_f32 v27, v27, v28
	v_cvt_pk_bf16_f32 v28, v36, v31
	v_addc_co_u32_e32 v31, vcc, 0, v147, vcc
	v_mul_f32_e32 v18, v18, v38
	v_mul_f32_e32 v19, v19, v38
	v_mul_f32_e32 v20, v20, v38
	v_cvt_pk_bf16_f32 v29, v32, v29
	global_store_dwordx4 v[30:31], v[26:29], off sc1
	v_max_f32_e32 v22, v22, v22
	v_max_f32_e32 v21, v21, v21
	v_mul_f32_e32 v26, v18, v18
	v_max_f32_e32 v18, v23, v23
	v_mul_f32_e32 v23, v19, v19
	v_max_f32_e32 v19, v24, v24
	v_mul_f32_e32 v24, v20, v20
	v_max_f32_e32 v20, v25, v25
	v_max_f32_e32 v22, 0, v22
	v_max_f32_e32 v18, 0, v18
	v_max_f32_e32 v19, 0, v19
	v_max_f32_e32 v20, 0, v20
	v_max_f32_e32 v21, 0, v21
	v_mul_f32_e32 v22, v22, v38
	v_mul_f32_e32 v18, v18, v38
	v_mul_f32_e32 v19, v19, v38
	v_mul_f32_e32 v20, v20, v38
	v_mul_f32_e32 v21, v21, v38
	v_mul_f32_e32 v22, v22, v22
	v_mul_f32_e32 v18, v18, v18
	v_mul_f32_e32 v19, v19, v19
	v_mul_f32_e32 v20, v20, v20
	v_mul_f32_e32 v21, v21, v21
	v_cvt_pk_bf16_f32 v18, v22, v18
	v_cvt_pk_bf16_f32 v19, v19, v20
	v_cvt_pk_bf16_f32 v20, v26, v23
	v_cvt_pk_bf16_f32 v21, v24, v21
	ds_read_b32 v22, v154 offset:704
	v_max_f32_e32 v10, v10, v10
	v_max_f32_e32 v10, 0, v10
	v_max_f32_e32 v11, v11, v11
	v_max_f32_e32 v12, v12, v12
	v_lshl_add_u64 v[34:35], v[146:147], 0, s[20:21]
	s_waitcnt lgkmcnt(0)
	v_mul_f32_e32 v10, v10, v22
	v_max_f32_e32 v11, 0, v11
	v_max_f32_e32 v12, 0, v12
	global_store_dwordx4 v[34:35], v[18:21], off offset:256 sc1
	v_max_f32_e32 v14, v14, v14
	v_mul_f32_e32 v11, v11, v22
	v_mul_f32_e32 v20, v10, v10
	v_max_f32_e32 v10, v15, v15
	v_mul_f32_e32 v12, v12, v22
	v_max_f32_e32 v14, 0, v14
	v_max_f32_e32 v10, 0, v10
	v_mul_f32_e32 v15, v11, v11
	v_max_f32_e32 v11, v16, v16
	v_mul_f32_e32 v16, v12, v12
	v_max_f32_e32 v12, v17, v17
	v_mul_f32_e32 v14, v14, v22
	v_mul_f32_e32 v10, v10, v22
	v_max_f32_e32 v11, 0, v11
	v_max_f32_e32 v12, 0, v12
	v_max_f32_e32 v13, v13, v13
	v_mul_f32_e32 v14, v14, v14
	v_mul_f32_e32 v10, v10, v10
	v_mul_f32_e32 v11, v11, v22
	v_mul_f32_e32 v12, v12, v22
	v_max_f32_e32 v13, 0, v13
	v_max_f32_e32 v2, v2, v2
	v_max_f32_e32 v3, v3, v3
	v_max_f32_e32 v4, v4, v4
	v_mul_f32_e32 v11, v11, v11
	v_mul_f32_e32 v13, v13, v22
	v_mul_f32_e32 v12, v12, v12
	v_cvt_pk_bf16_f32 v10, v14, v10
	v_add_co_u32_e32 v14, vcc, s55, v146
	v_max_f32_e32 v2, 0, v2
	v_max_f32_e32 v3, 0, v3
	v_max_f32_e32 v4, 0, v4
	v_mul_f32_e32 v13, v13, v13
	v_cvt_pk_bf16_f32 v11, v11, v12
	v_cvt_pk_bf16_f32 v12, v20, v15
	v_addc_co_u32_e32 v15, vcc, 0, v147, vcc
	v_mul_f32_e32 v2, v2, v22
	v_mul_f32_e32 v3, v3, v22
	v_mul_f32_e32 v4, v4, v22
	v_cvt_pk_bf16_f32 v13, v16, v13
	global_store_dwordx4 v[14:15], v[10:13], off sc1
	v_max_f32_e32 v5, v5, v5
	v_max_f32_e32 v6, v6, v6
	v_mul_f32_e32 v10, v2, v2
	v_max_f32_e32 v2, v7, v7
	v_mul_f32_e32 v7, v3, v3
	v_max_f32_e32 v3, v8, v8
	v_mul_f32_e32 v8, v4, v4
	v_max_f32_e32 v4, v9, v9
	v_max_f32_e32 v2, 0, v2
	v_max_f32_e32 v3, 0, v3
	v_max_f32_e32 v4, 0, v4
	v_max_f32_e32 v5, 0, v5
	v_max_f32_e32 v6, 0, v6
	v_mul_f32_e32 v2, v2, v22
	v_mul_f32_e32 v3, v3, v22
	v_mul_f32_e32 v4, v4, v22
	v_mul_f32_e32 v5, v5, v22
	v_lshl_add_u64 v[18:19], v[146:147], 0, s[22:23]
	v_mul_f32_e32 v6, v6, v22
	v_mul_f32_e32 v2, v2, v2
	v_mul_f32_e32 v3, v3, v3
	v_mul_f32_e32 v4, v4, v4
	v_mul_f32_e32 v5, v5, v5
	s_andn2_b64 vcc, exec, s[0:1]
	s_mov_b64 s[0:1], -1
	v_mul_f32_e32 v6, v6, v6
	v_cvt_pk_bf16_f32 v2, v6, v2
	v_cvt_pk_bf16_f32 v3, v3, v4
	v_cvt_pk_bf16_f32 v4, v10, v7
	v_cvt_pk_bf16_f32 v5, v8, v5
	global_store_dwordx4 v[18:19], v[2:5], off offset:256 sc1
	s_cbranch_vccnz .LBB0_1745
	s_andn2_b64 vcc, exec, s[8:9]
	s_cbranch_vccnz .LBB0_1744
	s_barrier
	s_branch .LBB0_1744
